# v083 + code placement: every 16-MFMA group 8-byte aligned (18 provably redundant duplicate s_waitcnt lgkmcnt(0) removed in front of misaligned groups)
# baseline (speedup 1.0000x reference)
.LBB0_241:
	s_add_u32 s94, s26, s92
	s_addc_u32 s95, s27, s93
	s_add_u32 s94, s94, 0x100
	s_addc_u32 s95, s95, 0
	s_add_u32 vcc_lo, s41, s92
	s_addc_u32 vcc_hi, s44, s93
	s_add_i32 s43, 0, 0x10000
	v_add_u32_e32 v152, s43, v171
	ds_read_b128 v[132:135], v152
	ds_read_b128 v[136:139], v152 offset:1024
	ds_read_b128 v[140:143], v152 offset:2048
	ds_read_b128 v[166:169], v152 offset:3072
	v_add_u32_e32 v152, s8, v171
	ds_read_b128 v[178:181], v152
	ds_read_b128 v[182:185], v152 offset:1024
	ds_read_b128 v[186:189], v152 offset:2048
	ds_read_b128 v[190:193], v152 offset:3072
	s_cmpk_eq_i32 s92, 0xf00
	s_cselect_b32 s97, s45, s95
	s_cselect_b32 s96, s50, s94
	s_cselect_b32 s95, s51, vcc_hi
	s_cselect_b32 s94, s81, vcc_lo
	v_lshl_add_u64 v[226:227], v[128:129], 0, s[92:93]
	s_add_i32 m0, s21, 0xc000
	ds_read_b128 v[194:197], v173
	ds_read_b128 v[198:201], v173 offset:1024
	ds_read_b128 v[202:205], v173 offset:2048
	ds_read_b128 v[206:209], v173 offset:3072
	ds_read_b128 v[210:213], v173 offset:4096
	ds_read_b128 v[214:217], v173 offset:5120
	ds_read_b128 v[218:221], v173 offset:6144
	ds_read_b128 v[222:225], v173 offset:7168
	global_load_lds_dwordx4 v[226:227], off
	v_lshl_add_u64 v[226:227], v[130:131], 0, s[92:93]
	s_add_i32 m0, s21, 0xe000
	s_nop 0
	global_load_lds_dwordx4 v[226:227], off
	s_waitcnt vmcnt(8)
	s_waitcnt lgkmcnt(0)
	s_barrier
	s_setprio 1
	v_mfma_f32_16x16x32_bf16 v[124:127], v[132:135], v[194:197], v[124:127]
	v_mfma_f32_16x16x32_bf16 v[124:127], v[136:139], v[198:201], v[124:127]
	v_mfma_f32_16x16x32_bf16 v[120:123], v[140:143], v[194:197], v[120:123]
	v_mfma_f32_16x16x32_bf16 v[120:123], v[166:169], v[198:201], v[120:123]
	v_mfma_f32_16x16x32_bf16 v[116:119], v[132:135], v[202:205], v[116:119]
	v_mfma_f32_16x16x32_bf16 v[116:119], v[136:139], v[206:209], v[116:119]
	v_mfma_f32_16x16x32_bf16 v[112:115], v[140:143], v[202:205], v[112:115]
	v_mfma_f32_16x16x32_bf16 v[112:115], v[166:169], v[206:209], v[112:115]
	v_mfma_f32_16x16x32_bf16 v[108:111], v[132:135], v[210:213], v[108:111]
	v_mfma_f32_16x16x32_bf16 v[108:111], v[136:139], v[214:217], v[108:111]
	v_mfma_f32_16x16x32_bf16 v[104:107], v[140:143], v[210:213], v[104:107]
	v_mfma_f32_16x16x32_bf16 v[104:107], v[166:169], v[214:217], v[104:107]
	v_mfma_f32_16x16x32_bf16 v[100:103], v[132:135], v[218:221], v[100:103]
	v_mfma_f32_16x16x32_bf16 v[100:103], v[136:139], v[222:225], v[100:103]
	v_mfma_f32_16x16x32_bf16 v[96:99], v[140:143], v[218:221], v[96:99]
	v_mfma_f32_16x16x32_bf16 v[96:99], v[166:169], v[222:225], v[96:99]
	s_setprio 0
	s_setprio 1
	v_mfma_f32_16x16x32_bf16 v[92:95], v[178:181], v[194:197], v[92:95]
	v_mfma_f32_16x16x32_bf16 v[92:95], v[182:185], v[198:201], v[92:95]
	v_mfma_f32_16x16x32_bf16 v[88:91], v[186:189], v[194:197], v[88:91]
	v_mfma_f32_16x16x32_bf16 v[88:91], v[190:193], v[198:201], v[88:91]
	v_mfma_f32_16x16x32_bf16 v[84:87], v[178:181], v[202:205], v[84:87]
	v_mfma_f32_16x16x32_bf16 v[84:87], v[182:185], v[206:209], v[84:87]
	v_mfma_f32_16x16x32_bf16 v[80:83], v[186:189], v[202:205], v[80:83]
	v_mfma_f32_16x16x32_bf16 v[80:83], v[190:193], v[206:209], v[80:83]
	v_mfma_f32_16x16x32_bf16 v[76:79], v[178:181], v[210:213], v[76:79]
	v_mfma_f32_16x16x32_bf16 v[76:79], v[182:185], v[214:217], v[76:79]
	v_mfma_f32_16x16x32_bf16 v[72:75], v[186:189], v[210:213], v[72:75]
	v_mfma_f32_16x16x32_bf16 v[72:75], v[190:193], v[214:217], v[72:75]
	v_mfma_f32_16x16x32_bf16 v[68:71], v[178:181], v[218:221], v[68:71]
	v_mfma_f32_16x16x32_bf16 v[68:71], v[182:185], v[222:225], v[68:71]
	v_mfma_f32_16x16x32_bf16 v[64:67], v[186:189], v[218:221], v[64:67]
	v_mfma_f32_16x16x32_bf16 v[64:67], v[190:193], v[222:225], v[64:67]
	s_setprio 0
	s_barrier
	s_add_i32 s43, s43, s17
	s_add_u32 s98, s94, s70
	s_addc_u32 s99, s95, s71
	s_mov_b32 m0, s43
	ds_read_b128 v[194:197], v173 offset:16384
	ds_read_b128 v[198:201], v173 offset:17408
	ds_read_b128 v[202:205], v173 offset:18432
	ds_read_b128 v[206:209], v173 offset:19456
	ds_read_b128 v[210:213], v173 offset:20480
	ds_read_b128 v[214:217], v173 offset:21504
	ds_read_b128 v[218:221], v173 offset:22528
	ds_read_b128 v[222:225], v173 offset:23552
	global_load_lds_dwordx4 v146, s[94:95]
	s_add_i32 m0, s43, 0x2000
	s_add_u32 vcc_lo, s94, 0x80000
	s_addc_u32 vcc_hi, s95, 0
	s_add_i32 s43, s8, s17
	global_load_lds_dwordx4 v150, s[94:95]
	s_mov_b32 m0, s43
	s_nop 0
	global_load_lds_dwordx4 v146, vcc
	s_add_i32 m0, s43, 0x2000
	s_nop 0
	global_load_lds_dwordx4 v150, vcc
	s_add_u32 s100, s96, s70
	s_addc_u32 s101, s97, s71
	s_mov_b32 m0, s21
	s_nop 0
	global_load_lds_dwordx4 v144, s[96:97]
	s_mov_b32 m0, s39
	s_nop 0
	global_load_lds_dwordx4 v148, s[96:97]
	s_waitcnt vmcnt(8)
	s_waitcnt lgkmcnt(0)
	s_barrier
	s_setprio 1
	s_waitcnt lgkmcnt(0)
	v_mfma_f32_16x16x32_bf16 v[60:63], v[132:135], v[194:197], v[60:63]
	v_mfma_f32_16x16x32_bf16 v[60:63], v[136:139], v[198:201], v[60:63]
	v_mfma_f32_16x16x32_bf16 v[56:59], v[140:143], v[194:197], v[56:59]
	v_mfma_f32_16x16x32_bf16 v[56:59], v[166:169], v[198:201], v[56:59]
	v_mfma_f32_16x16x32_bf16 v[52:55], v[132:135], v[202:205], v[52:55]
	v_mfma_f32_16x16x32_bf16 v[52:55], v[136:139], v[206:209], v[52:55]
	v_mfma_f32_16x16x32_bf16 v[48:51], v[140:143], v[202:205], v[48:51]
	v_mfma_f32_16x16x32_bf16 v[48:51], v[166:169], v[206:209], v[48:51]
	v_mfma_f32_16x16x32_bf16 v[44:47], v[132:135], v[210:213], v[44:47]
	v_mfma_f32_16x16x32_bf16 v[44:47], v[136:139], v[214:217], v[44:47]
	v_mfma_f32_16x16x32_bf16 v[40:43], v[140:143], v[210:213], v[40:43]
	v_mfma_f32_16x16x32_bf16 v[40:43], v[166:169], v[214:217], v[40:43]
	v_mfma_f32_16x16x32_bf16 v[36:39], v[132:135], v[218:221], v[36:39]
	v_mfma_f32_16x16x32_bf16 v[36:39], v[136:139], v[222:225], v[36:39]
	v_mfma_f32_16x16x32_bf16 v[32:35], v[140:143], v[218:221], v[32:35]
	v_mfma_f32_16x16x32_bf16 v[32:35], v[166:169], v[222:225], v[32:35]
	s_setprio 0
	s_setprio 1
	v_mfma_f32_16x16x32_bf16 v[28:31], v[178:181], v[194:197], v[28:31]
	v_mfma_f32_16x16x32_bf16 v[28:31], v[182:185], v[198:201], v[28:31]
	v_mfma_f32_16x16x32_bf16 v[24:27], v[186:189], v[194:197], v[24:27]
	v_mfma_f32_16x16x32_bf16 v[24:27], v[190:193], v[198:201], v[24:27]
	v_mfma_f32_16x16x32_bf16 v[20:23], v[178:181], v[202:205], v[20:23]
	v_mfma_f32_16x16x32_bf16 v[20:23], v[182:185], v[206:209], v[20:23]
	v_mfma_f32_16x16x32_bf16 v[16:19], v[186:189], v[202:205], v[16:19]
	v_mfma_f32_16x16x32_bf16 v[16:19], v[190:193], v[206:209], v[16:19]
	v_mfma_f32_16x16x32_bf16 v[12:15], v[178:181], v[210:213], v[12:15]
	v_mfma_f32_16x16x32_bf16 v[12:15], v[182:185], v[214:217], v[12:15]
	v_mfma_f32_16x16x32_bf16 v[8:11], v[186:189], v[210:213], v[8:11]
	v_mfma_f32_16x16x32_bf16 v[8:11], v[190:193], v[214:217], v[8:11]
	v_mfma_f32_16x16x32_bf16 v[4:7], v[178:181], v[218:221], v[4:7]
	v_mfma_f32_16x16x32_bf16 v[4:7], v[182:185], v[222:225], v[4:7]
	v_mfma_f32_16x16x32_bf16 v[0:3], v[186:189], v[218:221], v[0:3]
	v_mfma_f32_16x16x32_bf16 v[0:3], v[190:193], v[222:225], v[0:3]
	s_setprio 0
	s_barrier
	s_add_i32 s43, 0, 0x18000
	v_add_u32_e32 v152, s43, v171
	s_add_i32 vcc_lo, 0, 0x1c000
	ds_read_b128 v[132:135], v152
	ds_read_b128 v[136:139], v152 offset:1024
	ds_read_b128 v[140:143], v152 offset:2048
	ds_read_b128 v[166:169], v152 offset:3072
	v_add_u32_e32 v152, vcc_lo, v171
	ds_read_b128 v[178:181], v152
	ds_read_b128 v[182:185], v152 offset:1024
	ds_read_b128 v[186:189], v152 offset:2048
	ds_read_b128 v[190:193], v152 offset:3072
	s_add_u32 s96, s96, 0x80000
	s_addc_u32 s97, s97, 0
	s_mov_b32 m0, s6
	ds_read_b128 v[194:197], v173 offset:32768
	ds_read_b128 v[198:201], v173 offset:33792
	ds_read_b128 v[202:205], v173 offset:34816
	ds_read_b128 v[206:209], v173 offset:35840
	ds_read_b128 v[210:213], v173 offset:36864
	ds_read_b128 v[214:217], v173 offset:37888
	ds_read_b128 v[218:221], v173 offset:38912
	ds_read_b128 v[222:225], v173 offset:39936
	global_load_lds_dwordx4 v144, s[96:97]
	s_mov_b32 m0, s10
	s_nop 0
	global_load_lds_dwordx4 v148, s[96:97]
	s_waitcnt vmcnt(8)
	s_waitcnt lgkmcnt(0)
	s_barrier
	s_setprio 1
	v_mfma_f32_16x16x32_bf16 v[124:127], v[132:135], v[194:197], v[124:127]
	v_mfma_f32_16x16x32_bf16 v[124:127], v[136:139], v[198:201], v[124:127]
	v_mfma_f32_16x16x32_bf16 v[120:123], v[140:143], v[194:197], v[120:123]
	v_mfma_f32_16x16x32_bf16 v[120:123], v[166:169], v[198:201], v[120:123]
	v_mfma_f32_16x16x32_bf16 v[116:119], v[132:135], v[202:205], v[116:119]
	v_mfma_f32_16x16x32_bf16 v[116:119], v[136:139], v[206:209], v[116:119]
	v_mfma_f32_16x16x32_bf16 v[112:115], v[140:143], v[202:205], v[112:115]
	v_mfma_f32_16x16x32_bf16 v[112:115], v[166:169], v[206:209], v[112:115]
	v_mfma_f32_16x16x32_bf16 v[108:111], v[132:135], v[210:213], v[108:111]
	v_mfma_f32_16x16x32_bf16 v[108:111], v[136:139], v[214:217], v[108:111]
	v_mfma_f32_16x16x32_bf16 v[104:107], v[140:143], v[210:213], v[104:107]
	v_mfma_f32_16x16x32_bf16 v[104:107], v[166:169], v[214:217], v[104:107]
	v_mfma_f32_16x16x32_bf16 v[100:103], v[132:135], v[218:221], v[100:103]
	v_mfma_f32_16x16x32_bf16 v[100:103], v[136:139], v[222:225], v[100:103]
	v_mfma_f32_16x16x32_bf16 v[96:99], v[140:143], v[218:221], v[96:99]
	v_mfma_f32_16x16x32_bf16 v[96:99], v[166:169], v[222:225], v[96:99]
	s_setprio 0
	s_setprio 1
	v_mfma_f32_16x16x32_bf16 v[92:95], v[178:181], v[194:197], v[92:95]
	v_mfma_f32_16x16x32_bf16 v[92:95], v[182:185], v[198:201], v[92:95]
	v_mfma_f32_16x16x32_bf16 v[88:91], v[186:189], v[194:197], v[88:91]
	v_mfma_f32_16x16x32_bf16 v[88:91], v[190:193], v[198:201], v[88:91]
	v_mfma_f32_16x16x32_bf16 v[84:87], v[178:181], v[202:205], v[84:87]
	v_mfma_f32_16x16x32_bf16 v[84:87], v[182:185], v[206:209], v[84:87]
	v_mfma_f32_16x16x32_bf16 v[80:83], v[186:189], v[202:205], v[80:83]
	v_mfma_f32_16x16x32_bf16 v[80:83], v[190:193], v[206:209], v[80:83]
	v_mfma_f32_16x16x32_bf16 v[76:79], v[178:181], v[210:213], v[76:79]
	v_mfma_f32_16x16x32_bf16 v[76:79], v[182:185], v[214:217], v[76:79]
	v_mfma_f32_16x16x32_bf16 v[72:75], v[186:189], v[210:213], v[72:75]
	v_mfma_f32_16x16x32_bf16 v[72:75], v[190:193], v[214:217], v[72:75]
	v_mfma_f32_16x16x32_bf16 v[68:71], v[178:181], v[218:221], v[68:71]
	v_mfma_f32_16x16x32_bf16 v[68:71], v[182:185], v[222:225], v[68:71]
	v_mfma_f32_16x16x32_bf16 v[64:67], v[186:189], v[218:221], v[64:67]
	v_mfma_f32_16x16x32_bf16 v[64:67], v[190:193], v[222:225], v[64:67]
	s_setprio 0
	s_barrier
	s_add_i32 s43, s43, s17
	s_mov_b32 m0, s43
	ds_read_b128 v[194:197], v173 offset:49152
	ds_read_b128 v[198:201], v173 offset:50176
	ds_read_b128 v[202:205], v173 offset:51200
	ds_read_b128 v[206:209], v173 offset:52224
	ds_read_b128 v[210:213], v173 offset:53248
	ds_read_b128 v[214:217], v173 offset:54272
	ds_read_b128 v[218:221], v173 offset:55296
	ds_read_b128 v[222:225], v173 offset:56320
	global_load_lds_dwordx4 v146, s[98:99]
	s_add_i32 m0, s43, 0x2000
	s_add_u32 s94, s94, 0x80080
	s_addc_u32 s95, s95, 0
	s_add_i32 s43, vcc_lo, s17
	global_load_lds_dwordx4 v150, s[98:99]
	s_mov_b32 m0, s43
	s_nop 0
	global_load_lds_dwordx4 v146, s[94:95]
	s_add_i32 m0, s43, 0x2000
	s_nop 0
	global_load_lds_dwordx4 v150, s[94:95]
	s_mov_b32 m0, s33
	s_nop 0
	global_load_lds_dwordx4 v144, s[100:101]
	s_mov_b32 m0, s7
	s_nop 0
	global_load_lds_dwordx4 v148, s[100:101]
	s_waitcnt vmcnt(8)
	s_waitcnt lgkmcnt(0)
	s_barrier
	s_setprio 1
	s_waitcnt lgkmcnt(0)
	v_mfma_f32_16x16x32_bf16 v[60:63], v[132:135], v[194:197], v[60:63]
	v_mfma_f32_16x16x32_bf16 v[60:63], v[136:139], v[198:201], v[60:63]
	v_mfma_f32_16x16x32_bf16 v[56:59], v[140:143], v[194:197], v[56:59]
	v_mfma_f32_16x16x32_bf16 v[56:59], v[166:169], v[198:201], v[56:59]
	v_mfma_f32_16x16x32_bf16 v[52:55], v[132:135], v[202:205], v[52:55]
	v_mfma_f32_16x16x32_bf16 v[52:55], v[136:139], v[206:209], v[52:55]
	v_mfma_f32_16x16x32_bf16 v[48:51], v[140:143], v[202:205], v[48:51]
	v_mfma_f32_16x16x32_bf16 v[48:51], v[166:169], v[206:209], v[48:51]
	v_mfma_f32_16x16x32_bf16 v[44:47], v[132:135], v[210:213], v[44:47]
	v_mfma_f32_16x16x32_bf16 v[44:47], v[136:139], v[214:217], v[44:47]
	v_mfma_f32_16x16x32_bf16 v[40:43], v[140:143], v[210:213], v[40:43]
	v_mfma_f32_16x16x32_bf16 v[40:43], v[166:169], v[214:217], v[40:43]
	v_mfma_f32_16x16x32_bf16 v[36:39], v[132:135], v[218:221], v[36:39]
	v_mfma_f32_16x16x32_bf16 v[36:39], v[136:139], v[222:225], v[36:39]
	v_mfma_f32_16x16x32_bf16 v[32:35], v[140:143], v[218:221], v[32:35]
	v_mfma_f32_16x16x32_bf16 v[32:35], v[166:169], v[222:225], v[32:35]
	s_setprio 0
	s_setprio 1
	v_mfma_f32_16x16x32_bf16 v[28:31], v[178:181], v[194:197], v[28:31]
	v_mfma_f32_16x16x32_bf16 v[28:31], v[182:185], v[198:201], v[28:31]
	v_mfma_f32_16x16x32_bf16 v[24:27], v[186:189], v[194:197], v[24:27]
	v_mfma_f32_16x16x32_bf16 v[24:27], v[190:193], v[198:201], v[24:27]
	v_mfma_f32_16x16x32_bf16 v[20:23], v[178:181], v[202:205], v[20:23]
	v_mfma_f32_16x16x32_bf16 v[20:23], v[182:185], v[206:209], v[20:23]
	v_mfma_f32_16x16x32_bf16 v[16:19], v[186:189], v[202:205], v[16:19]
	v_mfma_f32_16x16x32_bf16 v[16:19], v[190:193], v[206:209], v[16:19]
	v_mfma_f32_16x16x32_bf16 v[12:15], v[178:181], v[210:213], v[12:15]
	v_mfma_f32_16x16x32_bf16 v[12:15], v[182:185], v[214:217], v[12:15]
	v_mfma_f32_16x16x32_bf16 v[8:11], v[186:189], v[210:213], v[8:11]
	v_mfma_f32_16x16x32_bf16 v[8:11], v[190:193], v[214:217], v[8:11]
	v_mfma_f32_16x16x32_bf16 v[4:7], v[178:181], v[218:221], v[4:7]
	v_mfma_f32_16x16x32_bf16 v[4:7], v[182:185], v[222:225], v[4:7]
	v_mfma_f32_16x16x32_bf16 v[0:3], v[186:189], v[218:221], v[0:3]
	v_mfma_f32_16x16x32_bf16 v[0:3], v[190:193], v[222:225], v[0:3]
	s_setprio 0
	s_barrier
	s_add_i32 s83, s83, 2
	s_add_u32 s92, s92, 0x100
	s_addc_u32 s93, s93, 0
	s_cmp_gt_u32 s83, 29
	s_cbranch_scc0 .LBB0_241
	s_and_b64 vcc, exec, s[72:73]
	s_cbranch_vccz .LBB0_244
	s_barrier

.LBB0_273:
	ds_read_b128 v[146:149], v141
	ds_read_b128 v[150:153], v141 offset:1024
	ds_read_b128 v[154:157], v141 offset:2048
	ds_read_b128 v[158:161], v141 offset:3072
	ds_read_b128 v[162:165], v142
	ds_read_b128 v[166:169], v142 offset:1024
	ds_read_b128 v[170:173], v142 offset:2048
	ds_read_b128 v[176:179], v142 offset:3072
	s_add_u32 s48, s46, 0xfff80080
	s_addc_u32 s49, s47, -1
	s_cmp_eq_u32 s80, 4
	s_cselect_b32 s69, s39, s49
	s_cselect_b32 s68, s38, s48
	s_cselect_b32 s49, s43, s79
	s_cselect_b32 s48, s42, s27
	s_add_i32 m0, s10, 0xc000
	ds_read_b128 v[180:183], v143
	ds_read_b128 v[184:187], v143 offset:1024
	ds_read_b128 v[188:191], v143 offset:2048
	ds_read_b128 v[192:195], v143 offset:3072
	ds_read_b128 v[196:199], v143 offset:4096
	ds_read_b128 v[200:203], v143 offset:5120
	ds_read_b128 v[204:207], v143 offset:6144
	ds_read_b128 v[208:211], v143 offset:7168
	global_load_lds_dwordx4 v136, s[46:47]
	s_add_i32 m0, s10, 0xe000
	s_nop 0
	global_load_lds_dwordx4 v138, s[46:47]
	s_waitcnt vmcnt(8)
	s_waitcnt lgkmcnt(0)
	s_barrier
	s_setprio 1
	v_mfma_f32_16x16x32_bf16 v[124:127], v[146:149], v[180:183], v[124:127]
	v_mfma_f32_16x16x32_bf16 v[124:127], v[150:153], v[184:187], v[124:127]
	v_mfma_f32_16x16x32_bf16 v[120:123], v[154:157], v[180:183], v[120:123]
	v_mfma_f32_16x16x32_bf16 v[120:123], v[158:161], v[184:187], v[120:123]
	v_mfma_f32_16x16x32_bf16 v[116:119], v[146:149], v[188:191], v[116:119]
	v_mfma_f32_16x16x32_bf16 v[116:119], v[150:153], v[192:195], v[116:119]
	v_mfma_f32_16x16x32_bf16 v[112:115], v[154:157], v[188:191], v[112:115]
	v_mfma_f32_16x16x32_bf16 v[112:115], v[158:161], v[192:195], v[112:115]
	v_mfma_f32_16x16x32_bf16 v[100:103], v[146:149], v[196:199], v[100:103]
	v_mfma_f32_16x16x32_bf16 v[100:103], v[150:153], v[200:203], v[100:103]
	v_mfma_f32_16x16x32_bf16 v[96:99], v[154:157], v[196:199], v[96:99]
	v_mfma_f32_16x16x32_bf16 v[96:99], v[158:161], v[200:203], v[96:99]
	v_mfma_f32_16x16x32_bf16 v[84:87], v[146:149], v[204:207], v[84:87]
	v_mfma_f32_16x16x32_bf16 v[84:87], v[150:153], v[208:211], v[84:87]
	v_mfma_f32_16x16x32_bf16 v[80:83], v[154:157], v[204:207], v[80:83]
	v_mfma_f32_16x16x32_bf16 v[80:83], v[158:161], v[208:211], v[80:83]
	s_setprio 0
	s_setprio 1
	v_mfma_f32_16x16x32_bf16 v[108:111], v[162:165], v[180:183], v[108:111]
	v_mfma_f32_16x16x32_bf16 v[108:111], v[166:169], v[184:187], v[108:111]
	v_mfma_f32_16x16x32_bf16 v[104:107], v[170:173], v[180:183], v[104:107]
	v_mfma_f32_16x16x32_bf16 v[104:107], v[176:179], v[184:187], v[104:107]
	v_mfma_f32_16x16x32_bf16 v[92:95], v[162:165], v[188:191], v[92:95]
	v_mfma_f32_16x16x32_bf16 v[92:95], v[166:169], v[192:195], v[92:95]
	v_mfma_f32_16x16x32_bf16 v[88:91], v[170:173], v[188:191], v[88:91]
	v_mfma_f32_16x16x32_bf16 v[88:91], v[176:179], v[192:195], v[88:91]
	v_mfma_f32_16x16x32_bf16 v[76:79], v[162:165], v[196:199], v[76:79]
	v_mfma_f32_16x16x32_bf16 v[76:79], v[166:169], v[200:203], v[76:79]
	v_mfma_f32_16x16x32_bf16 v[72:75], v[170:173], v[196:199], v[72:75]
	v_mfma_f32_16x16x32_bf16 v[72:75], v[176:179], v[200:203], v[72:75]
	v_mfma_f32_16x16x32_bf16 v[68:71], v[162:165], v[204:207], v[68:71]
	v_mfma_f32_16x16x32_bf16 v[68:71], v[166:169], v[208:211], v[68:71]
	v_mfma_f32_16x16x32_bf16 v[64:67], v[170:173], v[204:207], v[64:67]
	v_mfma_f32_16x16x32_bf16 v[64:67], v[176:179], v[208:211], v[64:67]
	s_setprio 0
	s_barrier
	s_add_i32 s81, s45, s6
	s_add_u32 s98, s48, s16
	s_addc_u32 s99, s49, s17
	s_mov_b32 m0, s81
	ds_read_b128 v[180:183], v143 offset:16384
	ds_read_b128 v[184:187], v143 offset:17408
	ds_read_b128 v[188:191], v143 offset:18432
	ds_read_b128 v[192:195], v143 offset:19456
	ds_read_b128 v[196:199], v143 offset:20480
	ds_read_b128 v[200:203], v143 offset:21504
	ds_read_b128 v[204:207], v143 offset:22528
	ds_read_b128 v[208:211], v143 offset:23552
	global_load_lds_dwordx4 v132, s[48:49]
	s_add_i32 m0, s81, 0x2000
	s_add_u32 s82, s48, 0x80000
	s_addc_u32 s83, s49, 0
	s_add_i32 s81, s50, s6
	global_load_lds_dwordx4 v128, s[48:49]
	s_mov_b32 m0, s81
	s_nop 0
	global_load_lds_dwordx4 v132, s[82:83]
	s_add_i32 m0, s81, 0x2000
	s_nop 0
	global_load_lds_dwordx4 v128, s[82:83]
	s_add_u32 s100, s68, s16
	s_addc_u32 s101, s69, s17
	s_mov_b32 m0, s10
	s_nop 0
	global_load_lds_dwordx4 v134, s[68:69]
	s_mov_b32 m0, s22
	s_nop 0
	global_load_lds_dwordx4 v130, s[68:69]
	s_waitcnt vmcnt(8)
	s_waitcnt lgkmcnt(0)
	s_barrier
	s_setprio 1
	s_waitcnt lgkmcnt(0)
	v_mfma_f32_16x16x32_bf16 v[60:63], v[146:149], v[180:183], v[60:63]
	v_mfma_f32_16x16x32_bf16 v[60:63], v[150:153], v[184:187], v[60:63]
	v_mfma_f32_16x16x32_bf16 v[56:59], v[154:157], v[180:183], v[56:59]
	v_mfma_f32_16x16x32_bf16 v[56:59], v[158:161], v[184:187], v[56:59]
	v_mfma_f32_16x16x32_bf16 v[52:55], v[146:149], v[188:191], v[52:55]
	v_mfma_f32_16x16x32_bf16 v[52:55], v[150:153], v[192:195], v[52:55]
	v_mfma_f32_16x16x32_bf16 v[48:51], v[154:157], v[188:191], v[48:51]
	v_mfma_f32_16x16x32_bf16 v[48:51], v[158:161], v[192:195], v[48:51]
	v_mfma_f32_16x16x32_bf16 v[36:39], v[146:149], v[196:199], v[36:39]
	v_mfma_f32_16x16x32_bf16 v[36:39], v[150:153], v[200:203], v[36:39]
	v_mfma_f32_16x16x32_bf16 v[32:35], v[154:157], v[196:199], v[32:35]
	v_mfma_f32_16x16x32_bf16 v[32:35], v[158:161], v[200:203], v[32:35]
	v_mfma_f32_16x16x32_bf16 v[20:23], v[146:149], v[204:207], v[20:23]
	v_mfma_f32_16x16x32_bf16 v[20:23], v[150:153], v[208:211], v[20:23]
	v_mfma_f32_16x16x32_bf16 v[16:19], v[154:157], v[204:207], v[16:19]
	v_mfma_f32_16x16x32_bf16 v[16:19], v[158:161], v[208:211], v[16:19]
	s_setprio 0
	s_setprio 1
	v_mfma_f32_16x16x32_bf16 v[44:47], v[162:165], v[180:183], v[44:47]
	v_mfma_f32_16x16x32_bf16 v[44:47], v[166:169], v[184:187], v[44:47]
	v_mfma_f32_16x16x32_bf16 v[40:43], v[170:173], v[180:183], v[40:43]
	v_mfma_f32_16x16x32_bf16 v[40:43], v[176:179], v[184:187], v[40:43]
	v_mfma_f32_16x16x32_bf16 v[28:31], v[162:165], v[188:191], v[28:31]
	v_mfma_f32_16x16x32_bf16 v[28:31], v[166:169], v[192:195], v[28:31]
	v_mfma_f32_16x16x32_bf16 v[24:27], v[170:173], v[188:191], v[24:27]
	v_mfma_f32_16x16x32_bf16 v[24:27], v[176:179], v[192:195], v[24:27]
	v_mfma_f32_16x16x32_bf16 v[12:15], v[162:165], v[196:199], v[12:15]
	v_mfma_f32_16x16x32_bf16 v[12:15], v[166:169], v[200:203], v[12:15]
	v_mfma_f32_16x16x32_bf16 v[8:11], v[170:173], v[196:199], v[8:11]
	v_mfma_f32_16x16x32_bf16 v[8:11], v[176:179], v[200:203], v[8:11]
	v_mfma_f32_16x16x32_bf16 v[4:7], v[162:165], v[204:207], v[4:7]
	v_mfma_f32_16x16x32_bf16 v[4:7], v[166:169], v[208:211], v[4:7]
	v_mfma_f32_16x16x32_bf16 v[0:3], v[170:173], v[204:207], v[0:3]
	v_mfma_f32_16x16x32_bf16 v[0:3], v[176:179], v[208:211], v[0:3]
	s_setprio 0
	s_barrier
	s_add_i32 s81, 0, 0x18000
	v_add_u32_e32 v145, s81, v140
	s_add_i32 s82, 0, 0x1c000
	ds_read_b128 v[146:149], v145
	ds_read_b128 v[150:153], v145 offset:1024
	ds_read_b128 v[154:157], v145 offset:2048
	ds_read_b128 v[158:161], v145 offset:3072
	v_add_u32_e32 v145, s82, v140
	ds_read_b128 v[162:165], v145
	ds_read_b128 v[166:169], v145 offset:1024
	ds_read_b128 v[170:173], v145 offset:2048
	ds_read_b128 v[176:179], v145 offset:3072
	s_add_u32 s68, s68, 0x80000
	s_addc_u32 s69, s69, 0
	s_mov_b32 m0, s23
	ds_read_b128 v[180:183], v143 offset:32768
	ds_read_b128 v[184:187], v143 offset:33792
	ds_read_b128 v[188:191], v143 offset:34816
	ds_read_b128 v[192:195], v143 offset:35840
	ds_read_b128 v[196:199], v143 offset:36864
	ds_read_b128 v[200:203], v143 offset:37888
	ds_read_b128 v[204:207], v143 offset:38912
	ds_read_b128 v[208:211], v143 offset:39936
	global_load_lds_dwordx4 v134, s[68:69]
	s_mov_b32 m0, s33
	s_nop 0
	global_load_lds_dwordx4 v130, s[68:69]
	s_waitcnt vmcnt(8)
	s_waitcnt lgkmcnt(0)
	s_barrier
	s_setprio 1
	v_mfma_f32_16x16x32_bf16 v[124:127], v[146:149], v[180:183], v[124:127]
	v_mfma_f32_16x16x32_bf16 v[124:127], v[150:153], v[184:187], v[124:127]
	v_mfma_f32_16x16x32_bf16 v[120:123], v[154:157], v[180:183], v[120:123]
	v_mfma_f32_16x16x32_bf16 v[120:123], v[158:161], v[184:187], v[120:123]
	v_mfma_f32_16x16x32_bf16 v[116:119], v[146:149], v[188:191], v[116:119]
	v_mfma_f32_16x16x32_bf16 v[116:119], v[150:153], v[192:195], v[116:119]
	v_mfma_f32_16x16x32_bf16 v[112:115], v[154:157], v[188:191], v[112:115]
	v_mfma_f32_16x16x32_bf16 v[112:115], v[158:161], v[192:195], v[112:115]
	v_mfma_f32_16x16x32_bf16 v[100:103], v[146:149], v[196:199], v[100:103]
	v_mfma_f32_16x16x32_bf16 v[100:103], v[150:153], v[200:203], v[100:103]
	v_mfma_f32_16x16x32_bf16 v[96:99], v[154:157], v[196:199], v[96:99]
	v_mfma_f32_16x16x32_bf16 v[96:99], v[158:161], v[200:203], v[96:99]
	v_mfma_f32_16x16x32_bf16 v[84:87], v[146:149], v[204:207], v[84:87]
	v_mfma_f32_16x16x32_bf16 v[84:87], v[150:153], v[208:211], v[84:87]
	v_mfma_f32_16x16x32_bf16 v[80:83], v[154:157], v[204:207], v[80:83]
	v_mfma_f32_16x16x32_bf16 v[80:83], v[158:161], v[208:211], v[80:83]
	s_setprio 0
	s_setprio 1
	v_mfma_f32_16x16x32_bf16 v[108:111], v[162:165], v[180:183], v[108:111]
	v_mfma_f32_16x16x32_bf16 v[108:111], v[166:169], v[184:187], v[108:111]
	v_mfma_f32_16x16x32_bf16 v[104:107], v[170:173], v[180:183], v[104:107]
	v_mfma_f32_16x16x32_bf16 v[104:107], v[176:179], v[184:187], v[104:107]
	v_mfma_f32_16x16x32_bf16 v[92:95], v[162:165], v[188:191], v[92:95]
	v_mfma_f32_16x16x32_bf16 v[92:95], v[166:169], v[192:195], v[92:95]
	v_mfma_f32_16x16x32_bf16 v[88:91], v[170:173], v[188:191], v[88:91]
	v_mfma_f32_16x16x32_bf16 v[88:91], v[176:179], v[192:195], v[88:91]
	v_mfma_f32_16x16x32_bf16 v[76:79], v[162:165], v[196:199], v[76:79]
	v_mfma_f32_16x16x32_bf16 v[76:79], v[166:169], v[200:203], v[76:79]
	v_mfma_f32_16x16x32_bf16 v[72:75], v[170:173], v[196:199], v[72:75]
	v_mfma_f32_16x16x32_bf16 v[72:75], v[176:179], v[200:203], v[72:75]
	v_mfma_f32_16x16x32_bf16 v[68:71], v[162:165], v[204:207], v[68:71]
	v_mfma_f32_16x16x32_bf16 v[68:71], v[166:169], v[208:211], v[68:71]
	v_mfma_f32_16x16x32_bf16 v[64:67], v[170:173], v[204:207], v[64:67]
	v_mfma_f32_16x16x32_bf16 v[64:67], v[176:179], v[208:211], v[64:67]
	s_setprio 0
	s_barrier
	s_add_i32 s68, s81, s6
	s_mov_b32 m0, s68
	ds_read_b128 v[180:183], v143 offset:49152
	ds_read_b128 v[184:187], v143 offset:50176
	ds_read_b128 v[188:191], v143 offset:51200
	ds_read_b128 v[192:195], v143 offset:52224
	ds_read_b128 v[196:199], v143 offset:53248
	ds_read_b128 v[200:203], v143 offset:54272
	ds_read_b128 v[204:207], v143 offset:55296
	ds_read_b128 v[208:211], v143 offset:56320
	global_load_lds_dwordx4 v132, s[98:99]
	s_add_i32 m0, s68, 0x2000
	s_add_u32 s48, s48, 0x80080
	s_addc_u32 s49, s49, 0
	s_add_i32 s68, s82, s6
	global_load_lds_dwordx4 v128, s[98:99]
	s_mov_b32 m0, s68
	s_nop 0
	global_load_lds_dwordx4 v132, s[48:49]
	s_add_i32 m0, s68, 0x2000
	s_nop 0
	global_load_lds_dwordx4 v128, s[48:49]
	s_mov_b32 m0, s41
	s_nop 0
	global_load_lds_dwordx4 v134, s[100:101]
	s_mov_b32 m0, s44
	s_nop 0
	global_load_lds_dwordx4 v130, s[100:101]
	s_waitcnt vmcnt(8)
	s_waitcnt lgkmcnt(0)
	s_barrier
	s_setprio 1
	s_waitcnt lgkmcnt(0)
	v_mfma_f32_16x16x32_bf16 v[60:63], v[146:149], v[180:183], v[60:63]
	v_mfma_f32_16x16x32_bf16 v[60:63], v[150:153], v[184:187], v[60:63]
	v_mfma_f32_16x16x32_bf16 v[56:59], v[154:157], v[180:183], v[56:59]
	v_mfma_f32_16x16x32_bf16 v[56:59], v[158:161], v[184:187], v[56:59]
	v_mfma_f32_16x16x32_bf16 v[52:55], v[146:149], v[188:191], v[52:55]
	v_mfma_f32_16x16x32_bf16 v[52:55], v[150:153], v[192:195], v[52:55]
	v_mfma_f32_16x16x32_bf16 v[48:51], v[154:157], v[188:191], v[48:51]
	v_mfma_f32_16x16x32_bf16 v[48:51], v[158:161], v[192:195], v[48:51]
	v_mfma_f32_16x16x32_bf16 v[36:39], v[146:149], v[196:199], v[36:39]
	v_mfma_f32_16x16x32_bf16 v[36:39], v[150:153], v[200:203], v[36:39]
	v_mfma_f32_16x16x32_bf16 v[32:35], v[154:157], v[196:199], v[32:35]
	v_mfma_f32_16x16x32_bf16 v[32:35], v[158:161], v[200:203], v[32:35]
	v_mfma_f32_16x16x32_bf16 v[20:23], v[146:149], v[204:207], v[20:23]
	v_mfma_f32_16x16x32_bf16 v[20:23], v[150:153], v[208:211], v[20:23]
	v_mfma_f32_16x16x32_bf16 v[16:19], v[154:157], v[204:207], v[16:19]
	v_mfma_f32_16x16x32_bf16 v[16:19], v[158:161], v[208:211], v[16:19]
	s_setprio 0
	s_setprio 1
	v_mfma_f32_16x16x32_bf16 v[44:47], v[162:165], v[180:183], v[44:47]
	v_mfma_f32_16x16x32_bf16 v[44:47], v[166:169], v[184:187], v[44:47]
	v_mfma_f32_16x16x32_bf16 v[40:43], v[170:173], v[180:183], v[40:43]
	v_mfma_f32_16x16x32_bf16 v[40:43], v[176:179], v[184:187], v[40:43]
	v_mfma_f32_16x16x32_bf16 v[28:31], v[162:165], v[188:191], v[28:31]
	v_mfma_f32_16x16x32_bf16 v[28:31], v[166:169], v[192:195], v[28:31]
	v_mfma_f32_16x16x32_bf16 v[24:27], v[170:173], v[188:191], v[24:27]
	v_mfma_f32_16x16x32_bf16 v[24:27], v[176:179], v[192:195], v[24:27]
	v_mfma_f32_16x16x32_bf16 v[12:15], v[162:165], v[196:199], v[12:15]
	v_mfma_f32_16x16x32_bf16 v[12:15], v[166:169], v[200:203], v[12:15]
	v_mfma_f32_16x16x32_bf16 v[8:11], v[170:173], v[196:199], v[8:11]
	v_mfma_f32_16x16x32_bf16 v[8:11], v[176:179], v[200:203], v[8:11]
	v_mfma_f32_16x16x32_bf16 v[4:7], v[162:165], v[204:207], v[4:7]
	v_mfma_f32_16x16x32_bf16 v[4:7], v[166:169], v[208:211], v[4:7]
	v_mfma_f32_16x16x32_bf16 v[0:3], v[170:173], v[204:207], v[0:3]
	v_mfma_f32_16x16x32_bf16 v[0:3], v[176:179], v[208:211], v[0:3]
	s_setprio 0
	s_barrier
	s_add_i32 s80, s80, 2
	s_add_u32 s46, s46, 0x100
	s_addc_u32 s47, s47, 0
	s_add_u32 s27, s27, 0x100
	s_addc_u32 s79, s79, 0
	s_cmp_gt_u32 s80, 5
	s_cbranch_scc0 .LBB0_273
	s_and_b64 vcc, exec, s[20:21]
	s_cbranch_vccz .LBB0_276
	s_barrier

.LBB0_414:
	ds_read_b128 v[146:149], v141
	ds_read_b128 v[150:153], v141 offset:1024
	ds_read_b128 v[154:157], v141 offset:2048
	ds_read_b128 v[158:161], v141 offset:3072
	ds_read_b128 v[162:165], v142
	ds_read_b128 v[166:169], v142 offset:1024
	ds_read_b128 v[170:173], v142 offset:2048
	ds_read_b128 v[176:179], v142 offset:3072
	s_add_u32 s46, s44, 0xfff80080
	s_addc_u32 s47, s45, -1
	s_cmp_eq_u32 s82, 4
	s_cselect_b32 s49, s41, s47
	s_cselect_b32 s48, s40, s46
	s_cselect_b32 s47, s43, s81
	s_cselect_b32 s46, s42, s39
	s_mov_b32 m0, s64
	ds_read_b128 v[180:183], v143
	ds_read_b128 v[184:187], v143 offset:1024
	ds_read_b128 v[188:191], v143 offset:2048
	ds_read_b128 v[192:195], v143 offset:3072
	ds_read_b128 v[196:199], v143 offset:4096
	ds_read_b128 v[200:203], v143 offset:5120
	ds_read_b128 v[204:207], v143 offset:6144
	ds_read_b128 v[208:211], v143 offset:7168
	global_load_lds_dwordx4 v136, s[44:45]
	s_mov_b32 m0, s65
	s_nop 0
	global_load_lds_dwordx4 v138, s[44:45]
	s_waitcnt vmcnt(8)
	s_waitcnt lgkmcnt(0)
	s_barrier
	s_setprio 1
	s_waitcnt lgkmcnt(0)
	v_mfma_f32_16x16x32_bf16 v[124:127], v[146:149], v[180:183], v[124:127]
	v_mfma_f32_16x16x32_bf16 v[124:127], v[150:153], v[184:187], v[124:127]
	v_mfma_f32_16x16x32_bf16 v[120:123], v[154:157], v[180:183], v[120:123]
	v_mfma_f32_16x16x32_bf16 v[120:123], v[158:161], v[184:187], v[120:123]
	v_mfma_f32_16x16x32_bf16 v[116:119], v[146:149], v[188:191], v[116:119]
	v_mfma_f32_16x16x32_bf16 v[116:119], v[150:153], v[192:195], v[116:119]
	v_mfma_f32_16x16x32_bf16 v[112:115], v[154:157], v[188:191], v[112:115]
	v_mfma_f32_16x16x32_bf16 v[112:115], v[158:161], v[192:195], v[112:115]
	v_mfma_f32_16x16x32_bf16 v[100:103], v[146:149], v[196:199], v[100:103]
	v_mfma_f32_16x16x32_bf16 v[100:103], v[150:153], v[200:203], v[100:103]
	v_mfma_f32_16x16x32_bf16 v[96:99], v[154:157], v[196:199], v[96:99]
	v_mfma_f32_16x16x32_bf16 v[96:99], v[158:161], v[200:203], v[96:99]
	v_mfma_f32_16x16x32_bf16 v[84:87], v[146:149], v[204:207], v[84:87]
	v_mfma_f32_16x16x32_bf16 v[84:87], v[150:153], v[208:211], v[84:87]
	v_mfma_f32_16x16x32_bf16 v[80:83], v[154:157], v[204:207], v[80:83]
	v_mfma_f32_16x16x32_bf16 v[80:83], v[158:161], v[208:211], v[80:83]
	s_setprio 0
	s_setprio 1
	v_mfma_f32_16x16x32_bf16 v[108:111], v[162:165], v[180:183], v[108:111]
	v_mfma_f32_16x16x32_bf16 v[108:111], v[166:169], v[184:187], v[108:111]
	v_mfma_f32_16x16x32_bf16 v[104:107], v[170:173], v[180:183], v[104:107]
	v_mfma_f32_16x16x32_bf16 v[104:107], v[176:179], v[184:187], v[104:107]
	v_mfma_f32_16x16x32_bf16 v[92:95], v[162:165], v[188:191], v[92:95]
	v_mfma_f32_16x16x32_bf16 v[92:95], v[166:169], v[192:195], v[92:95]
	v_mfma_f32_16x16x32_bf16 v[88:91], v[170:173], v[188:191], v[88:91]
	v_mfma_f32_16x16x32_bf16 v[88:91], v[176:179], v[192:195], v[88:91]
	v_mfma_f32_16x16x32_bf16 v[76:79], v[162:165], v[196:199], v[76:79]
	v_mfma_f32_16x16x32_bf16 v[76:79], v[166:169], v[200:203], v[76:79]
	v_mfma_f32_16x16x32_bf16 v[72:75], v[170:173], v[196:199], v[72:75]
	v_mfma_f32_16x16x32_bf16 v[72:75], v[176:179], v[200:203], v[72:75]
	v_mfma_f32_16x16x32_bf16 v[68:71], v[162:165], v[204:207], v[68:71]
	v_mfma_f32_16x16x32_bf16 v[68:71], v[166:169], v[208:211], v[68:71]
	v_mfma_f32_16x16x32_bf16 v[64:67], v[170:173], v[204:207], v[64:67]
	v_mfma_f32_16x16x32_bf16 v[64:67], v[176:179], v[208:211], v[64:67]
	s_setprio 0
	s_barrier
	s_mov_b32 m0, s68
	s_add_u32 s98, s46, s24
	s_addc_u32 s99, s47, s25
	s_add_u32 s84, s46, 0x80000
	ds_read_b128 v[180:183], v143 offset:16384
	ds_read_b128 v[184:187], v143 offset:17408
	ds_read_b128 v[188:191], v143 offset:18432
	ds_read_b128 v[192:195], v143 offset:19456
	ds_read_b128 v[196:199], v143 offset:20480
	ds_read_b128 v[200:203], v143 offset:21504
	ds_read_b128 v[204:207], v143 offset:22528
	ds_read_b128 v[208:211], v143 offset:23552
	global_load_lds_dwordx4 v132, s[46:47]
	s_mov_b32 m0, s69
	s_addc_u32 s85, s47, 0
	global_load_lds_dwordx4 v128, s[46:47]
	s_mov_b32 m0, s77
	s_nop 0
	global_load_lds_dwordx4 v132, s[84:85]
	s_add_i32 m0, s77, 0x2000
	s_nop 0
	global_load_lds_dwordx4 v128, s[84:85]
	s_add_u32 s100, s48, s24
	s_addc_u32 s101, s49, s25
	s_mov_b32 m0, s22
	s_nop 0
	global_load_lds_dwordx4 v134, s[48:49]
	s_mov_b32 m0, s23
	s_nop 0
	global_load_lds_dwordx4 v130, s[48:49]
	s_waitcnt vmcnt(8)
	s_waitcnt lgkmcnt(0)
	s_barrier
	s_setprio 1
	v_mfma_f32_16x16x32_bf16 v[60:63], v[146:149], v[180:183], v[60:63]
	v_mfma_f32_16x16x32_bf16 v[60:63], v[150:153], v[184:187], v[60:63]
	v_mfma_f32_16x16x32_bf16 v[56:59], v[154:157], v[180:183], v[56:59]
	v_mfma_f32_16x16x32_bf16 v[56:59], v[158:161], v[184:187], v[56:59]
	v_mfma_f32_16x16x32_bf16 v[52:55], v[146:149], v[188:191], v[52:55]
	v_mfma_f32_16x16x32_bf16 v[52:55], v[150:153], v[192:195], v[52:55]
	v_mfma_f32_16x16x32_bf16 v[48:51], v[154:157], v[188:191], v[48:51]
	v_mfma_f32_16x16x32_bf16 v[48:51], v[158:161], v[192:195], v[48:51]
	v_mfma_f32_16x16x32_bf16 v[36:39], v[146:149], v[196:199], v[36:39]
	v_mfma_f32_16x16x32_bf16 v[36:39], v[150:153], v[200:203], v[36:39]
	v_mfma_f32_16x16x32_bf16 v[32:35], v[154:157], v[196:199], v[32:35]
	v_mfma_f32_16x16x32_bf16 v[32:35], v[158:161], v[200:203], v[32:35]
	v_mfma_f32_16x16x32_bf16 v[20:23], v[146:149], v[204:207], v[20:23]
	v_mfma_f32_16x16x32_bf16 v[20:23], v[150:153], v[208:211], v[20:23]
	v_mfma_f32_16x16x32_bf16 v[16:19], v[154:157], v[204:207], v[16:19]
	v_mfma_f32_16x16x32_bf16 v[16:19], v[158:161], v[208:211], v[16:19]
	s_setprio 0
	s_setprio 1
	v_mfma_f32_16x16x32_bf16 v[44:47], v[162:165], v[180:183], v[44:47]
	v_mfma_f32_16x16x32_bf16 v[44:47], v[166:169], v[184:187], v[44:47]
	v_mfma_f32_16x16x32_bf16 v[40:43], v[170:173], v[180:183], v[40:43]
	v_mfma_f32_16x16x32_bf16 v[40:43], v[176:179], v[184:187], v[40:43]
	v_mfma_f32_16x16x32_bf16 v[28:31], v[162:165], v[188:191], v[28:31]
	v_mfma_f32_16x16x32_bf16 v[28:31], v[166:169], v[192:195], v[28:31]
	v_mfma_f32_16x16x32_bf16 v[24:27], v[170:173], v[188:191], v[24:27]
	v_mfma_f32_16x16x32_bf16 v[24:27], v[176:179], v[192:195], v[24:27]
	v_mfma_f32_16x16x32_bf16 v[12:15], v[162:165], v[196:199], v[12:15]
	v_mfma_f32_16x16x32_bf16 v[12:15], v[166:169], v[200:203], v[12:15]
	v_mfma_f32_16x16x32_bf16 v[8:11], v[170:173], v[196:199], v[8:11]
	v_mfma_f32_16x16x32_bf16 v[8:11], v[176:179], v[200:203], v[8:11]
	v_mfma_f32_16x16x32_bf16 v[4:7], v[162:165], v[204:207], v[4:7]
	v_mfma_f32_16x16x32_bf16 v[4:7], v[166:169], v[208:211], v[4:7]
	v_mfma_f32_16x16x32_bf16 v[0:3], v[170:173], v[204:207], v[0:3]
	v_mfma_f32_16x16x32_bf16 v[0:3], v[176:179], v[208:211], v[0:3]
	s_setprio 0
	s_barrier
	s_add_i32 s83, 0, 0x18000
	v_add_u32_e32 v145, s83, v140
	s_add_i32 s84, 0, 0x1c000
	ds_read_b128 v[146:149], v145
	ds_read_b128 v[150:153], v145 offset:1024
	ds_read_b128 v[154:157], v145 offset:2048
	ds_read_b128 v[158:161], v145 offset:3072
	v_add_u32_e32 v145, s84, v140
	ds_read_b128 v[162:165], v145
	ds_read_b128 v[166:169], v145 offset:1024
	ds_read_b128 v[170:173], v145 offset:2048
	ds_read_b128 v[176:179], v145 offset:3072
	s_add_u32 s48, s48, 0x80000
	s_addc_u32 s49, s49, 0
	s_mov_b32 m0, s33
	ds_read_b128 v[180:183], v143 offset:32768
	ds_read_b128 v[184:187], v143 offset:33792
	ds_read_b128 v[188:191], v143 offset:34816
	ds_read_b128 v[192:195], v143 offset:35840
	ds_read_b128 v[196:199], v143 offset:36864
	ds_read_b128 v[200:203], v143 offset:37888
	ds_read_b128 v[204:207], v143 offset:38912
	ds_read_b128 v[208:211], v143 offset:39936
	global_load_lds_dwordx4 v134, s[48:49]
	s_mov_b32 m0, s50
	s_nop 0
	global_load_lds_dwordx4 v130, s[48:49]
	s_waitcnt vmcnt(8)
	s_waitcnt lgkmcnt(0)
	s_barrier
	s_setprio 1
	v_mfma_f32_16x16x32_bf16 v[124:127], v[146:149], v[180:183], v[124:127]
	v_mfma_f32_16x16x32_bf16 v[124:127], v[150:153], v[184:187], v[124:127]
	v_mfma_f32_16x16x32_bf16 v[120:123], v[154:157], v[180:183], v[120:123]
	v_mfma_f32_16x16x32_bf16 v[120:123], v[158:161], v[184:187], v[120:123]
	v_mfma_f32_16x16x32_bf16 v[116:119], v[146:149], v[188:191], v[116:119]
	v_mfma_f32_16x16x32_bf16 v[116:119], v[150:153], v[192:195], v[116:119]
	v_mfma_f32_16x16x32_bf16 v[112:115], v[154:157], v[188:191], v[112:115]
	v_mfma_f32_16x16x32_bf16 v[112:115], v[158:161], v[192:195], v[112:115]
	v_mfma_f32_16x16x32_bf16 v[100:103], v[146:149], v[196:199], v[100:103]
	v_mfma_f32_16x16x32_bf16 v[100:103], v[150:153], v[200:203], v[100:103]
	v_mfma_f32_16x16x32_bf16 v[96:99], v[154:157], v[196:199], v[96:99]
	v_mfma_f32_16x16x32_bf16 v[96:99], v[158:161], v[200:203], v[96:99]
	v_mfma_f32_16x16x32_bf16 v[84:87], v[146:149], v[204:207], v[84:87]
	v_mfma_f32_16x16x32_bf16 v[84:87], v[150:153], v[208:211], v[84:87]
	v_mfma_f32_16x16x32_bf16 v[80:83], v[154:157], v[204:207], v[80:83]
	v_mfma_f32_16x16x32_bf16 v[80:83], v[158:161], v[208:211], v[80:83]
	s_setprio 0
	s_setprio 1
	v_mfma_f32_16x16x32_bf16 v[108:111], v[162:165], v[180:183], v[108:111]
	v_mfma_f32_16x16x32_bf16 v[108:111], v[166:169], v[184:187], v[108:111]
	v_mfma_f32_16x16x32_bf16 v[104:107], v[170:173], v[180:183], v[104:107]
	v_mfma_f32_16x16x32_bf16 v[104:107], v[176:179], v[184:187], v[104:107]
	v_mfma_f32_16x16x32_bf16 v[92:95], v[162:165], v[188:191], v[92:95]
	v_mfma_f32_16x16x32_bf16 v[92:95], v[166:169], v[192:195], v[92:95]
	v_mfma_f32_16x16x32_bf16 v[88:91], v[170:173], v[188:191], v[88:91]
	v_mfma_f32_16x16x32_bf16 v[88:91], v[176:179], v[192:195], v[88:91]
	v_mfma_f32_16x16x32_bf16 v[76:79], v[162:165], v[196:199], v[76:79]
	v_mfma_f32_16x16x32_bf16 v[76:79], v[166:169], v[200:203], v[76:79]
	v_mfma_f32_16x16x32_bf16 v[72:75], v[170:173], v[196:199], v[72:75]
	v_mfma_f32_16x16x32_bf16 v[72:75], v[176:179], v[200:203], v[72:75]
	v_mfma_f32_16x16x32_bf16 v[68:71], v[162:165], v[204:207], v[68:71]
	v_mfma_f32_16x16x32_bf16 v[68:71], v[166:169], v[208:211], v[68:71]
	v_mfma_f32_16x16x32_bf16 v[64:67], v[170:173], v[204:207], v[64:67]
	v_mfma_f32_16x16x32_bf16 v[64:67], v[176:179], v[208:211], v[64:67]
	s_setprio 0
	s_barrier
	s_add_i32 s48, s83, s10
	s_mov_b32 m0, s48
	ds_read_b128 v[180:183], v143 offset:49152
	ds_read_b128 v[184:187], v143 offset:50176
	ds_read_b128 v[188:191], v143 offset:51200
	ds_read_b128 v[192:195], v143 offset:52224
	ds_read_b128 v[196:199], v143 offset:53248
	ds_read_b128 v[200:203], v143 offset:54272
	ds_read_b128 v[204:207], v143 offset:55296
	ds_read_b128 v[208:211], v143 offset:56320
	global_load_lds_dwordx4 v132, s[98:99]
	s_add_i32 m0, s48, 0x2000
	s_add_u32 s46, s46, 0x80080
	s_addc_u32 s47, s47, 0
	s_add_i32 s48, s84, s10
	global_load_lds_dwordx4 v128, s[98:99]
	s_mov_b32 m0, s48
	s_nop 0
	global_load_lds_dwordx4 v132, s[46:47]
	s_add_i32 m0, s48, 0x2000
	s_nop 0
	global_load_lds_dwordx4 v128, s[46:47]
	s_mov_b32 m0, s62
	s_nop 0
	global_load_lds_dwordx4 v134, s[100:101]
	s_mov_b32 m0, s63
	s_nop 0
	global_load_lds_dwordx4 v130, s[100:101]
	s_waitcnt vmcnt(8)
	s_waitcnt lgkmcnt(0)
	s_barrier
	s_setprio 1
	s_waitcnt lgkmcnt(0)
	v_mfma_f32_16x16x32_bf16 v[60:63], v[146:149], v[180:183], v[60:63]
	v_mfma_f32_16x16x32_bf16 v[60:63], v[150:153], v[184:187], v[60:63]
	v_mfma_f32_16x16x32_bf16 v[56:59], v[154:157], v[180:183], v[56:59]
	v_mfma_f32_16x16x32_bf16 v[56:59], v[158:161], v[184:187], v[56:59]
	v_mfma_f32_16x16x32_bf16 v[52:55], v[146:149], v[188:191], v[52:55]
	v_mfma_f32_16x16x32_bf16 v[52:55], v[150:153], v[192:195], v[52:55]
	v_mfma_f32_16x16x32_bf16 v[48:51], v[154:157], v[188:191], v[48:51]
	v_mfma_f32_16x16x32_bf16 v[48:51], v[158:161], v[192:195], v[48:51]
	v_mfma_f32_16x16x32_bf16 v[36:39], v[146:149], v[196:199], v[36:39]
	v_mfma_f32_16x16x32_bf16 v[36:39], v[150:153], v[200:203], v[36:39]
	v_mfma_f32_16x16x32_bf16 v[32:35], v[154:157], v[196:199], v[32:35]
	v_mfma_f32_16x16x32_bf16 v[32:35], v[158:161], v[200:203], v[32:35]
	v_mfma_f32_16x16x32_bf16 v[20:23], v[146:149], v[204:207], v[20:23]
	v_mfma_f32_16x16x32_bf16 v[20:23], v[150:153], v[208:211], v[20:23]
	v_mfma_f32_16x16x32_bf16 v[16:19], v[154:157], v[204:207], v[16:19]
	v_mfma_f32_16x16x32_bf16 v[16:19], v[158:161], v[208:211], v[16:19]
	s_setprio 0
	s_setprio 1
	v_mfma_f32_16x16x32_bf16 v[44:47], v[162:165], v[180:183], v[44:47]
	v_mfma_f32_16x16x32_bf16 v[44:47], v[166:169], v[184:187], v[44:47]
	v_mfma_f32_16x16x32_bf16 v[40:43], v[170:173], v[180:183], v[40:43]
	v_mfma_f32_16x16x32_bf16 v[40:43], v[176:179], v[184:187], v[40:43]
	v_mfma_f32_16x16x32_bf16 v[28:31], v[162:165], v[188:191], v[28:31]
	v_mfma_f32_16x16x32_bf16 v[28:31], v[166:169], v[192:195], v[28:31]
	v_mfma_f32_16x16x32_bf16 v[24:27], v[170:173], v[188:191], v[24:27]
	v_mfma_f32_16x16x32_bf16 v[24:27], v[176:179], v[192:195], v[24:27]
	v_mfma_f32_16x16x32_bf16 v[12:15], v[162:165], v[196:199], v[12:15]
	v_mfma_f32_16x16x32_bf16 v[12:15], v[166:169], v[200:203], v[12:15]
	v_mfma_f32_16x16x32_bf16 v[8:11], v[170:173], v[196:199], v[8:11]
	v_mfma_f32_16x16x32_bf16 v[8:11], v[176:179], v[200:203], v[8:11]
	v_mfma_f32_16x16x32_bf16 v[4:7], v[162:165], v[204:207], v[4:7]
	v_mfma_f32_16x16x32_bf16 v[4:7], v[166:169], v[208:211], v[4:7]
	v_mfma_f32_16x16x32_bf16 v[0:3], v[170:173], v[204:207], v[0:3]
	v_mfma_f32_16x16x32_bf16 v[0:3], v[176:179], v[208:211], v[0:3]
	s_setprio 0
	s_barrier
	s_add_i32 s82, s82, 2
	s_add_u32 s44, s44, 0x100
	s_addc_u32 s45, s45, 0
	s_add_u32 s39, s39, 0x100
	s_addc_u32 s81, s81, 0
	s_cmp_gt_u32 s82, 5
	s_cbranch_scc0 .LBB0_414
	s_and_b64 vcc, exec, s[36:37]
	s_cbranch_vccz .LBB0_417
	s_barrier

.LBB0_428:
	ds_read_b128 v[148:151], v143
	ds_read_b128 v[152:155], v143 offset:1024
	ds_read_b128 v[156:159], v143 offset:2048
	ds_read_b128 v[160:163], v143 offset:3072
	ds_read_b128 v[164:167], v144
	ds_read_b128 v[168:171], v144 offset:1024
	ds_read_b128 v[176:179], v144 offset:2048
	ds_read_b128 v[180:183], v144 offset:3072
	s_add_u32 s48, s46, 0xfff80080
	s_addc_u32 s49, s47, -1
	s_cmp_eq_u32 s83, 4
	s_cselect_b32 s51, s77, s49
	s_cselect_b32 s50, s78, s48
	s_cselect_b32 s49, s79, s82
	s_cselect_b32 s48, s80, s81
	s_add_i32 m0, s15, 0xc000
	ds_read_b128 v[184:187], v145
	ds_read_b128 v[188:191], v145 offset:1024
	ds_read_b128 v[192:195], v145 offset:2048
	ds_read_b128 v[196:199], v145 offset:3072
	ds_read_b128 v[200:203], v145 offset:4096
	ds_read_b128 v[204:207], v145 offset:5120
	ds_read_b128 v[208:211], v145 offset:6144
	ds_read_b128 v[212:215], v145 offset:7168
	global_load_lds_dwordx4 v138, s[46:47]
	s_add_i32 m0, s15, 0xe000
	s_nop 0
	global_load_lds_dwordx4 v140, s[46:47]
	s_waitcnt vmcnt(8)
	s_waitcnt lgkmcnt(0)
	s_barrier
	s_setprio 1
	s_waitcnt lgkmcnt(0)
	v_mfma_f32_16x16x32_bf16 v[124:127], v[148:151], v[184:187], v[124:127]
	v_mfma_f32_16x16x32_bf16 v[124:127], v[152:155], v[188:191], v[124:127]
	v_mfma_f32_16x16x32_bf16 v[120:123], v[156:159], v[184:187], v[120:123]
	v_mfma_f32_16x16x32_bf16 v[120:123], v[160:163], v[188:191], v[120:123]
	v_mfma_f32_16x16x32_bf16 v[116:119], v[148:151], v[192:195], v[116:119]
	v_mfma_f32_16x16x32_bf16 v[116:119], v[152:155], v[196:199], v[116:119]
	v_mfma_f32_16x16x32_bf16 v[112:115], v[156:159], v[192:195], v[112:115]
	v_mfma_f32_16x16x32_bf16 v[112:115], v[160:163], v[196:199], v[112:115]
	v_mfma_f32_16x16x32_bf16 v[100:103], v[148:151], v[200:203], v[100:103]
	v_mfma_f32_16x16x32_bf16 v[100:103], v[152:155], v[204:207], v[100:103]
	v_mfma_f32_16x16x32_bf16 v[96:99], v[156:159], v[200:203], v[96:99]
	v_mfma_f32_16x16x32_bf16 v[96:99], v[160:163], v[204:207], v[96:99]
	v_mfma_f32_16x16x32_bf16 v[84:87], v[148:151], v[208:211], v[84:87]
	v_mfma_f32_16x16x32_bf16 v[84:87], v[152:155], v[212:215], v[84:87]
	v_mfma_f32_16x16x32_bf16 v[80:83], v[156:159], v[208:211], v[80:83]
	v_mfma_f32_16x16x32_bf16 v[80:83], v[160:163], v[212:215], v[80:83]
	s_setprio 0
	s_setprio 1
	v_mfma_f32_16x16x32_bf16 v[108:111], v[164:167], v[184:187], v[108:111]
	v_mfma_f32_16x16x32_bf16 v[108:111], v[168:171], v[188:191], v[108:111]
	v_mfma_f32_16x16x32_bf16 v[104:107], v[176:179], v[184:187], v[104:107]
	v_mfma_f32_16x16x32_bf16 v[104:107], v[180:183], v[188:191], v[104:107]
	v_mfma_f32_16x16x32_bf16 v[92:95], v[164:167], v[192:195], v[92:95]
	v_mfma_f32_16x16x32_bf16 v[92:95], v[168:171], v[196:199], v[92:95]
	v_mfma_f32_16x16x32_bf16 v[88:91], v[176:179], v[192:195], v[88:91]
	v_mfma_f32_16x16x32_bf16 v[88:91], v[180:183], v[196:199], v[88:91]
	v_mfma_f32_16x16x32_bf16 v[76:79], v[164:167], v[200:203], v[76:79]
	v_mfma_f32_16x16x32_bf16 v[76:79], v[168:171], v[204:207], v[76:79]
	v_mfma_f32_16x16x32_bf16 v[72:75], v[176:179], v[200:203], v[72:75]
	v_mfma_f32_16x16x32_bf16 v[72:75], v[180:183], v[204:207], v[72:75]
	v_mfma_f32_16x16x32_bf16 v[68:71], v[164:167], v[208:211], v[68:71]
	v_mfma_f32_16x16x32_bf16 v[68:71], v[168:171], v[212:215], v[68:71]
	v_mfma_f32_16x16x32_bf16 v[64:67], v[176:179], v[208:211], v[64:67]
	v_mfma_f32_16x16x32_bf16 v[64:67], v[180:183], v[212:215], v[64:67]
	s_setprio 0
	s_barrier
	s_add_i32 s84, s68, s10
	s_add_u32 s98, s48, s38
	s_addc_u32 s99, s49, s39
	s_mov_b32 m0, s84
	ds_read_b128 v[184:187], v145 offset:16384
	ds_read_b128 v[188:191], v145 offset:17408
	ds_read_b128 v[192:195], v145 offset:18432
	ds_read_b128 v[196:199], v145 offset:19456
	ds_read_b128 v[200:203], v145 offset:20480
	ds_read_b128 v[204:207], v145 offset:21504
	ds_read_b128 v[208:211], v145 offset:22528
	ds_read_b128 v[212:215], v145 offset:23552
	global_load_lds_dwordx4 v132, s[48:49]
	s_add_i32 m0, s84, 0x2000
	s_add_u32 s84, s48, 0x80000
	s_addc_u32 s85, s49, 0
	s_add_i32 s86, s69, s10
	global_load_lds_dwordx4 v128, s[48:49]
	s_mov_b32 m0, s86
	s_nop 0
	global_load_lds_dwordx4 v132, s[84:85]
	s_add_i32 m0, s86, 0x2000
	s_nop 0
	global_load_lds_dwordx4 v128, s[84:85]
	s_add_u32 s100, s50, s38
	s_addc_u32 s101, s51, s39
	s_mov_b32 m0, s15
	s_nop 0
	global_load_lds_dwordx4 v134, s[50:51]
	s_mov_b32 m0, s22
	s_nop 0
	global_load_lds_dwordx4 v130, s[50:51]
	s_waitcnt vmcnt(8)
	s_waitcnt lgkmcnt(0)
	s_barrier
	s_setprio 1
	s_waitcnt lgkmcnt(0)
	v_mfma_f32_16x16x32_bf16 v[60:63], v[148:151], v[184:187], v[60:63]
	v_mfma_f32_16x16x32_bf16 v[60:63], v[152:155], v[188:191], v[60:63]
	v_mfma_f32_16x16x32_bf16 v[56:59], v[156:159], v[184:187], v[56:59]
	v_mfma_f32_16x16x32_bf16 v[56:59], v[160:163], v[188:191], v[56:59]
	v_mfma_f32_16x16x32_bf16 v[52:55], v[148:151], v[192:195], v[52:55]
	v_mfma_f32_16x16x32_bf16 v[52:55], v[152:155], v[196:199], v[52:55]
	v_mfma_f32_16x16x32_bf16 v[48:51], v[156:159], v[192:195], v[48:51]
	v_mfma_f32_16x16x32_bf16 v[48:51], v[160:163], v[196:199], v[48:51]
	v_mfma_f32_16x16x32_bf16 v[36:39], v[148:151], v[200:203], v[36:39]
	v_mfma_f32_16x16x32_bf16 v[36:39], v[152:155], v[204:207], v[36:39]
	v_mfma_f32_16x16x32_bf16 v[32:35], v[156:159], v[200:203], v[32:35]
	v_mfma_f32_16x16x32_bf16 v[32:35], v[160:163], v[204:207], v[32:35]
	v_mfma_f32_16x16x32_bf16 v[20:23], v[148:151], v[208:211], v[20:23]
	v_mfma_f32_16x16x32_bf16 v[20:23], v[152:155], v[212:215], v[20:23]
	v_mfma_f32_16x16x32_bf16 v[16:19], v[156:159], v[208:211], v[16:19]
	v_mfma_f32_16x16x32_bf16 v[16:19], v[160:163], v[212:215], v[16:19]
	s_setprio 0
	s_setprio 1
	v_mfma_f32_16x16x32_bf16 v[44:47], v[164:167], v[184:187], v[44:47]
	v_mfma_f32_16x16x32_bf16 v[44:47], v[168:171], v[188:191], v[44:47]
	v_mfma_f32_16x16x32_bf16 v[40:43], v[176:179], v[184:187], v[40:43]
	v_mfma_f32_16x16x32_bf16 v[40:43], v[180:183], v[188:191], v[40:43]
	v_mfma_f32_16x16x32_bf16 v[28:31], v[164:167], v[192:195], v[28:31]
	v_mfma_f32_16x16x32_bf16 v[28:31], v[168:171], v[196:199], v[28:31]
	v_mfma_f32_16x16x32_bf16 v[24:27], v[176:179], v[192:195], v[24:27]
	v_mfma_f32_16x16x32_bf16 v[24:27], v[180:183], v[196:199], v[24:27]
	v_mfma_f32_16x16x32_bf16 v[12:15], v[164:167], v[200:203], v[12:15]
	v_mfma_f32_16x16x32_bf16 v[12:15], v[168:171], v[204:207], v[12:15]
	v_mfma_f32_16x16x32_bf16 v[8:11], v[176:179], v[200:203], v[8:11]
	v_mfma_f32_16x16x32_bf16 v[8:11], v[180:183], v[204:207], v[8:11]
	v_mfma_f32_16x16x32_bf16 v[4:7], v[164:167], v[208:211], v[4:7]
	v_mfma_f32_16x16x32_bf16 v[4:7], v[168:171], v[212:215], v[4:7]
	v_mfma_f32_16x16x32_bf16 v[0:3], v[176:179], v[208:211], v[0:3]
	v_mfma_f32_16x16x32_bf16 v[0:3], v[180:183], v[212:215], v[0:3]
	s_setprio 0
	s_barrier
	s_add_i32 s84, 0, 0x18000
	v_add_u32_e32 v136, s84, v142
	s_add_i32 s85, 0, 0x1c000
	ds_read_b128 v[148:151], v136
	ds_read_b128 v[152:155], v136 offset:1024
	ds_read_b128 v[156:159], v136 offset:2048
	ds_read_b128 v[160:163], v136 offset:3072
	v_add_u32_e32 v136, s85, v142
	ds_read_b128 v[164:167], v136
	ds_read_b128 v[168:171], v136 offset:1024
	ds_read_b128 v[176:179], v136 offset:2048
	ds_read_b128 v[180:183], v136 offset:3072
	s_add_u32 s50, s50, 0x80000
	s_addc_u32 s51, s51, 0
	s_mov_b32 m0, s23
	ds_read_b128 v[184:187], v145 offset:32768
	ds_read_b128 v[188:191], v145 offset:33792
	ds_read_b128 v[192:195], v145 offset:34816
	ds_read_b128 v[196:199], v145 offset:35840
	ds_read_b128 v[200:203], v145 offset:36864
	ds_read_b128 v[204:207], v145 offset:37888
	ds_read_b128 v[208:211], v145 offset:38912
	ds_read_b128 v[212:215], v145 offset:39936
	global_load_lds_dwordx4 v134, s[50:51]
	s_mov_b32 m0, s33
	s_nop 0
	global_load_lds_dwordx4 v130, s[50:51]
	s_waitcnt vmcnt(8)
	s_waitcnt lgkmcnt(0)
	s_barrier
	s_setprio 1
	v_mfma_f32_16x16x32_bf16 v[124:127], v[148:151], v[184:187], v[124:127]
	v_mfma_f32_16x16x32_bf16 v[124:127], v[152:155], v[188:191], v[124:127]
	v_mfma_f32_16x16x32_bf16 v[120:123], v[156:159], v[184:187], v[120:123]
	v_mfma_f32_16x16x32_bf16 v[120:123], v[160:163], v[188:191], v[120:123]
	v_mfma_f32_16x16x32_bf16 v[116:119], v[148:151], v[192:195], v[116:119]
	v_mfma_f32_16x16x32_bf16 v[116:119], v[152:155], v[196:199], v[116:119]
	v_mfma_f32_16x16x32_bf16 v[112:115], v[156:159], v[192:195], v[112:115]
	v_mfma_f32_16x16x32_bf16 v[112:115], v[160:163], v[196:199], v[112:115]
	v_mfma_f32_16x16x32_bf16 v[100:103], v[148:151], v[200:203], v[100:103]
	v_mfma_f32_16x16x32_bf16 v[100:103], v[152:155], v[204:207], v[100:103]
	v_mfma_f32_16x16x32_bf16 v[96:99], v[156:159], v[200:203], v[96:99]
	v_mfma_f32_16x16x32_bf16 v[96:99], v[160:163], v[204:207], v[96:99]
	v_mfma_f32_16x16x32_bf16 v[84:87], v[148:151], v[208:211], v[84:87]
	v_mfma_f32_16x16x32_bf16 v[84:87], v[152:155], v[212:215], v[84:87]
	v_mfma_f32_16x16x32_bf16 v[80:83], v[156:159], v[208:211], v[80:83]
	v_mfma_f32_16x16x32_bf16 v[80:83], v[160:163], v[212:215], v[80:83]
	s_setprio 0
	s_setprio 1
	v_mfma_f32_16x16x32_bf16 v[108:111], v[164:167], v[184:187], v[108:111]
	v_mfma_f32_16x16x32_bf16 v[108:111], v[168:171], v[188:191], v[108:111]
	v_mfma_f32_16x16x32_bf16 v[104:107], v[176:179], v[184:187], v[104:107]
	v_mfma_f32_16x16x32_bf16 v[104:107], v[180:183], v[188:191], v[104:107]
	v_mfma_f32_16x16x32_bf16 v[92:95], v[164:167], v[192:195], v[92:95]
	v_mfma_f32_16x16x32_bf16 v[92:95], v[168:171], v[196:199], v[92:95]
	v_mfma_f32_16x16x32_bf16 v[88:91], v[176:179], v[192:195], v[88:91]
	v_mfma_f32_16x16x32_bf16 v[88:91], v[180:183], v[196:199], v[88:91]
	v_mfma_f32_16x16x32_bf16 v[76:79], v[164:167], v[200:203], v[76:79]
	v_mfma_f32_16x16x32_bf16 v[76:79], v[168:171], v[204:207], v[76:79]
	v_mfma_f32_16x16x32_bf16 v[72:75], v[176:179], v[200:203], v[72:75]
	v_mfma_f32_16x16x32_bf16 v[72:75], v[180:183], v[204:207], v[72:75]
	v_mfma_f32_16x16x32_bf16 v[68:71], v[164:167], v[208:211], v[68:71]
	v_mfma_f32_16x16x32_bf16 v[68:71], v[168:171], v[212:215], v[68:71]
	v_mfma_f32_16x16x32_bf16 v[64:67], v[176:179], v[208:211], v[64:67]
	v_mfma_f32_16x16x32_bf16 v[64:67], v[180:183], v[212:215], v[64:67]
	s_setprio 0
	s_barrier
	s_add_i32 s50, s84, s10
	s_mov_b32 m0, s50
	ds_read_b128 v[184:187], v145 offset:49152
	ds_read_b128 v[188:191], v145 offset:50176
	ds_read_b128 v[192:195], v145 offset:51200
	ds_read_b128 v[196:199], v145 offset:52224
	ds_read_b128 v[200:203], v145 offset:53248
	ds_read_b128 v[204:207], v145 offset:54272
	ds_read_b128 v[208:211], v145 offset:55296
	ds_read_b128 v[212:215], v145 offset:56320
	global_load_lds_dwordx4 v132, s[98:99]
	s_add_i32 m0, s50, 0x2000
	s_add_u32 s48, s48, 0x80080
	s_addc_u32 s49, s49, 0
	s_add_i32 s50, s85, s10
	global_load_lds_dwordx4 v128, s[98:99]
	s_mov_b32 m0, s50
	s_nop 0
	global_load_lds_dwordx4 v132, s[48:49]
	s_add_i32 m0, s50, 0x2000
	s_nop 0
	global_load_lds_dwordx4 v128, s[48:49]
	s_mov_b32 m0, s64
	s_nop 0
	global_load_lds_dwordx4 v134, s[100:101]
	s_mov_b32 m0, s65
	s_nop 0
	global_load_lds_dwordx4 v130, s[100:101]
	s_waitcnt vmcnt(8)
	s_waitcnt lgkmcnt(0)
	s_barrier
	s_setprio 1
	s_waitcnt lgkmcnt(0)
	v_mfma_f32_16x16x32_bf16 v[60:63], v[148:151], v[184:187], v[60:63]
	v_mfma_f32_16x16x32_bf16 v[60:63], v[152:155], v[188:191], v[60:63]
	v_mfma_f32_16x16x32_bf16 v[56:59], v[156:159], v[184:187], v[56:59]
	v_mfma_f32_16x16x32_bf16 v[56:59], v[160:163], v[188:191], v[56:59]
	v_mfma_f32_16x16x32_bf16 v[52:55], v[148:151], v[192:195], v[52:55]
	v_mfma_f32_16x16x32_bf16 v[52:55], v[152:155], v[196:199], v[52:55]
	v_mfma_f32_16x16x32_bf16 v[48:51], v[156:159], v[192:195], v[48:51]
	v_mfma_f32_16x16x32_bf16 v[48:51], v[160:163], v[196:199], v[48:51]
	v_mfma_f32_16x16x32_bf16 v[36:39], v[148:151], v[200:203], v[36:39]
	v_mfma_f32_16x16x32_bf16 v[36:39], v[152:155], v[204:207], v[36:39]
	v_mfma_f32_16x16x32_bf16 v[32:35], v[156:159], v[200:203], v[32:35]
	v_mfma_f32_16x16x32_bf16 v[32:35], v[160:163], v[204:207], v[32:35]
	v_mfma_f32_16x16x32_bf16 v[20:23], v[148:151], v[208:211], v[20:23]
	v_mfma_f32_16x16x32_bf16 v[20:23], v[152:155], v[212:215], v[20:23]
	v_mfma_f32_16x16x32_bf16 v[16:19], v[156:159], v[208:211], v[16:19]
	v_mfma_f32_16x16x32_bf16 v[16:19], v[160:163], v[212:215], v[16:19]
	s_setprio 0
	s_setprio 1
	v_mfma_f32_16x16x32_bf16 v[44:47], v[164:167], v[184:187], v[44:47]
	v_mfma_f32_16x16x32_bf16 v[44:47], v[168:171], v[188:191], v[44:47]
	v_mfma_f32_16x16x32_bf16 v[40:43], v[176:179], v[184:187], v[40:43]
	v_mfma_f32_16x16x32_bf16 v[40:43], v[180:183], v[188:191], v[40:43]
	v_mfma_f32_16x16x32_bf16 v[28:31], v[164:167], v[192:195], v[28:31]
	v_mfma_f32_16x16x32_bf16 v[28:31], v[168:171], v[196:199], v[28:31]
	v_mfma_f32_16x16x32_bf16 v[24:27], v[176:179], v[192:195], v[24:27]
	v_mfma_f32_16x16x32_bf16 v[24:27], v[180:183], v[196:199], v[24:27]
	v_mfma_f32_16x16x32_bf16 v[12:15], v[164:167], v[200:203], v[12:15]
	v_mfma_f32_16x16x32_bf16 v[12:15], v[168:171], v[204:207], v[12:15]
	v_mfma_f32_16x16x32_bf16 v[8:11], v[176:179], v[200:203], v[8:11]
	v_mfma_f32_16x16x32_bf16 v[8:11], v[180:183], v[204:207], v[8:11]
	v_mfma_f32_16x16x32_bf16 v[4:7], v[164:167], v[208:211], v[4:7]
	v_mfma_f32_16x16x32_bf16 v[4:7], v[168:171], v[212:215], v[4:7]
	v_mfma_f32_16x16x32_bf16 v[0:3], v[176:179], v[208:211], v[0:3]
	v_mfma_f32_16x16x32_bf16 v[0:3], v[180:183], v[212:215], v[0:3]
	s_setprio 0
	s_barrier
	s_add_i32 s83, s83, 2
	s_add_u32 s46, s46, 0x100
	s_addc_u32 s47, s47, 0
	s_add_u32 s81, s81, 0x100
	s_addc_u32 s82, s82, 0
	s_cmp_gt_u32 s83, 5
	s_cbranch_scc0 .LBB0_428
	s_and_b64 vcc, exec, s[40:41]
	s_cbranch_vccz .LBB0_431
	s_barrier

.LBB0_502:
	ds_read_b128 v[128:131], v192
	ds_read_b128 v[132:135], v192 offset:1024
	ds_read_b128 v[136:139], v192 offset:2048
	ds_read_b128 v[140:143], v192 offset:3072
	ds_read_b128 v[144:147], v193
	ds_read_b128 v[148:151], v193 offset:1024
	ds_read_b128 v[168:171], v193 offset:2048
	ds_read_b128 v[196:199], v193 offset:3072
	s_add_u32 s62, s60, 0xfff80080
	s_addc_u32 s63, s61, -1
	s_cmp_eq_u32 s76, 28
	s_cselect_b32 s65, s27, s63
	s_cselect_b32 s64, s45, s62
	s_cselect_b32 s63, s43, s75
	s_cselect_b32 s62, s51, s74
	s_add_i32 m0, s1, 0xc000
	ds_read_b128 v[200:203], v194
	ds_read_b128 v[204:207], v194 offset:1024
	ds_read_b128 v[208:211], v194 offset:2048
	ds_read_b128 v[212:215], v194 offset:3072
	ds_read_b128 v[216:219], v194 offset:4096
	ds_read_b128 v[220:223], v194 offset:5120
	ds_read_b128 v[224:227], v194 offset:6144
	ds_read_b128 v[228:231], v194 offset:7168
	global_load_lds_dwordx4 v160, s[60:61]
	s_add_i32 m0, s1, 0xe000
	s_nop 0
	global_load_lds_dwordx4 v162, s[60:61]
	s_waitcnt vmcnt(8)
	s_waitcnt lgkmcnt(0)
	s_barrier
	s_setprio 1
	s_waitcnt lgkmcnt(0)
	v_mfma_f32_16x16x32_bf16 v[124:127], v[128:131], v[200:203], v[124:127]
	v_mfma_f32_16x16x32_bf16 v[124:127], v[132:135], v[204:207], v[124:127]
	v_mfma_f32_16x16x32_bf16 v[120:123], v[136:139], v[200:203], v[120:123]
	v_mfma_f32_16x16x32_bf16 v[120:123], v[140:143], v[204:207], v[120:123]
	v_mfma_f32_16x16x32_bf16 v[108:111], v[128:131], v[208:211], v[108:111]
	v_mfma_f32_16x16x32_bf16 v[108:111], v[132:135], v[212:215], v[108:111]
	v_mfma_f32_16x16x32_bf16 v[104:107], v[136:139], v[208:211], v[104:107]
	v_mfma_f32_16x16x32_bf16 v[104:107], v[140:143], v[212:215], v[104:107]
	v_mfma_f32_16x16x32_bf16 v[92:95], v[128:131], v[216:219], v[92:95]
	v_mfma_f32_16x16x32_bf16 v[92:95], v[132:135], v[220:223], v[92:95]
	v_mfma_f32_16x16x32_bf16 v[88:91], v[136:139], v[216:219], v[88:91]
	v_mfma_f32_16x16x32_bf16 v[88:91], v[140:143], v[220:223], v[88:91]
	v_mfma_f32_16x16x32_bf16 v[76:79], v[128:131], v[224:227], v[76:79]
	v_mfma_f32_16x16x32_bf16 v[76:79], v[132:135], v[228:231], v[76:79]
	v_mfma_f32_16x16x32_bf16 v[72:75], v[136:139], v[224:227], v[72:75]
	v_mfma_f32_16x16x32_bf16 v[72:75], v[140:143], v[228:231], v[72:75]
	s_setprio 0
	s_setprio 1
	v_mfma_f32_16x16x32_bf16 v[116:119], v[144:147], v[200:203], v[116:119]
	v_mfma_f32_16x16x32_bf16 v[116:119], v[148:151], v[204:207], v[116:119]
	v_mfma_f32_16x16x32_bf16 v[112:115], v[168:171], v[200:203], v[112:115]
	v_mfma_f32_16x16x32_bf16 v[112:115], v[196:199], v[204:207], v[112:115]
	v_mfma_f32_16x16x32_bf16 v[100:103], v[144:147], v[208:211], v[100:103]
	v_mfma_f32_16x16x32_bf16 v[100:103], v[148:151], v[212:215], v[100:103]
	v_mfma_f32_16x16x32_bf16 v[96:99], v[168:171], v[208:211], v[96:99]
	v_mfma_f32_16x16x32_bf16 v[96:99], v[196:199], v[212:215], v[96:99]
	v_mfma_f32_16x16x32_bf16 v[84:87], v[144:147], v[216:219], v[84:87]
	v_mfma_f32_16x16x32_bf16 v[84:87], v[148:151], v[220:223], v[84:87]
	v_mfma_f32_16x16x32_bf16 v[80:83], v[168:171], v[216:219], v[80:83]
	v_mfma_f32_16x16x32_bf16 v[80:83], v[196:199], v[220:223], v[80:83]
	v_mfma_f32_16x16x32_bf16 v[68:71], v[144:147], v[224:227], v[68:71]
	v_mfma_f32_16x16x32_bf16 v[68:71], v[148:151], v[228:231], v[68:71]
	v_mfma_f32_16x16x32_bf16 v[64:67], v[168:171], v[224:227], v[64:67]
	v_mfma_f32_16x16x32_bf16 v[64:67], v[196:199], v[228:231], v[64:67]
	s_setprio 0
	s_barrier
	s_add_i32 s77, s69, s0
	s_add_u32 s98, s62, s38
	s_addc_u32 s99, s63, s39
	s_mov_b32 m0, s77
	ds_read_b128 v[200:203], v194 offset:16384
	ds_read_b128 v[204:207], v194 offset:17408
	ds_read_b128 v[208:211], v194 offset:18432
	ds_read_b128 v[212:215], v194 offset:19456
	ds_read_b128 v[216:219], v194 offset:20480
	ds_read_b128 v[220:223], v194 offset:21504
	ds_read_b128 v[224:227], v194 offset:22528
	ds_read_b128 v[228:231], v194 offset:23552
	global_load_lds_dwordx4 v154, s[62:63]
	s_add_i32 m0, s77, 0x2000
	s_add_u32 s78, s62, 0x80000
	s_addc_u32 s79, s63, 0
	s_add_i32 s77, s73, s0
	global_load_lds_dwordx4 v158, s[62:63]
	s_mov_b32 m0, s77
	s_nop 0
	global_load_lds_dwordx4 v154, s[78:79]
	s_add_i32 m0, s77, 0x2000
	s_nop 0
	global_load_lds_dwordx4 v158, s[78:79]
	s_add_u32 s100, s64, s38
	s_addc_u32 s101, s65, s39
	s_mov_b32 m0, s1
	s_nop 0
	global_load_lds_dwordx4 v152, s[64:65]
	s_mov_b32 m0, s10
	s_nop 0
	global_load_lds_dwordx4 v156, s[64:65]
	s_waitcnt vmcnt(8)
	s_waitcnt lgkmcnt(0)
	s_barrier
	s_setprio 1
	s_waitcnt lgkmcnt(0)
	v_mfma_f32_16x16x32_bf16 v[60:63], v[128:131], v[200:203], v[60:63]
	v_mfma_f32_16x16x32_bf16 v[60:63], v[132:135], v[204:207], v[60:63]
	v_mfma_f32_16x16x32_bf16 v[56:59], v[136:139], v[200:203], v[56:59]
	v_mfma_f32_16x16x32_bf16 v[56:59], v[140:143], v[204:207], v[56:59]
	v_mfma_f32_16x16x32_bf16 v[44:47], v[128:131], v[208:211], v[44:47]
	v_mfma_f32_16x16x32_bf16 v[44:47], v[132:135], v[212:215], v[44:47]
	v_mfma_f32_16x16x32_bf16 v[40:43], v[136:139], v[208:211], v[40:43]
	v_mfma_f32_16x16x32_bf16 v[40:43], v[140:143], v[212:215], v[40:43]
	v_mfma_f32_16x16x32_bf16 v[28:31], v[128:131], v[216:219], v[28:31]
	v_mfma_f32_16x16x32_bf16 v[28:31], v[132:135], v[220:223], v[28:31]
	v_mfma_f32_16x16x32_bf16 v[24:27], v[136:139], v[216:219], v[24:27]
	v_mfma_f32_16x16x32_bf16 v[24:27], v[140:143], v[220:223], v[24:27]
	v_mfma_f32_16x16x32_bf16 v[12:15], v[128:131], v[224:227], v[12:15]
	v_mfma_f32_16x16x32_bf16 v[12:15], v[132:135], v[228:231], v[12:15]
	v_mfma_f32_16x16x32_bf16 v[8:11], v[136:139], v[224:227], v[8:11]
	v_mfma_f32_16x16x32_bf16 v[8:11], v[140:143], v[228:231], v[8:11]
	s_setprio 0
	s_setprio 1
	v_mfma_f32_16x16x32_bf16 v[52:55], v[144:147], v[200:203], v[52:55]
	v_mfma_f32_16x16x32_bf16 v[52:55], v[148:151], v[204:207], v[52:55]
	v_mfma_f32_16x16x32_bf16 v[48:51], v[168:171], v[200:203], v[48:51]
	v_mfma_f32_16x16x32_bf16 v[48:51], v[196:199], v[204:207], v[48:51]
	v_mfma_f32_16x16x32_bf16 v[36:39], v[144:147], v[208:211], v[36:39]
	v_mfma_f32_16x16x32_bf16 v[36:39], v[148:151], v[212:215], v[36:39]
	v_mfma_f32_16x16x32_bf16 v[32:35], v[168:171], v[208:211], v[32:35]
	v_mfma_f32_16x16x32_bf16 v[32:35], v[196:199], v[212:215], v[32:35]
	v_mfma_f32_16x16x32_bf16 v[20:23], v[144:147], v[216:219], v[20:23]
	v_mfma_f32_16x16x32_bf16 v[20:23], v[148:151], v[220:223], v[20:23]
	v_mfma_f32_16x16x32_bf16 v[16:19], v[168:171], v[216:219], v[16:19]
	v_mfma_f32_16x16x32_bf16 v[16:19], v[196:199], v[220:223], v[16:19]
	v_mfma_f32_16x16x32_bf16 v[4:7], v[144:147], v[224:227], v[4:7]
	v_mfma_f32_16x16x32_bf16 v[4:7], v[148:151], v[228:231], v[4:7]
	v_mfma_f32_16x16x32_bf16 v[0:3], v[168:171], v[224:227], v[0:3]
	v_mfma_f32_16x16x32_bf16 v[0:3], v[196:199], v[228:231], v[0:3]
	s_setprio 0
	s_barrier
	s_add_i32 s77, 0, 0x18000
	s_add_i32 s78, 0, 0x1c000
	v_add_u32_e32 v140, s77, v177
	v_add_u32_e32 v196, s78, v177
	ds_read_b128 v[128:131], v140
	ds_read_b128 v[132:135], v140 offset:1024
	ds_read_b128 v[136:139], v140 offset:2048
	ds_read_b128 v[140:143], v140 offset:3072
	ds_read_b128 v[144:147], v196
	ds_read_b128 v[148:151], v196 offset:1024
	ds_read_b128 v[168:171], v196 offset:2048
	ds_read_b128 v[196:199], v196 offset:3072
	s_add_u32 s64, s64, 0x80000
	s_addc_u32 s65, s65, 0
	s_mov_b32 m0, s11
	ds_read_b128 v[200:203], v194 offset:32768
	ds_read_b128 v[204:207], v194 offset:33792
	ds_read_b128 v[208:211], v194 offset:34816
	ds_read_b128 v[212:215], v194 offset:35840
	ds_read_b128 v[216:219], v194 offset:36864
	ds_read_b128 v[220:223], v194 offset:37888
	ds_read_b128 v[224:227], v194 offset:38912
	ds_read_b128 v[228:231], v194 offset:39936
	global_load_lds_dwordx4 v152, s[64:65]
	s_mov_b32 m0, s14
	s_nop 0
	global_load_lds_dwordx4 v156, s[64:65]
	s_waitcnt vmcnt(8)
	s_waitcnt lgkmcnt(0)
	s_barrier
	s_setprio 1
	v_mfma_f32_16x16x32_bf16 v[124:127], v[128:131], v[200:203], v[124:127]
	v_mfma_f32_16x16x32_bf16 v[124:127], v[132:135], v[204:207], v[124:127]
	v_mfma_f32_16x16x32_bf16 v[120:123], v[136:139], v[200:203], v[120:123]
	v_mfma_f32_16x16x32_bf16 v[120:123], v[140:143], v[204:207], v[120:123]
	v_mfma_f32_16x16x32_bf16 v[108:111], v[128:131], v[208:211], v[108:111]
	v_mfma_f32_16x16x32_bf16 v[108:111], v[132:135], v[212:215], v[108:111]
	v_mfma_f32_16x16x32_bf16 v[104:107], v[136:139], v[208:211], v[104:107]
	v_mfma_f32_16x16x32_bf16 v[104:107], v[140:143], v[212:215], v[104:107]
	v_mfma_f32_16x16x32_bf16 v[92:95], v[128:131], v[216:219], v[92:95]
	v_mfma_f32_16x16x32_bf16 v[92:95], v[132:135], v[220:223], v[92:95]
	v_mfma_f32_16x16x32_bf16 v[88:91], v[136:139], v[216:219], v[88:91]
	v_mfma_f32_16x16x32_bf16 v[88:91], v[140:143], v[220:223], v[88:91]
	v_mfma_f32_16x16x32_bf16 v[76:79], v[128:131], v[224:227], v[76:79]
	v_mfma_f32_16x16x32_bf16 v[76:79], v[132:135], v[228:231], v[76:79]
	v_mfma_f32_16x16x32_bf16 v[72:75], v[136:139], v[224:227], v[72:75]
	v_mfma_f32_16x16x32_bf16 v[72:75], v[140:143], v[228:231], v[72:75]
	s_setprio 0
	s_setprio 1
	v_mfma_f32_16x16x32_bf16 v[116:119], v[144:147], v[200:203], v[116:119]
	v_mfma_f32_16x16x32_bf16 v[116:119], v[148:151], v[204:207], v[116:119]
	v_mfma_f32_16x16x32_bf16 v[112:115], v[168:171], v[200:203], v[112:115]
	v_mfma_f32_16x16x32_bf16 v[112:115], v[196:199], v[204:207], v[112:115]
	v_mfma_f32_16x16x32_bf16 v[100:103], v[144:147], v[208:211], v[100:103]
	v_mfma_f32_16x16x32_bf16 v[100:103], v[148:151], v[212:215], v[100:103]
	v_mfma_f32_16x16x32_bf16 v[96:99], v[168:171], v[208:211], v[96:99]
	v_mfma_f32_16x16x32_bf16 v[96:99], v[196:199], v[212:215], v[96:99]
	v_mfma_f32_16x16x32_bf16 v[84:87], v[144:147], v[216:219], v[84:87]
	v_mfma_f32_16x16x32_bf16 v[84:87], v[148:151], v[220:223], v[84:87]
	v_mfma_f32_16x16x32_bf16 v[80:83], v[168:171], v[216:219], v[80:83]
	v_mfma_f32_16x16x32_bf16 v[80:83], v[196:199], v[220:223], v[80:83]
	v_mfma_f32_16x16x32_bf16 v[68:71], v[144:147], v[224:227], v[68:71]
	v_mfma_f32_16x16x32_bf16 v[68:71], v[148:151], v[228:231], v[68:71]
	v_mfma_f32_16x16x32_bf16 v[64:67], v[168:171], v[224:227], v[64:67]
	v_mfma_f32_16x16x32_bf16 v[64:67], v[196:199], v[228:231], v[64:67]
	s_setprio 0
	s_barrier
	s_add_i32 s64, s77, s0
	s_mov_b32 m0, s64
	ds_read_b128 v[200:203], v194 offset:49152
	ds_read_b128 v[204:207], v194 offset:50176
	ds_read_b128 v[208:211], v194 offset:51200
	ds_read_b128 v[212:215], v194 offset:52224
	ds_read_b128 v[216:219], v194 offset:53248
	ds_read_b128 v[220:223], v194 offset:54272
	ds_read_b128 v[224:227], v194 offset:55296
	ds_read_b128 v[228:231], v194 offset:56320
	global_load_lds_dwordx4 v154, s[98:99]
	s_add_i32 m0, s64, 0x2000
	s_add_u32 s62, s62, 0x80080
	s_addc_u32 s63, s63, 0
	s_add_i32 s64, s78, s0
	global_load_lds_dwordx4 v158, s[98:99]
	s_mov_b32 m0, s64
	s_nop 0
	global_load_lds_dwordx4 v154, s[62:63]
	s_add_i32 m0, s64, 0x2000
	s_nop 0
	global_load_lds_dwordx4 v158, s[62:63]
	s_mov_b32 m0, s33
	s_nop 0
	global_load_lds_dwordx4 v152, s[100:101]
	s_mov_b32 m0, s68
	s_nop 0
	global_load_lds_dwordx4 v156, s[100:101]
	s_waitcnt vmcnt(8)
	s_waitcnt lgkmcnt(0)
	s_barrier
	s_setprio 1
	s_waitcnt lgkmcnt(0)
	v_mfma_f32_16x16x32_bf16 v[60:63], v[128:131], v[200:203], v[60:63]
	v_mfma_f32_16x16x32_bf16 v[60:63], v[132:135], v[204:207], v[60:63]
	v_mfma_f32_16x16x32_bf16 v[56:59], v[136:139], v[200:203], v[56:59]
	v_mfma_f32_16x16x32_bf16 v[56:59], v[140:143], v[204:207], v[56:59]
	v_mfma_f32_16x16x32_bf16 v[44:47], v[128:131], v[208:211], v[44:47]
	v_mfma_f32_16x16x32_bf16 v[44:47], v[132:135], v[212:215], v[44:47]
	v_mfma_f32_16x16x32_bf16 v[40:43], v[136:139], v[208:211], v[40:43]
	v_mfma_f32_16x16x32_bf16 v[40:43], v[140:143], v[212:215], v[40:43]
	v_mfma_f32_16x16x32_bf16 v[28:31], v[128:131], v[216:219], v[28:31]
	v_mfma_f32_16x16x32_bf16 v[28:31], v[132:135], v[220:223], v[28:31]
	v_mfma_f32_16x16x32_bf16 v[24:27], v[136:139], v[216:219], v[24:27]
	v_mfma_f32_16x16x32_bf16 v[24:27], v[140:143], v[220:223], v[24:27]
	v_mfma_f32_16x16x32_bf16 v[12:15], v[128:131], v[224:227], v[12:15]
	v_mfma_f32_16x16x32_bf16 v[12:15], v[132:135], v[228:231], v[12:15]
	v_mfma_f32_16x16x32_bf16 v[8:11], v[136:139], v[224:227], v[8:11]
	v_mfma_f32_16x16x32_bf16 v[8:11], v[140:143], v[228:231], v[8:11]
	s_setprio 0
	s_setprio 1
	v_mfma_f32_16x16x32_bf16 v[52:55], v[144:147], v[200:203], v[52:55]
	v_mfma_f32_16x16x32_bf16 v[52:55], v[148:151], v[204:207], v[52:55]
	v_mfma_f32_16x16x32_bf16 v[48:51], v[168:171], v[200:203], v[48:51]
	v_mfma_f32_16x16x32_bf16 v[48:51], v[196:199], v[204:207], v[48:51]
	v_mfma_f32_16x16x32_bf16 v[36:39], v[144:147], v[208:211], v[36:39]
	v_mfma_f32_16x16x32_bf16 v[36:39], v[148:151], v[212:215], v[36:39]
	v_mfma_f32_16x16x32_bf16 v[32:35], v[168:171], v[208:211], v[32:35]
	v_mfma_f32_16x16x32_bf16 v[32:35], v[196:199], v[212:215], v[32:35]
	v_mfma_f32_16x16x32_bf16 v[20:23], v[144:147], v[216:219], v[20:23]
	v_mfma_f32_16x16x32_bf16 v[20:23], v[148:151], v[220:223], v[20:23]
	v_mfma_f32_16x16x32_bf16 v[16:19], v[168:171], v[216:219], v[16:19]
	v_mfma_f32_16x16x32_bf16 v[16:19], v[196:199], v[220:223], v[16:19]
	v_mfma_f32_16x16x32_bf16 v[4:7], v[144:147], v[224:227], v[4:7]
	v_mfma_f32_16x16x32_bf16 v[4:7], v[148:151], v[228:231], v[4:7]
	v_mfma_f32_16x16x32_bf16 v[0:3], v[168:171], v[224:227], v[0:3]
	v_mfma_f32_16x16x32_bf16 v[0:3], v[196:199], v[228:231], v[0:3]
	s_setprio 0
	s_barrier
	s_add_i32 s76, s76, 2
	s_add_u32 s60, s60, 0x100
	s_addc_u32 s61, s61, 0
	s_add_u32 s74, s74, 0x100
	s_addc_u32 s75, s75, 0
	s_cmp_gt_u32 s76, 29
	s_cbranch_scc0 .LBB0_502
	s_and_b64 vcc, exec, s[40:41]
	s_cbranch_vccz .LBB0_505
	s_barrier

.LBB0_596:
	ds_read_b128 v[142:145], v159
	ds_read_b128 v[146:149], v159 offset:1024
	ds_read_b128 v[150:153], v159 offset:2048
	ds_read_b128 v[154:157], v159 offset:3072
	ds_read_b128 v[166:169], v160
	ds_read_b128 v[170:173], v160 offset:1024
	ds_read_b128 v[176:179], v160 offset:2048
	ds_read_b128 v[180:183], v160 offset:3072
	s_add_u32 s50, s48, 0xfff80080
	s_addc_u32 s51, s49, -1
	s_cmp_eq_u32 s76, 28
	s_cselect_b32 s61, s39, s51
	s_cselect_b32 s60, s47, s50
	s_cselect_b32 s51, s72, s75
	s_cselect_b32 s50, s73, s74
	s_add_i32 m0, s1, 0xc000
	ds_read_b128 v[184:187], v161
	ds_read_b128 v[188:191], v161 offset:1024
	ds_read_b128 v[192:195], v161 offset:2048
	ds_read_b128 v[196:199], v161 offset:3072
	ds_read_b128 v[200:203], v161 offset:4096
	ds_read_b128 v[204:207], v161 offset:5120
	ds_read_b128 v[208:211], v161 offset:6144
	ds_read_b128 v[212:215], v161 offset:7168
	global_load_lds_dwordx4 v138, s[48:49]
	s_add_i32 m0, s1, 0xe000
	s_nop 0
	global_load_lds_dwordx4 v140, s[48:49]
	s_waitcnt vmcnt(8)
	s_waitcnt lgkmcnt(0)
	s_barrier
	s_setprio 1
	s_waitcnt lgkmcnt(0)
	v_mfma_f32_16x16x32_bf16 v[124:127], v[142:145], v[184:187], v[124:127]
	v_mfma_f32_16x16x32_bf16 v[124:127], v[146:149], v[188:191], v[124:127]
	v_mfma_f32_16x16x32_bf16 v[120:123], v[150:153], v[184:187], v[120:123]
	v_mfma_f32_16x16x32_bf16 v[120:123], v[154:157], v[188:191], v[120:123]
	v_mfma_f32_16x16x32_bf16 v[108:111], v[142:145], v[192:195], v[108:111]
	v_mfma_f32_16x16x32_bf16 v[108:111], v[146:149], v[196:199], v[108:111]
	v_mfma_f32_16x16x32_bf16 v[104:107], v[150:153], v[192:195], v[104:107]
	v_mfma_f32_16x16x32_bf16 v[104:107], v[154:157], v[196:199], v[104:107]
	v_mfma_f32_16x16x32_bf16 v[92:95], v[142:145], v[200:203], v[92:95]
	v_mfma_f32_16x16x32_bf16 v[92:95], v[146:149], v[204:207], v[92:95]
	v_mfma_f32_16x16x32_bf16 v[88:91], v[150:153], v[200:203], v[88:91]
	v_mfma_f32_16x16x32_bf16 v[88:91], v[154:157], v[204:207], v[88:91]
	v_mfma_f32_16x16x32_bf16 v[76:79], v[142:145], v[208:211], v[76:79]
	v_mfma_f32_16x16x32_bf16 v[76:79], v[146:149], v[212:215], v[76:79]
	v_mfma_f32_16x16x32_bf16 v[72:75], v[150:153], v[208:211], v[72:75]
	v_mfma_f32_16x16x32_bf16 v[72:75], v[154:157], v[212:215], v[72:75]
	s_setprio 0
	s_setprio 1
	v_mfma_f32_16x16x32_bf16 v[116:119], v[166:169], v[184:187], v[116:119]
	v_mfma_f32_16x16x32_bf16 v[116:119], v[170:173], v[188:191], v[116:119]
	v_mfma_f32_16x16x32_bf16 v[112:115], v[176:179], v[184:187], v[112:115]
	v_mfma_f32_16x16x32_bf16 v[112:115], v[180:183], v[188:191], v[112:115]
	v_mfma_f32_16x16x32_bf16 v[100:103], v[166:169], v[192:195], v[100:103]
	v_mfma_f32_16x16x32_bf16 v[100:103], v[170:173], v[196:199], v[100:103]
	v_mfma_f32_16x16x32_bf16 v[96:99], v[176:179], v[192:195], v[96:99]
	v_mfma_f32_16x16x32_bf16 v[96:99], v[180:183], v[196:199], v[96:99]
	v_mfma_f32_16x16x32_bf16 v[84:87], v[166:169], v[200:203], v[84:87]
	v_mfma_f32_16x16x32_bf16 v[84:87], v[170:173], v[204:207], v[84:87]
	v_mfma_f32_16x16x32_bf16 v[80:83], v[176:179], v[200:203], v[80:83]
	v_mfma_f32_16x16x32_bf16 v[80:83], v[180:183], v[204:207], v[80:83]
	v_mfma_f32_16x16x32_bf16 v[68:71], v[166:169], v[208:211], v[68:71]
	v_mfma_f32_16x16x32_bf16 v[68:71], v[170:173], v[212:215], v[68:71]
	v_mfma_f32_16x16x32_bf16 v[64:67], v[176:179], v[208:211], v[64:67]
	v_mfma_f32_16x16x32_bf16 v[64:67], v[180:183], v[212:215], v[64:67]
	s_setprio 0
	s_barrier
	s_add_i32 s77, s64, s0
	s_add_u32 s98, s50, s34
	s_addc_u32 s99, s51, s35
	s_mov_b32 m0, s77
	ds_read_b128 v[184:187], v161 offset:16384
	ds_read_b128 v[188:191], v161 offset:17408
	ds_read_b128 v[192:195], v161 offset:18432
	ds_read_b128 v[196:199], v161 offset:19456
	ds_read_b128 v[200:203], v161 offset:20480
	ds_read_b128 v[204:207], v161 offset:21504
	ds_read_b128 v[208:211], v161 offset:22528
	ds_read_b128 v[212:215], v161 offset:23552
	global_load_lds_dwordx4 v130, s[50:51]
	s_add_i32 m0, s77, 0x2000
	s_add_u32 s78, s50, 0x80000
	s_addc_u32 s79, s51, 0
	s_add_i32 s77, s65, s0
	global_load_lds_dwordx4 v134, s[50:51]
	s_mov_b32 m0, s77
	s_nop 0
	global_load_lds_dwordx4 v130, s[78:79]
	s_add_i32 m0, s77, 0x2000
	s_nop 0
	global_load_lds_dwordx4 v134, s[78:79]
	s_add_u32 s100, s60, s34
	s_addc_u32 s101, s61, s35
	s_mov_b32 m0, s1
	s_nop 0
	global_load_lds_dwordx4 v128, s[60:61]
	s_mov_b32 m0, s10
	s_nop 0
	global_load_lds_dwordx4 v132, s[60:61]
	s_waitcnt vmcnt(8)
	s_waitcnt lgkmcnt(0)
	s_barrier
	s_setprio 1
	s_waitcnt lgkmcnt(0)
	v_mfma_f32_16x16x32_bf16 v[60:63], v[142:145], v[184:187], v[60:63]
	v_mfma_f32_16x16x32_bf16 v[60:63], v[146:149], v[188:191], v[60:63]
	v_mfma_f32_16x16x32_bf16 v[56:59], v[150:153], v[184:187], v[56:59]
	v_mfma_f32_16x16x32_bf16 v[56:59], v[154:157], v[188:191], v[56:59]
	v_mfma_f32_16x16x32_bf16 v[44:47], v[142:145], v[192:195], v[44:47]
	v_mfma_f32_16x16x32_bf16 v[44:47], v[146:149], v[196:199], v[44:47]
	v_mfma_f32_16x16x32_bf16 v[40:43], v[150:153], v[192:195], v[40:43]
	v_mfma_f32_16x16x32_bf16 v[40:43], v[154:157], v[196:199], v[40:43]
	v_mfma_f32_16x16x32_bf16 v[28:31], v[142:145], v[200:203], v[28:31]
	v_mfma_f32_16x16x32_bf16 v[28:31], v[146:149], v[204:207], v[28:31]
	v_mfma_f32_16x16x32_bf16 v[24:27], v[150:153], v[200:203], v[24:27]
	v_mfma_f32_16x16x32_bf16 v[24:27], v[154:157], v[204:207], v[24:27]
	v_mfma_f32_16x16x32_bf16 v[12:15], v[142:145], v[208:211], v[12:15]
	v_mfma_f32_16x16x32_bf16 v[12:15], v[146:149], v[212:215], v[12:15]
	v_mfma_f32_16x16x32_bf16 v[8:11], v[150:153], v[208:211], v[8:11]
	v_mfma_f32_16x16x32_bf16 v[8:11], v[154:157], v[212:215], v[8:11]
	s_setprio 0
	s_setprio 1
	v_mfma_f32_16x16x32_bf16 v[52:55], v[166:169], v[184:187], v[52:55]
	v_mfma_f32_16x16x32_bf16 v[52:55], v[170:173], v[188:191], v[52:55]
	v_mfma_f32_16x16x32_bf16 v[48:51], v[176:179], v[184:187], v[48:51]
	v_mfma_f32_16x16x32_bf16 v[48:51], v[180:183], v[188:191], v[48:51]
	v_mfma_f32_16x16x32_bf16 v[36:39], v[166:169], v[192:195], v[36:39]
	v_mfma_f32_16x16x32_bf16 v[36:39], v[170:173], v[196:199], v[36:39]
	v_mfma_f32_16x16x32_bf16 v[32:35], v[176:179], v[192:195], v[32:35]
	v_mfma_f32_16x16x32_bf16 v[32:35], v[180:183], v[196:199], v[32:35]
	v_mfma_f32_16x16x32_bf16 v[20:23], v[166:169], v[200:203], v[20:23]
	v_mfma_f32_16x16x32_bf16 v[20:23], v[170:173], v[204:207], v[20:23]
	v_mfma_f32_16x16x32_bf16 v[16:19], v[176:179], v[200:203], v[16:19]
	v_mfma_f32_16x16x32_bf16 v[16:19], v[180:183], v[204:207], v[16:19]
	v_mfma_f32_16x16x32_bf16 v[4:7], v[166:169], v[208:211], v[4:7]
	v_mfma_f32_16x16x32_bf16 v[4:7], v[170:173], v[212:215], v[4:7]
	v_mfma_f32_16x16x32_bf16 v[0:3], v[176:179], v[208:211], v[0:3]
	v_mfma_f32_16x16x32_bf16 v[0:3], v[180:183], v[212:215], v[0:3]
	s_setprio 0
	s_barrier
	s_add_i32 s77, 0, 0x18000
	v_add_u32_e32 v136, s77, v158
	s_add_i32 s78, 0, 0x1c000
	ds_read_b128 v[142:145], v136
	ds_read_b128 v[146:149], v136 offset:1024
	ds_read_b128 v[150:153], v136 offset:2048
	ds_read_b128 v[154:157], v136 offset:3072
	v_add_u32_e32 v136, s78, v158
	ds_read_b128 v[166:169], v136
	ds_read_b128 v[170:173], v136 offset:1024
	ds_read_b128 v[176:179], v136 offset:2048
	ds_read_b128 v[180:183], v136 offset:3072
	s_add_u32 s60, s60, 0x80000
	s_addc_u32 s61, s61, 0
	s_mov_b32 m0, s11
	ds_read_b128 v[184:187], v161 offset:32768
	ds_read_b128 v[188:191], v161 offset:33792
	ds_read_b128 v[192:195], v161 offset:34816
	ds_read_b128 v[196:199], v161 offset:35840
	ds_read_b128 v[200:203], v161 offset:36864
	ds_read_b128 v[204:207], v161 offset:37888
	ds_read_b128 v[208:211], v161 offset:38912
	ds_read_b128 v[212:215], v161 offset:39936
	global_load_lds_dwordx4 v128, s[60:61]
	s_mov_b32 m0, s14
	s_nop 0
	global_load_lds_dwordx4 v132, s[60:61]
	s_waitcnt vmcnt(8)
	s_waitcnt lgkmcnt(0)
	s_barrier
	s_setprio 1
	v_mfma_f32_16x16x32_bf16 v[124:127], v[142:145], v[184:187], v[124:127]
	v_mfma_f32_16x16x32_bf16 v[124:127], v[146:149], v[188:191], v[124:127]
	v_mfma_f32_16x16x32_bf16 v[120:123], v[150:153], v[184:187], v[120:123]
	v_mfma_f32_16x16x32_bf16 v[120:123], v[154:157], v[188:191], v[120:123]
	v_mfma_f32_16x16x32_bf16 v[108:111], v[142:145], v[192:195], v[108:111]
	v_mfma_f32_16x16x32_bf16 v[108:111], v[146:149], v[196:199], v[108:111]
	v_mfma_f32_16x16x32_bf16 v[104:107], v[150:153], v[192:195], v[104:107]
	v_mfma_f32_16x16x32_bf16 v[104:107], v[154:157], v[196:199], v[104:107]
	v_mfma_f32_16x16x32_bf16 v[92:95], v[142:145], v[200:203], v[92:95]
	v_mfma_f32_16x16x32_bf16 v[92:95], v[146:149], v[204:207], v[92:95]
	v_mfma_f32_16x16x32_bf16 v[88:91], v[150:153], v[200:203], v[88:91]
	v_mfma_f32_16x16x32_bf16 v[88:91], v[154:157], v[204:207], v[88:91]
	v_mfma_f32_16x16x32_bf16 v[76:79], v[142:145], v[208:211], v[76:79]
	v_mfma_f32_16x16x32_bf16 v[76:79], v[146:149], v[212:215], v[76:79]
	v_mfma_f32_16x16x32_bf16 v[72:75], v[150:153], v[208:211], v[72:75]
	v_mfma_f32_16x16x32_bf16 v[72:75], v[154:157], v[212:215], v[72:75]
	s_setprio 0
	s_setprio 1
	v_mfma_f32_16x16x32_bf16 v[116:119], v[166:169], v[184:187], v[116:119]
	v_mfma_f32_16x16x32_bf16 v[116:119], v[170:173], v[188:191], v[116:119]
	v_mfma_f32_16x16x32_bf16 v[112:115], v[176:179], v[184:187], v[112:115]
	v_mfma_f32_16x16x32_bf16 v[112:115], v[180:183], v[188:191], v[112:115]
	v_mfma_f32_16x16x32_bf16 v[100:103], v[166:169], v[192:195], v[100:103]
	v_mfma_f32_16x16x32_bf16 v[100:103], v[170:173], v[196:199], v[100:103]
	v_mfma_f32_16x16x32_bf16 v[96:99], v[176:179], v[192:195], v[96:99]
	v_mfma_f32_16x16x32_bf16 v[96:99], v[180:183], v[196:199], v[96:99]
	v_mfma_f32_16x16x32_bf16 v[84:87], v[166:169], v[200:203], v[84:87]
	v_mfma_f32_16x16x32_bf16 v[84:87], v[170:173], v[204:207], v[84:87]
	v_mfma_f32_16x16x32_bf16 v[80:83], v[176:179], v[200:203], v[80:83]
	v_mfma_f32_16x16x32_bf16 v[80:83], v[180:183], v[204:207], v[80:83]
	v_mfma_f32_16x16x32_bf16 v[68:71], v[166:169], v[208:211], v[68:71]
	v_mfma_f32_16x16x32_bf16 v[68:71], v[170:173], v[212:215], v[68:71]
	v_mfma_f32_16x16x32_bf16 v[64:67], v[176:179], v[208:211], v[64:67]
	v_mfma_f32_16x16x32_bf16 v[64:67], v[180:183], v[212:215], v[64:67]
	s_setprio 0
	s_barrier
	s_add_i32 s60, s77, s0
	s_mov_b32 m0, s60
	ds_read_b128 v[184:187], v161 offset:49152
	ds_read_b128 v[188:191], v161 offset:50176
	ds_read_b128 v[192:195], v161 offset:51200
	ds_read_b128 v[196:199], v161 offset:52224
	ds_read_b128 v[200:203], v161 offset:53248
	ds_read_b128 v[204:207], v161 offset:54272
	ds_read_b128 v[208:211], v161 offset:55296
	ds_read_b128 v[212:215], v161 offset:56320
	global_load_lds_dwordx4 v130, s[98:99]
	s_add_i32 m0, s60, 0x2000
	s_add_u32 s50, s50, 0x80080
	s_addc_u32 s51, s51, 0
	s_add_i32 s60, s78, s0
	global_load_lds_dwordx4 v134, s[98:99]
	s_mov_b32 m0, s60
	s_nop 0
	global_load_lds_dwordx4 v130, s[50:51]
	s_add_i32 m0, s60, 0x2000
	s_nop 0
	global_load_lds_dwordx4 v134, s[50:51]
	s_mov_b32 m0, s15
	s_nop 0
	global_load_lds_dwordx4 v128, s[100:101]
	s_mov_b32 m0, s33
	s_nop 0
	global_load_lds_dwordx4 v132, s[100:101]
	s_waitcnt vmcnt(8)
	s_waitcnt lgkmcnt(0)
	s_barrier
	s_setprio 1
	s_waitcnt lgkmcnt(0)
	v_mfma_f32_16x16x32_bf16 v[60:63], v[142:145], v[184:187], v[60:63]
	v_mfma_f32_16x16x32_bf16 v[60:63], v[146:149], v[188:191], v[60:63]
	v_mfma_f32_16x16x32_bf16 v[56:59], v[150:153], v[184:187], v[56:59]
	v_mfma_f32_16x16x32_bf16 v[56:59], v[154:157], v[188:191], v[56:59]
	v_mfma_f32_16x16x32_bf16 v[44:47], v[142:145], v[192:195], v[44:47]
	v_mfma_f32_16x16x32_bf16 v[44:47], v[146:149], v[196:199], v[44:47]
	v_mfma_f32_16x16x32_bf16 v[40:43], v[150:153], v[192:195], v[40:43]
	v_mfma_f32_16x16x32_bf16 v[40:43], v[154:157], v[196:199], v[40:43]
	v_mfma_f32_16x16x32_bf16 v[28:31], v[142:145], v[200:203], v[28:31]
	v_mfma_f32_16x16x32_bf16 v[28:31], v[146:149], v[204:207], v[28:31]
	v_mfma_f32_16x16x32_bf16 v[24:27], v[150:153], v[200:203], v[24:27]
	v_mfma_f32_16x16x32_bf16 v[24:27], v[154:157], v[204:207], v[24:27]
	v_mfma_f32_16x16x32_bf16 v[12:15], v[142:145], v[208:211], v[12:15]
	v_mfma_f32_16x16x32_bf16 v[12:15], v[146:149], v[212:215], v[12:15]
	v_mfma_f32_16x16x32_bf16 v[8:11], v[150:153], v[208:211], v[8:11]
	v_mfma_f32_16x16x32_bf16 v[8:11], v[154:157], v[212:215], v[8:11]
	s_setprio 0
	s_setprio 1
	v_mfma_f32_16x16x32_bf16 v[52:55], v[166:169], v[184:187], v[52:55]
	v_mfma_f32_16x16x32_bf16 v[52:55], v[170:173], v[188:191], v[52:55]
	v_mfma_f32_16x16x32_bf16 v[48:51], v[176:179], v[184:187], v[48:51]
	v_mfma_f32_16x16x32_bf16 v[48:51], v[180:183], v[188:191], v[48:51]
	v_mfma_f32_16x16x32_bf16 v[36:39], v[166:169], v[192:195], v[36:39]
	v_mfma_f32_16x16x32_bf16 v[36:39], v[170:173], v[196:199], v[36:39]
	v_mfma_f32_16x16x32_bf16 v[32:35], v[176:179], v[192:195], v[32:35]
	v_mfma_f32_16x16x32_bf16 v[32:35], v[180:183], v[196:199], v[32:35]
	v_mfma_f32_16x16x32_bf16 v[20:23], v[166:169], v[200:203], v[20:23]
	v_mfma_f32_16x16x32_bf16 v[20:23], v[170:173], v[204:207], v[20:23]
	v_mfma_f32_16x16x32_bf16 v[16:19], v[176:179], v[200:203], v[16:19]
	v_mfma_f32_16x16x32_bf16 v[16:19], v[180:183], v[204:207], v[16:19]
	v_mfma_f32_16x16x32_bf16 v[4:7], v[166:169], v[208:211], v[4:7]
	v_mfma_f32_16x16x32_bf16 v[4:7], v[170:173], v[212:215], v[4:7]
	v_mfma_f32_16x16x32_bf16 v[0:3], v[176:179], v[208:211], v[0:3]
	v_mfma_f32_16x16x32_bf16 v[0:3], v[180:183], v[212:215], v[0:3]
	s_setprio 0
	s_barrier
	s_add_i32 s76, s76, 2
	s_add_u32 s48, s48, 0x100
	s_addc_u32 s49, s49, 0
	s_add_u32 s74, s74, 0x100
	s_addc_u32 s75, s75, 0
	s_cmp_gt_u32 s76, 29
	s_cbranch_scc0 .LBB0_596
	s_and_b64 vcc, exec, s[36:37]
	s_cbranch_vccz .LBB0_599
	s_barrier

.LBB0_707:
	ds_read_b128 v[128:131], v188
	ds_read_b128 v[132:135], v188 offset:1024
	ds_read_b128 v[136:139], v188 offset:2048
	ds_read_b128 v[140:143], v188 offset:3072
	ds_read_b128 v[144:147], v189
	ds_read_b128 v[148:151], v189 offset:1024
	ds_read_b128 v[164:167], v189 offset:2048
	ds_read_b128 v[192:195], v189 offset:3072
	s_add_u32 s60, s50, 0xfffc0080
	s_addc_u32 s61, s51, -1
	s_cmp_eq_u32 s73, 12
	s_cselect_b32 s63, s27, s61
	s_cselect_b32 s62, s41, s60
	s_cselect_b32 s61, s49, s72
	s_cselect_b32 s60, s70, s71
	s_add_i32 m0, s1, 0xc000
	ds_read_b128 v[196:199], v190
	ds_read_b128 v[200:203], v190 offset:1024
	ds_read_b128 v[204:207], v190 offset:2048
	ds_read_b128 v[208:211], v190 offset:3072
	ds_read_b128 v[212:215], v190 offset:4096
	ds_read_b128 v[216:219], v190 offset:5120
	ds_read_b128 v[220:223], v190 offset:6144
	ds_read_b128 v[224:227], v190 offset:7168
	global_load_lds_dwordx4 v160, s[50:51]
	s_add_i32 m0, s1, 0xe000
	s_nop 0
	global_load_lds_dwordx4 v162, s[50:51]
	s_waitcnt vmcnt(8)
	s_waitcnt lgkmcnt(0)
	s_barrier
	s_setprio 1
	s_waitcnt lgkmcnt(0)
	v_mfma_f32_16x16x32_bf16 v[124:127], v[128:131], v[196:199], v[124:127]
	v_mfma_f32_16x16x32_bf16 v[124:127], v[132:135], v[200:203], v[124:127]
	v_mfma_f32_16x16x32_bf16 v[120:123], v[136:139], v[196:199], v[120:123]
	v_mfma_f32_16x16x32_bf16 v[120:123], v[140:143], v[200:203], v[120:123]
	v_mfma_f32_16x16x32_bf16 v[108:111], v[128:131], v[204:207], v[108:111]
	v_mfma_f32_16x16x32_bf16 v[108:111], v[132:135], v[208:211], v[108:111]
	v_mfma_f32_16x16x32_bf16 v[104:107], v[136:139], v[204:207], v[104:107]
	v_mfma_f32_16x16x32_bf16 v[104:107], v[140:143], v[208:211], v[104:107]
	v_mfma_f32_16x16x32_bf16 v[92:95], v[128:131], v[212:215], v[92:95]
	v_mfma_f32_16x16x32_bf16 v[92:95], v[132:135], v[216:219], v[92:95]
	v_mfma_f32_16x16x32_bf16 v[88:91], v[136:139], v[212:215], v[88:91]
	v_mfma_f32_16x16x32_bf16 v[88:91], v[140:143], v[216:219], v[88:91]
	v_mfma_f32_16x16x32_bf16 v[76:79], v[128:131], v[220:223], v[76:79]
	v_mfma_f32_16x16x32_bf16 v[76:79], v[132:135], v[224:227], v[76:79]
	v_mfma_f32_16x16x32_bf16 v[72:75], v[136:139], v[220:223], v[72:75]
	v_mfma_f32_16x16x32_bf16 v[72:75], v[140:143], v[224:227], v[72:75]
	s_setprio 0
	s_setprio 1
	v_mfma_f32_16x16x32_bf16 v[116:119], v[144:147], v[196:199], v[116:119]
	v_mfma_f32_16x16x32_bf16 v[116:119], v[148:151], v[200:203], v[116:119]
	v_mfma_f32_16x16x32_bf16 v[112:115], v[164:167], v[196:199], v[112:115]
	v_mfma_f32_16x16x32_bf16 v[112:115], v[192:195], v[200:203], v[112:115]
	v_mfma_f32_16x16x32_bf16 v[100:103], v[144:147], v[204:207], v[100:103]
	v_mfma_f32_16x16x32_bf16 v[100:103], v[148:151], v[208:211], v[100:103]
	v_mfma_f32_16x16x32_bf16 v[96:99], v[164:167], v[204:207], v[96:99]
	v_mfma_f32_16x16x32_bf16 v[96:99], v[192:195], v[208:211], v[96:99]
	v_mfma_f32_16x16x32_bf16 v[84:87], v[144:147], v[212:215], v[84:87]
	v_mfma_f32_16x16x32_bf16 v[84:87], v[148:151], v[216:219], v[84:87]
	v_mfma_f32_16x16x32_bf16 v[80:83], v[164:167], v[212:215], v[80:83]
	v_mfma_f32_16x16x32_bf16 v[80:83], v[192:195], v[216:219], v[80:83]
	v_mfma_f32_16x16x32_bf16 v[68:71], v[144:147], v[220:223], v[68:71]
	v_mfma_f32_16x16x32_bf16 v[68:71], v[148:151], v[224:227], v[68:71]
	v_mfma_f32_16x16x32_bf16 v[64:67], v[164:167], v[220:223], v[64:67]
	v_mfma_f32_16x16x32_bf16 v[64:67], v[192:195], v[224:227], v[64:67]
	s_setprio 0
	s_barrier
	s_add_i32 s74, s66, s0
	s_add_u32 s98, s60, s36
	s_addc_u32 s99, s61, s37
	s_mov_b32 m0, s74
	ds_read_b128 v[196:199], v190 offset:16384
	ds_read_b128 v[200:203], v190 offset:17408
	ds_read_b128 v[204:207], v190 offset:18432
	ds_read_b128 v[208:211], v190 offset:19456
	ds_read_b128 v[212:215], v190 offset:20480
	ds_read_b128 v[216:219], v190 offset:21504
	ds_read_b128 v[220:223], v190 offset:22528
	ds_read_b128 v[224:227], v190 offset:23552
	global_load_lds_dwordx4 v154, s[60:61]
	s_add_i32 m0, s74, 0x2000
	s_add_u32 s74, s60, 0x40000
	s_addc_u32 s75, s61, 0
	s_add_i32 s76, s67, s0
	global_load_lds_dwordx4 v158, s[60:61]
	s_mov_b32 m0, s76
	s_nop 0
	global_load_lds_dwordx4 v154, s[74:75]
	s_add_i32 m0, s76, 0x2000
	s_nop 0
	global_load_lds_dwordx4 v158, s[74:75]
	s_add_u32 s100, s62, s36
	s_addc_u32 s101, s63, s37
	s_mov_b32 m0, s1
	s_nop 0
	global_load_lds_dwordx4 v152, s[62:63]
	s_mov_b32 m0, s10
	s_nop 0
	global_load_lds_dwordx4 v156, s[62:63]
	s_waitcnt vmcnt(8)
	s_waitcnt lgkmcnt(0)
	s_barrier
	s_setprio 1
	s_waitcnt lgkmcnt(0)
	v_mfma_f32_16x16x32_bf16 v[60:63], v[128:131], v[196:199], v[60:63]
	v_mfma_f32_16x16x32_bf16 v[60:63], v[132:135], v[200:203], v[60:63]
	v_mfma_f32_16x16x32_bf16 v[56:59], v[136:139], v[196:199], v[56:59]
	v_mfma_f32_16x16x32_bf16 v[56:59], v[140:143], v[200:203], v[56:59]
	v_mfma_f32_16x16x32_bf16 v[44:47], v[128:131], v[204:207], v[44:47]
	v_mfma_f32_16x16x32_bf16 v[44:47], v[132:135], v[208:211], v[44:47]
	v_mfma_f32_16x16x32_bf16 v[40:43], v[136:139], v[204:207], v[40:43]
	v_mfma_f32_16x16x32_bf16 v[40:43], v[140:143], v[208:211], v[40:43]
	v_mfma_f32_16x16x32_bf16 v[28:31], v[128:131], v[212:215], v[28:31]
	v_mfma_f32_16x16x32_bf16 v[28:31], v[132:135], v[216:219], v[28:31]
	v_mfma_f32_16x16x32_bf16 v[24:27], v[136:139], v[212:215], v[24:27]
	v_mfma_f32_16x16x32_bf16 v[24:27], v[140:143], v[216:219], v[24:27]
	v_mfma_f32_16x16x32_bf16 v[12:15], v[128:131], v[220:223], v[12:15]
	v_mfma_f32_16x16x32_bf16 v[12:15], v[132:135], v[224:227], v[12:15]
	v_mfma_f32_16x16x32_bf16 v[8:11], v[136:139], v[220:223], v[8:11]
	v_mfma_f32_16x16x32_bf16 v[8:11], v[140:143], v[224:227], v[8:11]
	s_setprio 0
	s_setprio 1
	v_mfma_f32_16x16x32_bf16 v[52:55], v[144:147], v[196:199], v[52:55]
	v_mfma_f32_16x16x32_bf16 v[52:55], v[148:151], v[200:203], v[52:55]
	v_mfma_f32_16x16x32_bf16 v[48:51], v[164:167], v[196:199], v[48:51]
	v_mfma_f32_16x16x32_bf16 v[48:51], v[192:195], v[200:203], v[48:51]
	v_mfma_f32_16x16x32_bf16 v[36:39], v[144:147], v[204:207], v[36:39]
	v_mfma_f32_16x16x32_bf16 v[36:39], v[148:151], v[208:211], v[36:39]
	v_mfma_f32_16x16x32_bf16 v[32:35], v[164:167], v[204:207], v[32:35]
	v_mfma_f32_16x16x32_bf16 v[32:35], v[192:195], v[208:211], v[32:35]
	v_mfma_f32_16x16x32_bf16 v[20:23], v[144:147], v[212:215], v[20:23]
	v_mfma_f32_16x16x32_bf16 v[20:23], v[148:151], v[216:219], v[20:23]
	v_mfma_f32_16x16x32_bf16 v[16:19], v[164:167], v[212:215], v[16:19]
	v_mfma_f32_16x16x32_bf16 v[16:19], v[192:195], v[216:219], v[16:19]
	v_mfma_f32_16x16x32_bf16 v[4:7], v[144:147], v[220:223], v[4:7]
	v_mfma_f32_16x16x32_bf16 v[4:7], v[148:151], v[224:227], v[4:7]
	v_mfma_f32_16x16x32_bf16 v[0:3], v[164:167], v[220:223], v[0:3]
	v_mfma_f32_16x16x32_bf16 v[0:3], v[192:195], v[224:227], v[0:3]
	s_setprio 0
	s_barrier
	s_add_i32 s74, 0, 0x18000
	s_add_i32 s75, 0, 0x1c000
	v_add_u32_e32 v140, s74, v171
	v_add_u32_e32 v192, s75, v171
	ds_read_b128 v[128:131], v140
	ds_read_b128 v[132:135], v140 offset:1024
	ds_read_b128 v[136:139], v140 offset:2048
	ds_read_b128 v[140:143], v140 offset:3072
	ds_read_b128 v[144:147], v192
	ds_read_b128 v[148:151], v192 offset:1024
	ds_read_b128 v[164:167], v192 offset:2048
	ds_read_b128 v[192:195], v192 offset:3072
	s_add_u32 s62, s62, 0x40000
	s_addc_u32 s63, s63, 0
	s_mov_b32 m0, s11
	ds_read_b128 v[196:199], v190 offset:32768
	ds_read_b128 v[200:203], v190 offset:33792
	ds_read_b128 v[204:207], v190 offset:34816
	ds_read_b128 v[208:211], v190 offset:35840
	ds_read_b128 v[212:215], v190 offset:36864
	ds_read_b128 v[216:219], v190 offset:37888
	ds_read_b128 v[220:223], v190 offset:38912
	ds_read_b128 v[224:227], v190 offset:39936
	global_load_lds_dwordx4 v152, s[62:63]
	s_mov_b32 m0, s14
	s_nop 0
	global_load_lds_dwordx4 v156, s[62:63]
	s_waitcnt vmcnt(8)
	s_waitcnt lgkmcnt(0)
	s_barrier
	s_setprio 1
	v_mfma_f32_16x16x32_bf16 v[124:127], v[128:131], v[196:199], v[124:127]
	v_mfma_f32_16x16x32_bf16 v[124:127], v[132:135], v[200:203], v[124:127]
	v_mfma_f32_16x16x32_bf16 v[120:123], v[136:139], v[196:199], v[120:123]
	v_mfma_f32_16x16x32_bf16 v[120:123], v[140:143], v[200:203], v[120:123]
	v_mfma_f32_16x16x32_bf16 v[108:111], v[128:131], v[204:207], v[108:111]
	v_mfma_f32_16x16x32_bf16 v[108:111], v[132:135], v[208:211], v[108:111]
	v_mfma_f32_16x16x32_bf16 v[104:107], v[136:139], v[204:207], v[104:107]
	v_mfma_f32_16x16x32_bf16 v[104:107], v[140:143], v[208:211], v[104:107]
	v_mfma_f32_16x16x32_bf16 v[92:95], v[128:131], v[212:215], v[92:95]
	v_mfma_f32_16x16x32_bf16 v[92:95], v[132:135], v[216:219], v[92:95]
	v_mfma_f32_16x16x32_bf16 v[88:91], v[136:139], v[212:215], v[88:91]
	v_mfma_f32_16x16x32_bf16 v[88:91], v[140:143], v[216:219], v[88:91]
	v_mfma_f32_16x16x32_bf16 v[76:79], v[128:131], v[220:223], v[76:79]
	v_mfma_f32_16x16x32_bf16 v[76:79], v[132:135], v[224:227], v[76:79]
	v_mfma_f32_16x16x32_bf16 v[72:75], v[136:139], v[220:223], v[72:75]
	v_mfma_f32_16x16x32_bf16 v[72:75], v[140:143], v[224:227], v[72:75]
	s_setprio 0
	s_setprio 1
	v_mfma_f32_16x16x32_bf16 v[116:119], v[144:147], v[196:199], v[116:119]
	v_mfma_f32_16x16x32_bf16 v[116:119], v[148:151], v[200:203], v[116:119]
	v_mfma_f32_16x16x32_bf16 v[112:115], v[164:167], v[196:199], v[112:115]
	v_mfma_f32_16x16x32_bf16 v[112:115], v[192:195], v[200:203], v[112:115]
	v_mfma_f32_16x16x32_bf16 v[100:103], v[144:147], v[204:207], v[100:103]
	v_mfma_f32_16x16x32_bf16 v[100:103], v[148:151], v[208:211], v[100:103]
	v_mfma_f32_16x16x32_bf16 v[96:99], v[164:167], v[204:207], v[96:99]
	v_mfma_f32_16x16x32_bf16 v[96:99], v[192:195], v[208:211], v[96:99]
	v_mfma_f32_16x16x32_bf16 v[84:87], v[144:147], v[212:215], v[84:87]
	v_mfma_f32_16x16x32_bf16 v[84:87], v[148:151], v[216:219], v[84:87]
	v_mfma_f32_16x16x32_bf16 v[80:83], v[164:167], v[212:215], v[80:83]
	v_mfma_f32_16x16x32_bf16 v[80:83], v[192:195], v[216:219], v[80:83]
	v_mfma_f32_16x16x32_bf16 v[68:71], v[144:147], v[220:223], v[68:71]
	v_mfma_f32_16x16x32_bf16 v[68:71], v[148:151], v[224:227], v[68:71]
	v_mfma_f32_16x16x32_bf16 v[64:67], v[164:167], v[220:223], v[64:67]
	v_mfma_f32_16x16x32_bf16 v[64:67], v[192:195], v[224:227], v[64:67]
	s_setprio 0
	s_barrier
	s_add_i32 s62, s74, s0
	s_mov_b32 m0, s62
	ds_read_b128 v[196:199], v190 offset:49152
	ds_read_b128 v[200:203], v190 offset:50176
	ds_read_b128 v[204:207], v190 offset:51200
	ds_read_b128 v[208:211], v190 offset:52224
	ds_read_b128 v[212:215], v190 offset:53248
	ds_read_b128 v[216:219], v190 offset:54272
	ds_read_b128 v[220:223], v190 offset:55296
	ds_read_b128 v[224:227], v190 offset:56320
	global_load_lds_dwordx4 v154, s[98:99]
	s_add_i32 m0, s62, 0x2000
	s_add_u32 s60, s60, 0x40080
	s_addc_u32 s61, s61, 0
	s_add_i32 s62, s75, s0
	global_load_lds_dwordx4 v158, s[98:99]
	s_mov_b32 m0, s62
	s_nop 0
	global_load_lds_dwordx4 v154, s[60:61]
	s_add_i32 m0, s62, 0x2000
	s_nop 0
	global_load_lds_dwordx4 v158, s[60:61]
	s_mov_b32 m0, s15
	s_nop 0
	global_load_lds_dwordx4 v152, s[100:101]
	s_mov_b32 m0, s33
	s_nop 0
	global_load_lds_dwordx4 v156, s[100:101]
	s_waitcnt vmcnt(8)
	s_waitcnt lgkmcnt(0)
	s_barrier
	s_setprio 1
	s_waitcnt lgkmcnt(0)
	v_mfma_f32_16x16x32_bf16 v[60:63], v[128:131], v[196:199], v[60:63]
	v_mfma_f32_16x16x32_bf16 v[60:63], v[132:135], v[200:203], v[60:63]
	v_mfma_f32_16x16x32_bf16 v[56:59], v[136:139], v[196:199], v[56:59]
	v_mfma_f32_16x16x32_bf16 v[56:59], v[140:143], v[200:203], v[56:59]
	v_mfma_f32_16x16x32_bf16 v[44:47], v[128:131], v[204:207], v[44:47]
	v_mfma_f32_16x16x32_bf16 v[44:47], v[132:135], v[208:211], v[44:47]
	v_mfma_f32_16x16x32_bf16 v[40:43], v[136:139], v[204:207], v[40:43]
	v_mfma_f32_16x16x32_bf16 v[40:43], v[140:143], v[208:211], v[40:43]
	v_mfma_f32_16x16x32_bf16 v[28:31], v[128:131], v[212:215], v[28:31]
	v_mfma_f32_16x16x32_bf16 v[28:31], v[132:135], v[216:219], v[28:31]
	v_mfma_f32_16x16x32_bf16 v[24:27], v[136:139], v[212:215], v[24:27]
	v_mfma_f32_16x16x32_bf16 v[24:27], v[140:143], v[216:219], v[24:27]
	v_mfma_f32_16x16x32_bf16 v[12:15], v[128:131], v[220:223], v[12:15]
	v_mfma_f32_16x16x32_bf16 v[12:15], v[132:135], v[224:227], v[12:15]
	v_mfma_f32_16x16x32_bf16 v[8:11], v[136:139], v[220:223], v[8:11]
	v_mfma_f32_16x16x32_bf16 v[8:11], v[140:143], v[224:227], v[8:11]
	s_setprio 0
	s_setprio 1
	v_mfma_f32_16x16x32_bf16 v[52:55], v[144:147], v[196:199], v[52:55]
	v_mfma_f32_16x16x32_bf16 v[52:55], v[148:151], v[200:203], v[52:55]
	v_mfma_f32_16x16x32_bf16 v[48:51], v[164:167], v[196:199], v[48:51]
	v_mfma_f32_16x16x32_bf16 v[48:51], v[192:195], v[200:203], v[48:51]
	v_mfma_f32_16x16x32_bf16 v[36:39], v[144:147], v[204:207], v[36:39]
	v_mfma_f32_16x16x32_bf16 v[36:39], v[148:151], v[208:211], v[36:39]
	v_mfma_f32_16x16x32_bf16 v[32:35], v[164:167], v[204:207], v[32:35]
	v_mfma_f32_16x16x32_bf16 v[32:35], v[192:195], v[208:211], v[32:35]
	v_mfma_f32_16x16x32_bf16 v[20:23], v[144:147], v[212:215], v[20:23]
	v_mfma_f32_16x16x32_bf16 v[20:23], v[148:151], v[216:219], v[20:23]
	v_mfma_f32_16x16x32_bf16 v[16:19], v[164:167], v[212:215], v[16:19]
	v_mfma_f32_16x16x32_bf16 v[16:19], v[192:195], v[216:219], v[16:19]
	v_mfma_f32_16x16x32_bf16 v[4:7], v[144:147], v[220:223], v[4:7]
	v_mfma_f32_16x16x32_bf16 v[4:7], v[148:151], v[224:227], v[4:7]
	v_mfma_f32_16x16x32_bf16 v[0:3], v[164:167], v[220:223], v[0:3]
	v_mfma_f32_16x16x32_bf16 v[0:3], v[192:195], v[224:227], v[0:3]
	s_setprio 0
	s_barrier
	s_add_i32 s73, s73, 2
	s_add_u32 s50, s50, 0x100
	s_addc_u32 s51, s51, 0
	s_add_u32 s71, s71, 0x100
	s_addc_u32 s72, s72, 0
	s_cmp_gt_u32 s73, 13
	s_cbranch_scc0 .LBB0_707
	s_and_b64 vcc, exec, s[38:39]
	s_cbranch_vccz .LBB0_710
	s_barrier

.LBB0_793:
	ds_read_b128 v[144:147], v153
	ds_read_b128 v[158:161], v153 offset:1024
	ds_read_b128 v[162:165], v153 offset:2048
	ds_read_b128 v[166:169], v153 offset:3072
	ds_read_b128 v[170:173], v154
	ds_read_b128 v[176:179], v154 offset:1024
	ds_read_b128 v[180:183], v154 offset:2048
	ds_read_b128 v[184:187], v154 offset:3072
	s_add_u32 s44, s42, 0xfff80080
	s_addc_u32 s45, s43, -1
	s_cmp_eq_u32 s65, 28
	s_cselect_b32 s47, s35, s45
	s_cselect_b32 s46, s61, s44
	s_cselect_b32 s45, s27, s64
	s_cselect_b32 s44, s62, s63
	s_add_u32 s100, s46, 0x80
	s_addc_u32 s101, s47, 0
	s_add_i32 m0, s10, 0xc000
	ds_read_b128 v[188:191], v155
	ds_read_b128 v[192:195], v155 offset:1024
	ds_read_b128 v[196:199], v155 offset:2048
	ds_read_b128 v[200:203], v155 offset:3072
	ds_read_b128 v[204:207], v155 offset:4096
	ds_read_b128 v[208:211], v155 offset:5120
	ds_read_b128 v[212:215], v155 offset:6144
	ds_read_b128 v[216:219], v155 offset:7168
	global_load_lds_dwordx4 v136, s[42:43]
	s_add_i32 m0, s10, 0xe000
	s_nop 0
	global_load_lds_dwordx4 v138, s[42:43]
	s_waitcnt vmcnt(8)
	s_waitcnt lgkmcnt(0)
	s_setprio 1
	v_mfma_f32_16x16x32_bf16 v[124:127], v[144:147], v[188:191], v[124:127]
	v_mfma_f32_16x16x32_bf16 v[124:127], v[158:161], v[192:195], v[124:127]
	v_mfma_f32_16x16x32_bf16 v[120:123], v[166:169], v[192:195], v[120:123]
	v_mfma_f32_16x16x32_bf16 v[120:123], v[162:165], v[188:191], v[120:123]
	v_mfma_f32_16x16x32_bf16 v[104:107], v[162:165], v[196:199], v[104:107]
	v_mfma_f32_16x16x32_bf16 v[104:107], v[166:169], v[200:203], v[104:107]
	v_mfma_f32_16x16x32_bf16 v[108:111], v[158:161], v[200:203], v[108:111]
	v_mfma_f32_16x16x32_bf16 v[108:111], v[144:147], v[196:199], v[108:111]
	v_mfma_f32_16x16x32_bf16 v[92:95], v[144:147], v[204:207], v[92:95]
	v_mfma_f32_16x16x32_bf16 v[92:95], v[158:161], v[208:211], v[92:95]
	v_mfma_f32_16x16x32_bf16 v[88:91], v[166:169], v[208:211], v[88:91]
	v_mfma_f32_16x16x32_bf16 v[88:91], v[162:165], v[204:207], v[88:91]
	v_mfma_f32_16x16x32_bf16 v[72:75], v[162:165], v[212:215], v[72:75]
	v_mfma_f32_16x16x32_bf16 v[72:75], v[166:169], v[216:219], v[72:75]
	v_mfma_f32_16x16x32_bf16 v[76:79], v[158:161], v[216:219], v[76:79]
	v_mfma_f32_16x16x32_bf16 v[76:79], v[144:147], v[212:215], v[76:79]
	s_setprio 0
	s_setprio 1
	v_mfma_f32_16x16x32_bf16 v[116:119], v[170:173], v[188:191], v[116:119]
	v_mfma_f32_16x16x32_bf16 v[116:119], v[176:179], v[192:195], v[116:119]
	v_mfma_f32_16x16x32_bf16 v[112:115], v[184:187], v[192:195], v[112:115]
	v_mfma_f32_16x16x32_bf16 v[112:115], v[180:183], v[188:191], v[112:115]
	v_mfma_f32_16x16x32_bf16 v[96:99], v[180:183], v[196:199], v[96:99]
	v_mfma_f32_16x16x32_bf16 v[96:99], v[184:187], v[200:203], v[96:99]
	v_mfma_f32_16x16x32_bf16 v[100:103], v[176:179], v[200:203], v[100:103]
	v_mfma_f32_16x16x32_bf16 v[100:103], v[170:173], v[196:199], v[100:103]
	v_mfma_f32_16x16x32_bf16 v[84:87], v[170:173], v[204:207], v[84:87]
	v_mfma_f32_16x16x32_bf16 v[84:87], v[176:179], v[208:211], v[84:87]
	v_mfma_f32_16x16x32_bf16 v[80:83], v[184:187], v[208:211], v[80:83]
	v_mfma_f32_16x16x32_bf16 v[80:83], v[180:183], v[204:207], v[80:83]
	v_mfma_f32_16x16x32_bf16 v[64:67], v[180:183], v[212:215], v[64:67]
	v_mfma_f32_16x16x32_bf16 v[64:67], v[184:187], v[216:219], v[64:67]
	v_mfma_f32_16x16x32_bf16 v[68:71], v[176:179], v[216:219], v[68:71]
	v_mfma_f32_16x16x32_bf16 v[68:71], v[170:173], v[212:215], v[68:71]
	s_setprio 0
	s_barrier
	s_add_i32 s66, s49, s0
	s_mov_b32 m0, s66
	ds_read_b128 v[188:191], v155 offset:16384
	ds_read_b128 v[192:195], v155 offset:17408
	ds_read_b128 v[196:199], v155 offset:18432
	ds_read_b128 v[200:203], v155 offset:19456
	ds_read_b128 v[204:207], v155 offset:20480
	ds_read_b128 v[208:211], v155 offset:21504
	ds_read_b128 v[212:215], v155 offset:22528
	ds_read_b128 v[216:219], v155 offset:23552
	global_load_lds_dwordx4 v132, s[44:45]
	s_add_i32 m0, s66, 0x2000
	s_add_u32 s66, s44, 0x80000
	s_addc_u32 s67, s45, 0
	s_add_i32 s68, s50, s0
	global_load_lds_dwordx4 v128, s[44:45]
	s_mov_b32 m0, s68
	s_nop 0
	global_load_lds_dwordx4 v132, s[66:67]
	s_add_i32 m0, s68, 0x2000
	s_nop 0
	global_load_lds_dwordx4 v128, s[66:67]
	s_mov_b32 m0, s10
	s_nop 0
	global_load_lds_dwordx4 v134, s[46:47]
	s_mov_b32 m0, s11
	s_nop 0
	global_load_lds_dwordx4 v130, s[46:47]
	s_waitcnt vmcnt(8)
	s_waitcnt lgkmcnt(0)
	s_setprio 1
	v_mfma_f32_16x16x32_bf16 v[60:63], v[144:147], v[188:191], v[60:63]
	v_mfma_f32_16x16x32_bf16 v[60:63], v[158:161], v[192:195], v[60:63]
	v_mfma_f32_16x16x32_bf16 v[56:59], v[166:169], v[192:195], v[56:59]
	v_mfma_f32_16x16x32_bf16 v[56:59], v[162:165], v[188:191], v[56:59]
	v_mfma_f32_16x16x32_bf16 v[40:43], v[162:165], v[196:199], v[40:43]
	v_mfma_f32_16x16x32_bf16 v[40:43], v[166:169], v[200:203], v[40:43]
	v_mfma_f32_16x16x32_bf16 v[44:47], v[158:161], v[200:203], v[44:47]
	v_mfma_f32_16x16x32_bf16 v[44:47], v[144:147], v[196:199], v[44:47]
	v_mfma_f32_16x16x32_bf16 v[28:31], v[144:147], v[204:207], v[28:31]
	v_mfma_f32_16x16x32_bf16 v[28:31], v[158:161], v[208:211], v[28:31]
	v_mfma_f32_16x16x32_bf16 v[24:27], v[166:169], v[208:211], v[24:27]
	v_mfma_f32_16x16x32_bf16 v[24:27], v[162:165], v[204:207], v[24:27]
	v_mfma_f32_16x16x32_bf16 v[8:11], v[162:165], v[212:215], v[8:11]
	v_mfma_f32_16x16x32_bf16 v[8:11], v[166:169], v[216:219], v[8:11]
	v_mfma_f32_16x16x32_bf16 v[12:15], v[158:161], v[216:219], v[12:15]
	v_mfma_f32_16x16x32_bf16 v[12:15], v[144:147], v[212:215], v[12:15]
	s_setprio 0
	s_setprio 1
	v_mfma_f32_16x16x32_bf16 v[52:55], v[170:173], v[188:191], v[52:55]
	v_mfma_f32_16x16x32_bf16 v[52:55], v[176:179], v[192:195], v[52:55]
	v_mfma_f32_16x16x32_bf16 v[48:51], v[184:187], v[192:195], v[48:51]
	v_mfma_f32_16x16x32_bf16 v[48:51], v[180:183], v[188:191], v[48:51]
	v_mfma_f32_16x16x32_bf16 v[32:35], v[180:183], v[196:199], v[32:35]
	v_mfma_f32_16x16x32_bf16 v[32:35], v[184:187], v[200:203], v[32:35]
	v_mfma_f32_16x16x32_bf16 v[36:39], v[176:179], v[200:203], v[36:39]
	v_mfma_f32_16x16x32_bf16 v[36:39], v[170:173], v[196:199], v[36:39]
	v_mfma_f32_16x16x32_bf16 v[20:23], v[170:173], v[204:207], v[20:23]
	v_mfma_f32_16x16x32_bf16 v[20:23], v[176:179], v[208:211], v[20:23]
	v_mfma_f32_16x16x32_bf16 v[16:19], v[184:187], v[208:211], v[16:19]
	v_mfma_f32_16x16x32_bf16 v[16:19], v[180:183], v[204:207], v[16:19]
	v_mfma_f32_16x16x32_bf16 v[0:3], v[180:183], v[212:215], v[0:3]
	v_mfma_f32_16x16x32_bf16 v[0:3], v[184:187], v[216:219], v[0:3]
	v_mfma_f32_16x16x32_bf16 v[4:7], v[176:179], v[216:219], v[4:7]
	v_mfma_f32_16x16x32_bf16 v[4:7], v[170:173], v[212:215], v[4:7]
	s_setprio 0
	s_barrier
	s_add_i32 s66, 0, 0x18000
	v_add_u32_e32 v157, s66, v151
	s_add_i32 s67, 0, 0x1c000
	ds_read_b128 v[144:147], v157
	ds_read_b128 v[158:161], v157 offset:1024
	ds_read_b128 v[162:165], v157 offset:2048
	ds_read_b128 v[166:169], v157 offset:3072
	v_add_u32_e32 v157, s67, v151
	ds_read_b128 v[170:173], v157
	ds_read_b128 v[176:179], v157 offset:1024
	ds_read_b128 v[180:183], v157 offset:2048
	ds_read_b128 v[184:187], v157 offset:3072
	s_add_u32 s46, s46, 0x80000
	s_addc_u32 s47, s47, 0
	s_mov_b32 m0, s14
	ds_read_b128 v[188:191], v155 offset:32768
	ds_read_b128 v[192:195], v155 offset:33792
	ds_read_b128 v[196:199], v155 offset:34816
	ds_read_b128 v[200:203], v155 offset:35840
	ds_read_b128 v[204:207], v155 offset:36864
	ds_read_b128 v[208:211], v155 offset:37888
	ds_read_b128 v[212:215], v155 offset:38912
	ds_read_b128 v[216:219], v155 offset:39936
	global_load_lds_dwordx4 v134, s[46:47]
	s_mov_b32 m0, s15
	s_nop 0
	global_load_lds_dwordx4 v130, s[46:47]
	s_waitcnt vmcnt(8)
	s_waitcnt lgkmcnt(0)
	s_setprio 1
	s_waitcnt lgkmcnt(0)
	v_mfma_f32_16x16x32_bf16 v[124:127], v[144:147], v[188:191], v[124:127]
	v_mfma_f32_16x16x32_bf16 v[124:127], v[158:161], v[192:195], v[124:127]
	v_mfma_f32_16x16x32_bf16 v[120:123], v[166:169], v[192:195], v[120:123]
	v_mfma_f32_16x16x32_bf16 v[120:123], v[162:165], v[188:191], v[120:123]
	v_mfma_f32_16x16x32_bf16 v[104:107], v[162:165], v[196:199], v[104:107]
	v_mfma_f32_16x16x32_bf16 v[104:107], v[166:169], v[200:203], v[104:107]
	v_mfma_f32_16x16x32_bf16 v[108:111], v[158:161], v[200:203], v[108:111]
	v_mfma_f32_16x16x32_bf16 v[108:111], v[144:147], v[196:199], v[108:111]
	v_mfma_f32_16x16x32_bf16 v[92:95], v[144:147], v[204:207], v[92:95]
	v_mfma_f32_16x16x32_bf16 v[92:95], v[158:161], v[208:211], v[92:95]
	v_mfma_f32_16x16x32_bf16 v[88:91], v[166:169], v[208:211], v[88:91]
	v_mfma_f32_16x16x32_bf16 v[88:91], v[162:165], v[204:207], v[88:91]
	v_mfma_f32_16x16x32_bf16 v[72:75], v[162:165], v[212:215], v[72:75]
	v_mfma_f32_16x16x32_bf16 v[72:75], v[166:169], v[216:219], v[72:75]
	v_mfma_f32_16x16x32_bf16 v[76:79], v[158:161], v[216:219], v[76:79]
	v_mfma_f32_16x16x32_bf16 v[76:79], v[144:147], v[212:215], v[76:79]
	s_setprio 0
	s_setprio 1
	v_mfma_f32_16x16x32_bf16 v[116:119], v[170:173], v[188:191], v[116:119]
	v_mfma_f32_16x16x32_bf16 v[116:119], v[176:179], v[192:195], v[116:119]
	v_mfma_f32_16x16x32_bf16 v[112:115], v[184:187], v[192:195], v[112:115]
	v_mfma_f32_16x16x32_bf16 v[112:115], v[180:183], v[188:191], v[112:115]
	v_mfma_f32_16x16x32_bf16 v[96:99], v[180:183], v[196:199], v[96:99]
	v_mfma_f32_16x16x32_bf16 v[96:99], v[184:187], v[200:203], v[96:99]
	v_mfma_f32_16x16x32_bf16 v[100:103], v[176:179], v[200:203], v[100:103]
	v_mfma_f32_16x16x32_bf16 v[100:103], v[170:173], v[196:199], v[100:103]
	v_mfma_f32_16x16x32_bf16 v[84:87], v[170:173], v[204:207], v[84:87]
	v_mfma_f32_16x16x32_bf16 v[84:87], v[176:179], v[208:211], v[84:87]
	v_mfma_f32_16x16x32_bf16 v[80:83], v[184:187], v[208:211], v[80:83]
	v_mfma_f32_16x16x32_bf16 v[80:83], v[180:183], v[204:207], v[80:83]
	v_mfma_f32_16x16x32_bf16 v[64:67], v[180:183], v[212:215], v[64:67]
	v_mfma_f32_16x16x32_bf16 v[64:67], v[184:187], v[216:219], v[64:67]
	v_mfma_f32_16x16x32_bf16 v[68:71], v[176:179], v[216:219], v[68:71]
	v_mfma_f32_16x16x32_bf16 v[68:71], v[170:173], v[212:215], v[68:71]
	s_setprio 0
	s_barrier
	s_add_i32 s46, s66, s0
	s_add_u32 s98, s44, 0x80
	s_addc_u32 s99, s45, 0
	s_mov_b32 m0, s46
	ds_read_b128 v[188:191], v155 offset:49152
	ds_read_b128 v[192:195], v155 offset:50176
	ds_read_b128 v[196:199], v155 offset:51200
	ds_read_b128 v[200:203], v155 offset:52224
	ds_read_b128 v[204:207], v155 offset:53248
	ds_read_b128 v[208:211], v155 offset:54272
	ds_read_b128 v[212:215], v155 offset:55296
	ds_read_b128 v[216:219], v155 offset:56320
	global_load_lds_dwordx4 v132, s[98:99]
	s_add_i32 m0, s46, 0x2000
	s_add_u32 s44, s44, 0x80080
	s_addc_u32 s45, s45, 0
	s_add_i32 s46, s67, s0
	global_load_lds_dwordx4 v128, s[98:99]
	s_mov_b32 m0, s46
	s_nop 0
	global_load_lds_dwordx4 v132, s[44:45]
	s_add_i32 m0, s46, 0x2000
	s_nop 0
	global_load_lds_dwordx4 v128, s[44:45]
	s_mov_b32 m0, s41
	s_nop 0
	global_load_lds_dwordx4 v134, s[100:101]
	s_mov_b32 m0, s48
	s_nop 0
	global_load_lds_dwordx4 v130, s[100:101]
	s_waitcnt vmcnt(8)
	s_waitcnt lgkmcnt(0)
	s_setprio 1
	s_waitcnt lgkmcnt(0)
	v_mfma_f32_16x16x32_bf16 v[60:63], v[144:147], v[188:191], v[60:63]
	v_mfma_f32_16x16x32_bf16 v[60:63], v[158:161], v[192:195], v[60:63]
	v_mfma_f32_16x16x32_bf16 v[56:59], v[166:169], v[192:195], v[56:59]
	v_mfma_f32_16x16x32_bf16 v[56:59], v[162:165], v[188:191], v[56:59]
	v_mfma_f32_16x16x32_bf16 v[40:43], v[162:165], v[196:199], v[40:43]
	v_mfma_f32_16x16x32_bf16 v[40:43], v[166:169], v[200:203], v[40:43]
	v_mfma_f32_16x16x32_bf16 v[44:47], v[158:161], v[200:203], v[44:47]
	v_mfma_f32_16x16x32_bf16 v[44:47], v[144:147], v[196:199], v[44:47]
	v_mfma_f32_16x16x32_bf16 v[28:31], v[144:147], v[204:207], v[28:31]
	v_mfma_f32_16x16x32_bf16 v[28:31], v[158:161], v[208:211], v[28:31]
	v_mfma_f32_16x16x32_bf16 v[24:27], v[166:169], v[208:211], v[24:27]
	v_mfma_f32_16x16x32_bf16 v[24:27], v[162:165], v[204:207], v[24:27]
	v_mfma_f32_16x16x32_bf16 v[8:11], v[162:165], v[212:215], v[8:11]
	v_mfma_f32_16x16x32_bf16 v[8:11], v[166:169], v[216:219], v[8:11]
	v_mfma_f32_16x16x32_bf16 v[12:15], v[158:161], v[216:219], v[12:15]
	v_mfma_f32_16x16x32_bf16 v[12:15], v[144:147], v[212:215], v[12:15]
	s_setprio 0
	s_setprio 1
	v_mfma_f32_16x16x32_bf16 v[52:55], v[170:173], v[188:191], v[52:55]
	v_mfma_f32_16x16x32_bf16 v[52:55], v[176:179], v[192:195], v[52:55]
	v_mfma_f32_16x16x32_bf16 v[48:51], v[184:187], v[192:195], v[48:51]
	v_mfma_f32_16x16x32_bf16 v[48:51], v[180:183], v[188:191], v[48:51]
	v_mfma_f32_16x16x32_bf16 v[32:35], v[180:183], v[196:199], v[32:35]
	v_mfma_f32_16x16x32_bf16 v[32:35], v[184:187], v[200:203], v[32:35]
	v_mfma_f32_16x16x32_bf16 v[36:39], v[176:179], v[200:203], v[36:39]
	v_mfma_f32_16x16x32_bf16 v[36:39], v[170:173], v[196:199], v[36:39]
	v_mfma_f32_16x16x32_bf16 v[20:23], v[170:173], v[204:207], v[20:23]
	v_mfma_f32_16x16x32_bf16 v[20:23], v[176:179], v[208:211], v[20:23]
	v_mfma_f32_16x16x32_bf16 v[16:19], v[184:187], v[208:211], v[16:19]
	v_mfma_f32_16x16x32_bf16 v[16:19], v[180:183], v[204:207], v[16:19]
	v_mfma_f32_16x16x32_bf16 v[0:3], v[180:183], v[212:215], v[0:3]
	v_mfma_f32_16x16x32_bf16 v[0:3], v[184:187], v[216:219], v[0:3]
	v_mfma_f32_16x16x32_bf16 v[4:7], v[176:179], v[216:219], v[4:7]
	v_mfma_f32_16x16x32_bf16 v[4:7], v[170:173], v[212:215], v[4:7]
	s_setprio 0
	s_barrier
	s_add_i32 s65, s65, 2
	s_add_u32 s42, s42, 0x100
	s_addc_u32 s43, s43, 0
	s_add_u32 s63, s63, 0x100
	s_addc_u32 s64, s64, 0
	s_cmp_gt_u32 s65, 29
	s_cbranch_scc0 .LBB0_793
	s_branch .Lp7_kloop_done
.Lp7_kloop_h1:
	ds_read_b128 v[144:147], v153
	ds_read_b128 v[158:161], v153 offset:1024
	ds_read_b128 v[162:165], v153 offset:2048
	ds_read_b128 v[166:169], v153 offset:3072
	ds_read_b128 v[170:173], v154
	ds_read_b128 v[176:179], v154 offset:1024
	ds_read_b128 v[180:183], v154 offset:2048
	ds_read_b128 v[184:187], v154 offset:3072
	s_add_u32 s44, s42, 0xfff80080
	s_addc_u32 s45, s43, -1
	s_cmp_eq_u32 s65, 28
	s_cselect_b32 s47, s35, s45
	s_cselect_b32 s46, s61, s44
	s_cselect_b32 s45, s27, s64
	s_cselect_b32 s44, s62, s63
	s_add_u32 s100, s46, 0x80
	s_addc_u32 s101, s47, 0
	s_add_i32 m0, s10, 0xc000
	ds_read_b128 v[188:191], v155
	ds_read_b128 v[192:195], v155 offset:1024
	ds_read_b128 v[196:199], v155 offset:2048
	ds_read_b128 v[200:203], v155 offset:3072
	ds_read_b128 v[204:207], v155 offset:4096
	ds_read_b128 v[208:211], v155 offset:5120
	ds_read_b128 v[212:215], v155 offset:6144
	ds_read_b128 v[216:219], v155 offset:7168
	global_load_lds_dwordx4 v136, s[42:43]
	s_add_i32 m0, s10, 0xe000
	s_nop 0
	global_load_lds_dwordx4 v138, s[42:43]
	s_waitcnt vmcnt(8)
	s_waitcnt lgkmcnt(0)
	s_barrier
	s_setprio 2
	v_mfma_f32_16x16x32_bf16 v[124:127], v[144:147], v[188:191], v[124:127]
	v_mfma_f32_16x16x32_bf16 v[120:123], v[162:165], v[188:191], v[120:123]
	v_mfma_f32_16x16x32_bf16 v[104:107], v[162:165], v[196:199], v[104:107]
	v_mfma_f32_16x16x32_bf16 v[108:111], v[144:147], v[196:199], v[108:111]
	v_mfma_f32_16x16x32_bf16 v[92:95], v[144:147], v[204:207], v[92:95]
	v_mfma_f32_16x16x32_bf16 v[88:91], v[162:165], v[204:207], v[88:91]
	v_mfma_f32_16x16x32_bf16 v[72:75], v[162:165], v[212:215], v[72:75]
	v_mfma_f32_16x16x32_bf16 v[76:79], v[144:147], v[212:215], v[76:79]
	v_mfma_f32_16x16x32_bf16 v[76:79], v[158:161], v[216:219], v[76:79]
	v_mfma_f32_16x16x32_bf16 v[72:75], v[166:169], v[216:219], v[72:75]
	v_mfma_f32_16x16x32_bf16 v[88:91], v[166:169], v[208:211], v[88:91]
	v_mfma_f32_16x16x32_bf16 v[92:95], v[158:161], v[208:211], v[92:95]
	v_mfma_f32_16x16x32_bf16 v[108:111], v[158:161], v[200:203], v[108:111]
	v_mfma_f32_16x16x32_bf16 v[104:107], v[166:169], v[200:203], v[104:107]
	v_mfma_f32_16x16x32_bf16 v[120:123], v[166:169], v[192:195], v[120:123]
	v_mfma_f32_16x16x32_bf16 v[124:127], v[158:161], v[192:195], v[124:127]
	s_setprio 0
	s_setprio 2
	v_mfma_f32_16x16x32_bf16 v[116:119], v[170:173], v[188:191], v[116:119]
	v_mfma_f32_16x16x32_bf16 v[112:115], v[180:183], v[188:191], v[112:115]
	v_mfma_f32_16x16x32_bf16 v[96:99], v[180:183], v[196:199], v[96:99]
	v_mfma_f32_16x16x32_bf16 v[100:103], v[170:173], v[196:199], v[100:103]
	v_mfma_f32_16x16x32_bf16 v[84:87], v[170:173], v[204:207], v[84:87]
	v_mfma_f32_16x16x32_bf16 v[80:83], v[180:183], v[204:207], v[80:83]
	v_mfma_f32_16x16x32_bf16 v[64:67], v[180:183], v[212:215], v[64:67]
	v_mfma_f32_16x16x32_bf16 v[68:71], v[170:173], v[212:215], v[68:71]
	v_mfma_f32_16x16x32_bf16 v[68:71], v[176:179], v[216:219], v[68:71]
	v_mfma_f32_16x16x32_bf16 v[64:67], v[184:187], v[216:219], v[64:67]
	v_mfma_f32_16x16x32_bf16 v[80:83], v[184:187], v[208:211], v[80:83]
	v_mfma_f32_16x16x32_bf16 v[84:87], v[176:179], v[208:211], v[84:87]
	v_mfma_f32_16x16x32_bf16 v[100:103], v[176:179], v[200:203], v[100:103]
	v_mfma_f32_16x16x32_bf16 v[96:99], v[184:187], v[200:203], v[96:99]
	v_mfma_f32_16x16x32_bf16 v[112:115], v[184:187], v[192:195], v[112:115]
	v_mfma_f32_16x16x32_bf16 v[116:119], v[176:179], v[192:195], v[116:119]
	s_setprio 0
	s_add_i32 s66, s49, s0
	s_mov_b32 m0, s66
	ds_read_b128 v[188:191], v155 offset:16384
	ds_read_b128 v[192:195], v155 offset:17408
	ds_read_b128 v[196:199], v155 offset:18432
	ds_read_b128 v[200:203], v155 offset:19456
	ds_read_b128 v[204:207], v155 offset:20480
	ds_read_b128 v[208:211], v155 offset:21504
	ds_read_b128 v[212:215], v155 offset:22528
	ds_read_b128 v[216:219], v155 offset:23552
	global_load_lds_dwordx4 v132, s[44:45]
	s_add_i32 m0, s66, 0x2000
	s_add_u32 s66, s44, 0x80000
	s_addc_u32 s67, s45, 0
	s_add_i32 s68, s50, s0
	global_load_lds_dwordx4 v128, s[44:45]
	s_mov_b32 m0, s68
	s_nop 0
	global_load_lds_dwordx4 v132, s[66:67]
	s_add_i32 m0, s68, 0x2000
	s_nop 0
	global_load_lds_dwordx4 v128, s[66:67]
	s_mov_b32 m0, s10
	s_nop 0
	global_load_lds_dwordx4 v134, s[46:47]
	s_mov_b32 m0, s11
	s_nop 0
	global_load_lds_dwordx4 v130, s[46:47]
	s_waitcnt vmcnt(8)
	s_waitcnt lgkmcnt(0)
	s_barrier
	s_setprio 2
	v_mfma_f32_16x16x32_bf16 v[60:63], v[144:147], v[188:191], v[60:63]
	v_mfma_f32_16x16x32_bf16 v[56:59], v[162:165], v[188:191], v[56:59]
	v_mfma_f32_16x16x32_bf16 v[40:43], v[162:165], v[196:199], v[40:43]
	v_mfma_f32_16x16x32_bf16 v[44:47], v[144:147], v[196:199], v[44:47]
	v_mfma_f32_16x16x32_bf16 v[28:31], v[144:147], v[204:207], v[28:31]
	v_mfma_f32_16x16x32_bf16 v[24:27], v[162:165], v[204:207], v[24:27]
	v_mfma_f32_16x16x32_bf16 v[8:11], v[162:165], v[212:215], v[8:11]
	v_mfma_f32_16x16x32_bf16 v[12:15], v[144:147], v[212:215], v[12:15]
	v_mfma_f32_16x16x32_bf16 v[12:15], v[158:161], v[216:219], v[12:15]
	v_mfma_f32_16x16x32_bf16 v[8:11], v[166:169], v[216:219], v[8:11]
	v_mfma_f32_16x16x32_bf16 v[24:27], v[166:169], v[208:211], v[24:27]
	v_mfma_f32_16x16x32_bf16 v[28:31], v[158:161], v[208:211], v[28:31]
	v_mfma_f32_16x16x32_bf16 v[44:47], v[158:161], v[200:203], v[44:47]
	v_mfma_f32_16x16x32_bf16 v[40:43], v[166:169], v[200:203], v[40:43]
	v_mfma_f32_16x16x32_bf16 v[56:59], v[166:169], v[192:195], v[56:59]
	v_mfma_f32_16x16x32_bf16 v[60:63], v[158:161], v[192:195], v[60:63]
	s_setprio 0
	s_setprio 2
	v_mfma_f32_16x16x32_bf16 v[52:55], v[170:173], v[188:191], v[52:55]
	v_mfma_f32_16x16x32_bf16 v[48:51], v[180:183], v[188:191], v[48:51]
	v_mfma_f32_16x16x32_bf16 v[32:35], v[180:183], v[196:199], v[32:35]
	v_mfma_f32_16x16x32_bf16 v[36:39], v[170:173], v[196:199], v[36:39]
	v_mfma_f32_16x16x32_bf16 v[20:23], v[170:173], v[204:207], v[20:23]
	v_mfma_f32_16x16x32_bf16 v[16:19], v[180:183], v[204:207], v[16:19]
	v_mfma_f32_16x16x32_bf16 v[0:3], v[180:183], v[212:215], v[0:3]
	v_mfma_f32_16x16x32_bf16 v[4:7], v[170:173], v[212:215], v[4:7]
	v_mfma_f32_16x16x32_bf16 v[4:7], v[176:179], v[216:219], v[4:7]
	v_mfma_f32_16x16x32_bf16 v[0:3], v[184:187], v[216:219], v[0:3]
	v_mfma_f32_16x16x32_bf16 v[16:19], v[184:187], v[208:211], v[16:19]
	v_mfma_f32_16x16x32_bf16 v[20:23], v[176:179], v[208:211], v[20:23]
	v_mfma_f32_16x16x32_bf16 v[36:39], v[176:179], v[200:203], v[36:39]
	v_mfma_f32_16x16x32_bf16 v[32:35], v[184:187], v[200:203], v[32:35]
	v_mfma_f32_16x16x32_bf16 v[48:51], v[184:187], v[192:195], v[48:51]
	v_mfma_f32_16x16x32_bf16 v[52:55], v[176:179], v[192:195], v[52:55]
	s_setprio 0
	s_add_i32 s66, 0, 0x18000
	v_add_u32_e32 v157, s66, v151
	s_add_i32 s67, 0, 0x1c000
	ds_read_b128 v[144:147], v157
	ds_read_b128 v[158:161], v157 offset:1024
	ds_read_b128 v[162:165], v157 offset:2048
	ds_read_b128 v[166:169], v157 offset:3072
	v_add_u32_e32 v157, s67, v151
	ds_read_b128 v[170:173], v157
	ds_read_b128 v[176:179], v157 offset:1024
	ds_read_b128 v[180:183], v157 offset:2048
	ds_read_b128 v[184:187], v157 offset:3072
	s_add_u32 s46, s46, 0x80000
	s_addc_u32 s47, s47, 0
	s_mov_b32 m0, s14
	ds_read_b128 v[188:191], v155 offset:32768
	ds_read_b128 v[192:195], v155 offset:33792
	ds_read_b128 v[196:199], v155 offset:34816
	ds_read_b128 v[200:203], v155 offset:35840
	ds_read_b128 v[204:207], v155 offset:36864
	ds_read_b128 v[208:211], v155 offset:37888
	ds_read_b128 v[212:215], v155 offset:38912
	ds_read_b128 v[216:219], v155 offset:39936
	global_load_lds_dwordx4 v134, s[46:47]
	s_mov_b32 m0, s15
	s_nop 0
	global_load_lds_dwordx4 v130, s[46:47]
	s_waitcnt vmcnt(8)
	s_waitcnt lgkmcnt(0)
	s_barrier
	s_setprio 2
	s_waitcnt lgkmcnt(0)
	v_mfma_f32_16x16x32_bf16 v[124:127], v[144:147], v[188:191], v[124:127]
	v_mfma_f32_16x16x32_bf16 v[120:123], v[162:165], v[188:191], v[120:123]
	v_mfma_f32_16x16x32_bf16 v[104:107], v[162:165], v[196:199], v[104:107]
	v_mfma_f32_16x16x32_bf16 v[108:111], v[144:147], v[196:199], v[108:111]
	v_mfma_f32_16x16x32_bf16 v[92:95], v[144:147], v[204:207], v[92:95]
	v_mfma_f32_16x16x32_bf16 v[88:91], v[162:165], v[204:207], v[88:91]
	v_mfma_f32_16x16x32_bf16 v[72:75], v[162:165], v[212:215], v[72:75]
	v_mfma_f32_16x16x32_bf16 v[76:79], v[144:147], v[212:215], v[76:79]
	v_mfma_f32_16x16x32_bf16 v[76:79], v[158:161], v[216:219], v[76:79]
	v_mfma_f32_16x16x32_bf16 v[72:75], v[166:169], v[216:219], v[72:75]
	v_mfma_f32_16x16x32_bf16 v[88:91], v[166:169], v[208:211], v[88:91]
	v_mfma_f32_16x16x32_bf16 v[92:95], v[158:161], v[208:211], v[92:95]
	v_mfma_f32_16x16x32_bf16 v[108:111], v[158:161], v[200:203], v[108:111]
	v_mfma_f32_16x16x32_bf16 v[104:107], v[166:169], v[200:203], v[104:107]
	v_mfma_f32_16x16x32_bf16 v[120:123], v[166:169], v[192:195], v[120:123]
	v_mfma_f32_16x16x32_bf16 v[124:127], v[158:161], v[192:195], v[124:127]
	s_setprio 0
	s_setprio 2
	v_mfma_f32_16x16x32_bf16 v[116:119], v[170:173], v[188:191], v[116:119]
	v_mfma_f32_16x16x32_bf16 v[112:115], v[180:183], v[188:191], v[112:115]
	v_mfma_f32_16x16x32_bf16 v[96:99], v[180:183], v[196:199], v[96:99]
	v_mfma_f32_16x16x32_bf16 v[100:103], v[170:173], v[196:199], v[100:103]
	v_mfma_f32_16x16x32_bf16 v[84:87], v[170:173], v[204:207], v[84:87]
	v_mfma_f32_16x16x32_bf16 v[80:83], v[180:183], v[204:207], v[80:83]
	v_mfma_f32_16x16x32_bf16 v[64:67], v[180:183], v[212:215], v[64:67]
	v_mfma_f32_16x16x32_bf16 v[68:71], v[170:173], v[212:215], v[68:71]
	v_mfma_f32_16x16x32_bf16 v[68:71], v[176:179], v[216:219], v[68:71]
	v_mfma_f32_16x16x32_bf16 v[64:67], v[184:187], v[216:219], v[64:67]
	v_mfma_f32_16x16x32_bf16 v[80:83], v[184:187], v[208:211], v[80:83]
	v_mfma_f32_16x16x32_bf16 v[84:87], v[176:179], v[208:211], v[84:87]
	v_mfma_f32_16x16x32_bf16 v[100:103], v[176:179], v[200:203], v[100:103]
	v_mfma_f32_16x16x32_bf16 v[96:99], v[184:187], v[200:203], v[96:99]
	v_mfma_f32_16x16x32_bf16 v[112:115], v[184:187], v[192:195], v[112:115]
	v_mfma_f32_16x16x32_bf16 v[116:119], v[176:179], v[192:195], v[116:119]
	s_setprio 0
	s_add_i32 s46, s66, s0
	s_add_u32 s98, s44, 0x80
	s_addc_u32 s99, s45, 0
	s_mov_b32 m0, s46
	ds_read_b128 v[188:191], v155 offset:49152
	ds_read_b128 v[192:195], v155 offset:50176
	ds_read_b128 v[196:199], v155 offset:51200
	ds_read_b128 v[200:203], v155 offset:52224
	ds_read_b128 v[204:207], v155 offset:53248
	ds_read_b128 v[208:211], v155 offset:54272
	ds_read_b128 v[212:215], v155 offset:55296
	ds_read_b128 v[216:219], v155 offset:56320
	global_load_lds_dwordx4 v132, s[98:99]
	s_add_i32 m0, s46, 0x2000
	s_add_u32 s44, s44, 0x80080
	s_addc_u32 s45, s45, 0
	s_add_i32 s46, s67, s0
	global_load_lds_dwordx4 v128, s[98:99]
	s_mov_b32 m0, s46
	s_nop 0
	global_load_lds_dwordx4 v132, s[44:45]
	s_add_i32 m0, s46, 0x2000
	s_nop 0
	global_load_lds_dwordx4 v128, s[44:45]
	s_mov_b32 m0, s41
	s_nop 0
	global_load_lds_dwordx4 v134, s[100:101]
	s_mov_b32 m0, s48
	s_nop 0
	global_load_lds_dwordx4 v130, s[100:101]
	s_waitcnt vmcnt(8)
	s_waitcnt lgkmcnt(0)
	s_barrier
	s_setprio 2
	s_waitcnt lgkmcnt(0)
	v_mfma_f32_16x16x32_bf16 v[60:63], v[144:147], v[188:191], v[60:63]
	v_mfma_f32_16x16x32_bf16 v[56:59], v[162:165], v[188:191], v[56:59]
	v_mfma_f32_16x16x32_bf16 v[40:43], v[162:165], v[196:199], v[40:43]
	v_mfma_f32_16x16x32_bf16 v[44:47], v[144:147], v[196:199], v[44:47]
	v_mfma_f32_16x16x32_bf16 v[28:31], v[144:147], v[204:207], v[28:31]
	v_mfma_f32_16x16x32_bf16 v[24:27], v[162:165], v[204:207], v[24:27]
	v_mfma_f32_16x16x32_bf16 v[8:11], v[162:165], v[212:215], v[8:11]
	v_mfma_f32_16x16x32_bf16 v[12:15], v[144:147], v[212:215], v[12:15]
	v_mfma_f32_16x16x32_bf16 v[12:15], v[158:161], v[216:219], v[12:15]
	v_mfma_f32_16x16x32_bf16 v[8:11], v[166:169], v[216:219], v[8:11]
	v_mfma_f32_16x16x32_bf16 v[24:27], v[166:169], v[208:211], v[24:27]
	v_mfma_f32_16x16x32_bf16 v[28:31], v[158:161], v[208:211], v[28:31]
	v_mfma_f32_16x16x32_bf16 v[44:47], v[158:161], v[200:203], v[44:47]
	v_mfma_f32_16x16x32_bf16 v[40:43], v[166:169], v[200:203], v[40:43]
	v_mfma_f32_16x16x32_bf16 v[56:59], v[166:169], v[192:195], v[56:59]
	v_mfma_f32_16x16x32_bf16 v[60:63], v[158:161], v[192:195], v[60:63]
	s_setprio 0
	s_setprio 2
	v_mfma_f32_16x16x32_bf16 v[52:55], v[170:173], v[188:191], v[52:55]
	v_mfma_f32_16x16x32_bf16 v[48:51], v[180:183], v[188:191], v[48:51]
	v_mfma_f32_16x16x32_bf16 v[32:35], v[180:183], v[196:199], v[32:35]
	v_mfma_f32_16x16x32_bf16 v[36:39], v[170:173], v[196:199], v[36:39]
	v_mfma_f32_16x16x32_bf16 v[20:23], v[170:173], v[204:207], v[20:23]
	v_mfma_f32_16x16x32_bf16 v[16:19], v[180:183], v[204:207], v[16:19]
	v_mfma_f32_16x16x32_bf16 v[0:3], v[180:183], v[212:215], v[0:3]
	v_mfma_f32_16x16x32_bf16 v[4:7], v[170:173], v[212:215], v[4:7]
	v_mfma_f32_16x16x32_bf16 v[4:7], v[176:179], v[216:219], v[4:7]
	v_mfma_f32_16x16x32_bf16 v[0:3], v[184:187], v[216:219], v[0:3]
	v_mfma_f32_16x16x32_bf16 v[16:19], v[184:187], v[208:211], v[16:19]
	v_mfma_f32_16x16x32_bf16 v[20:23], v[176:179], v[208:211], v[20:23]
	v_mfma_f32_16x16x32_bf16 v[36:39], v[176:179], v[200:203], v[36:39]
	v_mfma_f32_16x16x32_bf16 v[32:35], v[184:187], v[200:203], v[32:35]
	v_mfma_f32_16x16x32_bf16 v[48:51], v[184:187], v[192:195], v[48:51]
	v_mfma_f32_16x16x32_bf16 v[52:55], v[176:179], v[192:195], v[52:55]
	s_setprio 0
	s_add_i32 s65, s65, 2
	s_add_u32 s42, s42, 0x100
	s_addc_u32 s43, s43, 0
	s_add_u32 s63, s63, 0x100
	s_addc_u32 s64, s64, 0
	s_cmp_gt_u32 s65, 29
	s_cbranch_scc0 .Lp7_kloop_h1

.LBB0_873:
	ds_read_b128 v[128:131], v192
	ds_read_b128 v[132:135], v192 offset:1024
	ds_read_b128 v[136:139], v192 offset:2048
	ds_read_b128 v[140:143], v192 offset:3072
	ds_read_b128 v[144:147], v193
	ds_read_b128 v[148:151], v193 offset:1024
	ds_read_b128 v[168:171], v193 offset:2048
	ds_read_b128 v[196:199], v193 offset:3072
	s_add_u32 s34, s26, 0x100
	s_addc_u32 s35, s27, 0
	s_cmpk_eq_i32 s51, 0x54
	s_cselect_b32 s39, s1, s35
	s_cselect_b32 s38, s0, s34
	s_cselect_b32 s37, s25, s50
	s_cselect_b32 s36, s24, s49
	v_lshl_add_u64 v[172:173], s[26:27], 0, v[160:161]
	s_add_i32 m0, s11, 0xc000
	ds_read_b128 v[200:203], v194
	ds_read_b128 v[204:207], v194 offset:1024
	ds_read_b128 v[208:211], v194 offset:2048
	ds_read_b128 v[212:215], v194 offset:3072
	ds_read_b128 v[216:219], v194 offset:4096
	ds_read_b128 v[220:223], v194 offset:5120
	ds_read_b128 v[224:227], v194 offset:6144
	ds_read_b128 v[228:231], v194 offset:7168
	global_load_lds_dwordx4 v[172:173], off
	v_lshl_add_u64 v[172:173], s[26:27], 0, v[162:163]
	s_add_i32 m0, s11, 0xe000
	s_nop 0
	global_load_lds_dwordx4 v[172:173], off
	s_waitcnt vmcnt(8)
	s_waitcnt lgkmcnt(0)
	s_barrier
	s_setprio 1
	s_waitcnt lgkmcnt(0)
	v_mfma_f32_16x16x32_bf16 v[124:127], v[128:131], v[200:203], v[124:127]
	v_mfma_f32_16x16x32_bf16 v[124:127], v[132:135], v[204:207], v[124:127]
	v_mfma_f32_16x16x32_bf16 v[120:123], v[136:139], v[200:203], v[120:123]
	v_mfma_f32_16x16x32_bf16 v[120:123], v[140:143], v[204:207], v[120:123]
	v_mfma_f32_16x16x32_bf16 v[108:111], v[128:131], v[208:211], v[108:111]
	v_mfma_f32_16x16x32_bf16 v[108:111], v[132:135], v[212:215], v[108:111]
	v_mfma_f32_16x16x32_bf16 v[104:107], v[136:139], v[208:211], v[104:107]
	v_mfma_f32_16x16x32_bf16 v[104:107], v[140:143], v[212:215], v[104:107]
	v_mfma_f32_16x16x32_bf16 v[92:95], v[128:131], v[216:219], v[92:95]
	v_mfma_f32_16x16x32_bf16 v[92:95], v[132:135], v[220:223], v[92:95]
	v_mfma_f32_16x16x32_bf16 v[88:91], v[136:139], v[216:219], v[88:91]
	v_mfma_f32_16x16x32_bf16 v[88:91], v[140:143], v[220:223], v[88:91]
	v_mfma_f32_16x16x32_bf16 v[76:79], v[128:131], v[224:227], v[76:79]
	v_mfma_f32_16x16x32_bf16 v[76:79], v[132:135], v[228:231], v[76:79]
	v_mfma_f32_16x16x32_bf16 v[72:75], v[136:139], v[224:227], v[72:75]
	v_mfma_f32_16x16x32_bf16 v[72:75], v[140:143], v[228:231], v[72:75]
	s_setprio 0
	s_setprio 1
	v_mfma_f32_16x16x32_bf16 v[116:119], v[144:147], v[200:203], v[116:119]
	v_mfma_f32_16x16x32_bf16 v[116:119], v[148:151], v[204:207], v[116:119]
	v_mfma_f32_16x16x32_bf16 v[112:115], v[168:171], v[200:203], v[112:115]
	v_mfma_f32_16x16x32_bf16 v[112:115], v[196:199], v[204:207], v[112:115]
	v_mfma_f32_16x16x32_bf16 v[100:103], v[144:147], v[208:211], v[100:103]
	v_mfma_f32_16x16x32_bf16 v[100:103], v[148:151], v[212:215], v[100:103]
	v_mfma_f32_16x16x32_bf16 v[96:99], v[168:171], v[208:211], v[96:99]
	v_mfma_f32_16x16x32_bf16 v[96:99], v[196:199], v[212:215], v[96:99]
	v_mfma_f32_16x16x32_bf16 v[84:87], v[144:147], v[216:219], v[84:87]
	v_mfma_f32_16x16x32_bf16 v[84:87], v[148:151], v[220:223], v[84:87]
	v_mfma_f32_16x16x32_bf16 v[80:83], v[168:171], v[216:219], v[80:83]
	v_mfma_f32_16x16x32_bf16 v[80:83], v[196:199], v[220:223], v[80:83]
	v_mfma_f32_16x16x32_bf16 v[68:71], v[144:147], v[224:227], v[68:71]
	v_mfma_f32_16x16x32_bf16 v[68:71], v[148:151], v[228:231], v[68:71]
	v_mfma_f32_16x16x32_bf16 v[64:67], v[168:171], v[224:227], v[64:67]
	v_mfma_f32_16x16x32_bf16 v[64:67], v[196:199], v[228:231], v[64:67]
	s_setprio 0
	s_barrier
	s_add_i32 s26, s45, s10
	v_lshl_add_u64 v[172:173], s[36:37], 0, v[154:155]
	s_mov_b32 m0, s26
	ds_read_b128 v[200:203], v194 offset:16384
	ds_read_b128 v[204:207], v194 offset:17408
	ds_read_b128 v[208:211], v194 offset:18432
	ds_read_b128 v[212:215], v194 offset:19456
	ds_read_b128 v[216:219], v194 offset:20480
	ds_read_b128 v[220:223], v194 offset:21504
	ds_read_b128 v[224:227], v194 offset:22528
	ds_read_b128 v[228:231], v194 offset:23552
	global_load_lds_dwordx4 v[172:173], off
	s_add_i32 m0, s26, 0x2000
	s_add_u32 s26, s36, 0x160000
	v_lshl_add_u64 v[232:233], s[36:37], 0, v[158:159]
	s_addc_u32 s27, s37, 0
	s_add_i32 s60, s46, s10
	global_load_lds_dwordx4 v[232:233], off
	v_lshl_add_u64 v[234:235], s[26:27], 0, v[154:155]
	s_mov_b32 m0, s60
	v_lshl_add_u64 v[236:237], s[38:39], 0, v[156:157]
	global_load_lds_dwordx4 v[234:235], off
	v_lshl_add_u64 v[234:235], s[26:27], 0, v[158:159]
	s_add_i32 m0, s60, 0x2000
	s_nop 0
	global_load_lds_dwordx4 v[234:235], off
	v_lshl_add_u64 v[234:235], s[38:39], 0, v[152:153]
	s_mov_b32 m0, s11
	s_nop 0
	global_load_lds_dwordx4 v[234:235], off
	s_mov_b32 m0, s33
	s_nop 0
	global_load_lds_dwordx4 v[236:237], off
	s_waitcnt vmcnt(8)
	s_waitcnt lgkmcnt(0)
	s_barrier
	s_setprio 1
	v_mfma_f32_16x16x32_bf16 v[60:63], v[128:131], v[200:203], v[60:63]
	v_mfma_f32_16x16x32_bf16 v[60:63], v[132:135], v[204:207], v[60:63]
	v_mfma_f32_16x16x32_bf16 v[56:59], v[136:139], v[200:203], v[56:59]
	v_mfma_f32_16x16x32_bf16 v[56:59], v[140:143], v[204:207], v[56:59]
	v_mfma_f32_16x16x32_bf16 v[44:47], v[128:131], v[208:211], v[44:47]
	v_mfma_f32_16x16x32_bf16 v[44:47], v[132:135], v[212:215], v[44:47]
	v_mfma_f32_16x16x32_bf16 v[40:43], v[136:139], v[208:211], v[40:43]
	v_mfma_f32_16x16x32_bf16 v[40:43], v[140:143], v[212:215], v[40:43]
	v_mfma_f32_16x16x32_bf16 v[28:31], v[128:131], v[216:219], v[28:31]
	v_mfma_f32_16x16x32_bf16 v[28:31], v[132:135], v[220:223], v[28:31]
	v_mfma_f32_16x16x32_bf16 v[24:27], v[136:139], v[216:219], v[24:27]
	v_mfma_f32_16x16x32_bf16 v[24:27], v[140:143], v[220:223], v[24:27]
	v_mfma_f32_16x16x32_bf16 v[12:15], v[128:131], v[224:227], v[12:15]
	v_mfma_f32_16x16x32_bf16 v[12:15], v[132:135], v[228:231], v[12:15]
	v_mfma_f32_16x16x32_bf16 v[8:11], v[136:139], v[224:227], v[8:11]
	v_mfma_f32_16x16x32_bf16 v[8:11], v[140:143], v[228:231], v[8:11]
	s_setprio 0
	s_setprio 1
	v_mfma_f32_16x16x32_bf16 v[52:55], v[144:147], v[200:203], v[52:55]
	v_mfma_f32_16x16x32_bf16 v[52:55], v[148:151], v[204:207], v[52:55]
	v_mfma_f32_16x16x32_bf16 v[48:51], v[168:171], v[200:203], v[48:51]
	v_mfma_f32_16x16x32_bf16 v[48:51], v[196:199], v[204:207], v[48:51]
	v_mfma_f32_16x16x32_bf16 v[36:39], v[144:147], v[208:211], v[36:39]
	v_mfma_f32_16x16x32_bf16 v[36:39], v[148:151], v[212:215], v[36:39]
	v_mfma_f32_16x16x32_bf16 v[32:35], v[168:171], v[208:211], v[32:35]
	v_mfma_f32_16x16x32_bf16 v[32:35], v[196:199], v[212:215], v[32:35]
	v_mfma_f32_16x16x32_bf16 v[20:23], v[144:147], v[216:219], v[20:23]
	v_mfma_f32_16x16x32_bf16 v[20:23], v[148:151], v[220:223], v[20:23]
	v_mfma_f32_16x16x32_bf16 v[16:19], v[168:171], v[216:219], v[16:19]
	v_mfma_f32_16x16x32_bf16 v[16:19], v[196:199], v[220:223], v[16:19]
	v_mfma_f32_16x16x32_bf16 v[4:7], v[144:147], v[224:227], v[4:7]
	v_mfma_f32_16x16x32_bf16 v[4:7], v[148:151], v[228:231], v[4:7]
	v_mfma_f32_16x16x32_bf16 v[0:3], v[168:171], v[224:227], v[0:3]
	v_mfma_f32_16x16x32_bf16 v[0:3], v[196:199], v[228:231], v[0:3]
	s_setprio 0
	s_barrier
	s_add_i32 s60, 0, 0x18000
	s_add_i32 s61, 0, 0x1c000
	v_add_u32_e32 v140, s60, v177
	v_add_u32_e32 v196, s61, v177
	ds_read_b128 v[128:131], v140
	ds_read_b128 v[132:135], v140 offset:1024
	ds_read_b128 v[136:139], v140 offset:2048
	ds_read_b128 v[140:143], v140 offset:3072
	ds_read_b128 v[144:147], v196
	ds_read_b128 v[148:151], v196 offset:1024
	ds_read_b128 v[168:171], v196 offset:2048
	ds_read_b128 v[196:199], v196 offset:3072
	s_add_u32 s26, s38, 0x160000
	s_addc_u32 s27, s39, 0
	s_mov_b32 m0, s40
	v_lshl_add_u64 v[238:239], s[26:27], 0, v[152:153]
	ds_read_b128 v[200:203], v194 offset:32768
	ds_read_b128 v[204:207], v194 offset:33792
	ds_read_b128 v[208:211], v194 offset:34816
	ds_read_b128 v[212:215], v194 offset:35840
	ds_read_b128 v[216:219], v194 offset:36864
	ds_read_b128 v[220:223], v194 offset:37888
	ds_read_b128 v[224:227], v194 offset:38912
	ds_read_b128 v[228:231], v194 offset:39936
	global_load_lds_dwordx4 v[238:239], off
	v_lshl_add_u64 v[238:239], s[26:27], 0, v[156:157]
	s_mov_b32 m0, s41
	s_nop 0
	global_load_lds_dwordx4 v[238:239], off
	s_waitcnt vmcnt(8)
	s_waitcnt lgkmcnt(0)
	s_barrier
	s_setprio 1
	v_mfma_f32_16x16x32_bf16 v[124:127], v[128:131], v[200:203], v[124:127]
	v_mfma_f32_16x16x32_bf16 v[124:127], v[132:135], v[204:207], v[124:127]
	v_mfma_f32_16x16x32_bf16 v[120:123], v[136:139], v[200:203], v[120:123]
	v_mfma_f32_16x16x32_bf16 v[120:123], v[140:143], v[204:207], v[120:123]
	v_mfma_f32_16x16x32_bf16 v[108:111], v[128:131], v[208:211], v[108:111]
	v_mfma_f32_16x16x32_bf16 v[108:111], v[132:135], v[212:215], v[108:111]
	v_mfma_f32_16x16x32_bf16 v[104:107], v[136:139], v[208:211], v[104:107]
	v_mfma_f32_16x16x32_bf16 v[104:107], v[140:143], v[212:215], v[104:107]
	v_mfma_f32_16x16x32_bf16 v[92:95], v[128:131], v[216:219], v[92:95]
	v_mfma_f32_16x16x32_bf16 v[92:95], v[132:135], v[220:223], v[92:95]
	v_mfma_f32_16x16x32_bf16 v[88:91], v[136:139], v[216:219], v[88:91]
	v_mfma_f32_16x16x32_bf16 v[88:91], v[140:143], v[220:223], v[88:91]
	v_mfma_f32_16x16x32_bf16 v[76:79], v[128:131], v[224:227], v[76:79]
	v_mfma_f32_16x16x32_bf16 v[76:79], v[132:135], v[228:231], v[76:79]
	v_mfma_f32_16x16x32_bf16 v[72:75], v[136:139], v[224:227], v[72:75]
	v_mfma_f32_16x16x32_bf16 v[72:75], v[140:143], v[228:231], v[72:75]
	s_setprio 0
	s_setprio 1
	v_mfma_f32_16x16x32_bf16 v[116:119], v[144:147], v[200:203], v[116:119]
	v_mfma_f32_16x16x32_bf16 v[116:119], v[148:151], v[204:207], v[116:119]
	v_mfma_f32_16x16x32_bf16 v[112:115], v[168:171], v[200:203], v[112:115]
	v_mfma_f32_16x16x32_bf16 v[112:115], v[196:199], v[204:207], v[112:115]
	v_mfma_f32_16x16x32_bf16 v[100:103], v[144:147], v[208:211], v[100:103]
	v_mfma_f32_16x16x32_bf16 v[100:103], v[148:151], v[212:215], v[100:103]
	v_mfma_f32_16x16x32_bf16 v[96:99], v[168:171], v[208:211], v[96:99]
	v_mfma_f32_16x16x32_bf16 v[96:99], v[196:199], v[212:215], v[96:99]
	v_mfma_f32_16x16x32_bf16 v[84:87], v[144:147], v[216:219], v[84:87]
	v_mfma_f32_16x16x32_bf16 v[84:87], v[148:151], v[220:223], v[84:87]
	v_mfma_f32_16x16x32_bf16 v[80:83], v[168:171], v[216:219], v[80:83]
	v_mfma_f32_16x16x32_bf16 v[80:83], v[196:199], v[220:223], v[80:83]
	v_mfma_f32_16x16x32_bf16 v[68:71], v[144:147], v[224:227], v[68:71]
	v_mfma_f32_16x16x32_bf16 v[68:71], v[148:151], v[228:231], v[68:71]
	v_mfma_f32_16x16x32_bf16 v[64:67], v[168:171], v[224:227], v[64:67]
	v_mfma_f32_16x16x32_bf16 v[64:67], v[196:199], v[228:231], v[64:67]
	s_setprio 0
	s_barrier
	s_add_i32 s26, s60, s10
	v_lshl_add_u64 v[172:173], v[172:173], 0, s[20:21]
	s_mov_b32 m0, s26
	ds_read_b128 v[200:203], v194 offset:49152
	ds_read_b128 v[204:207], v194 offset:50176
	ds_read_b128 v[208:211], v194 offset:51200
	ds_read_b128 v[212:215], v194 offset:52224
	ds_read_b128 v[216:219], v194 offset:53248
	ds_read_b128 v[220:223], v194 offset:54272
	ds_read_b128 v[224:227], v194 offset:55296
	ds_read_b128 v[228:231], v194 offset:56320
	global_load_lds_dwordx4 v[172:173], off
	s_add_i32 m0, s26, 0x2000
	s_add_u32 s26, s36, 0x160080
	v_lshl_add_u64 v[172:173], v[232:233], 0, s[20:21]
	s_addc_u32 s27, s37, 0
	s_add_i32 s36, s61, s10
	global_load_lds_dwordx4 v[172:173], off
	v_lshl_add_u64 v[172:173], s[26:27], 0, v[154:155]
	s_mov_b32 m0, s36
	s_nop 0
	global_load_lds_dwordx4 v[172:173], off
	v_lshl_add_u64 v[172:173], s[26:27], 0, v[158:159]
	s_add_i32 m0, s36, 0x2000
	s_nop 0
	global_load_lds_dwordx4 v[172:173], off
	v_lshl_add_u64 v[172:173], v[234:235], 0, s[20:21]
	s_mov_b32 m0, s43
	s_nop 0
	global_load_lds_dwordx4 v[172:173], off
	v_lshl_add_u64 v[172:173], v[236:237], 0, s[20:21]
	s_mov_b32 m0, s44
	s_nop 0
	global_load_lds_dwordx4 v[172:173], off
	s_waitcnt vmcnt(8)
	s_waitcnt lgkmcnt(0)
	s_barrier
	s_setprio 1
	s_waitcnt lgkmcnt(0)
	v_mfma_f32_16x16x32_bf16 v[60:63], v[128:131], v[200:203], v[60:63]
	v_mfma_f32_16x16x32_bf16 v[60:63], v[132:135], v[204:207], v[60:63]
	v_mfma_f32_16x16x32_bf16 v[56:59], v[136:139], v[200:203], v[56:59]
	v_mfma_f32_16x16x32_bf16 v[56:59], v[140:143], v[204:207], v[56:59]
	v_mfma_f32_16x16x32_bf16 v[44:47], v[128:131], v[208:211], v[44:47]
	v_mfma_f32_16x16x32_bf16 v[44:47], v[132:135], v[212:215], v[44:47]
	v_mfma_f32_16x16x32_bf16 v[40:43], v[136:139], v[208:211], v[40:43]
	v_mfma_f32_16x16x32_bf16 v[40:43], v[140:143], v[212:215], v[40:43]
	v_mfma_f32_16x16x32_bf16 v[28:31], v[128:131], v[216:219], v[28:31]
	v_mfma_f32_16x16x32_bf16 v[28:31], v[132:135], v[220:223], v[28:31]
	v_mfma_f32_16x16x32_bf16 v[24:27], v[136:139], v[216:219], v[24:27]
	v_mfma_f32_16x16x32_bf16 v[24:27], v[140:143], v[220:223], v[24:27]
	v_mfma_f32_16x16x32_bf16 v[12:15], v[128:131], v[224:227], v[12:15]
	v_mfma_f32_16x16x32_bf16 v[12:15], v[132:135], v[228:231], v[12:15]
	v_mfma_f32_16x16x32_bf16 v[8:11], v[136:139], v[224:227], v[8:11]
	v_mfma_f32_16x16x32_bf16 v[8:11], v[140:143], v[228:231], v[8:11]
	s_setprio 0
	s_setprio 1
	v_mfma_f32_16x16x32_bf16 v[52:55], v[144:147], v[200:203], v[52:55]
	v_mfma_f32_16x16x32_bf16 v[52:55], v[148:151], v[204:207], v[52:55]
	v_mfma_f32_16x16x32_bf16 v[48:51], v[168:171], v[200:203], v[48:51]
	v_mfma_f32_16x16x32_bf16 v[48:51], v[196:199], v[204:207], v[48:51]
	v_mfma_f32_16x16x32_bf16 v[36:39], v[144:147], v[208:211], v[36:39]
	v_mfma_f32_16x16x32_bf16 v[36:39], v[148:151], v[212:215], v[36:39]
	v_mfma_f32_16x16x32_bf16 v[32:35], v[168:171], v[208:211], v[32:35]
	v_mfma_f32_16x16x32_bf16 v[32:35], v[196:199], v[212:215], v[32:35]
	v_mfma_f32_16x16x32_bf16 v[20:23], v[144:147], v[216:219], v[20:23]
	v_mfma_f32_16x16x32_bf16 v[20:23], v[148:151], v[220:223], v[20:23]
	v_mfma_f32_16x16x32_bf16 v[16:19], v[168:171], v[216:219], v[16:19]
	v_mfma_f32_16x16x32_bf16 v[16:19], v[196:199], v[220:223], v[16:19]
	v_mfma_f32_16x16x32_bf16 v[4:7], v[144:147], v[224:227], v[4:7]
	v_mfma_f32_16x16x32_bf16 v[4:7], v[148:151], v[228:231], v[4:7]
	v_mfma_f32_16x16x32_bf16 v[0:3], v[168:171], v[224:227], v[0:3]
	v_mfma_f32_16x16x32_bf16 v[0:3], v[196:199], v[228:231], v[0:3]
	s_setprio 0
	s_barrier
	s_add_i32 s51, s51, 2
	s_add_u32 s49, s49, 0x100
	s_addc_u32 s50, s50, 0
	s_cmpk_gt_u32 s51, 0x55
	s_mov_b64 s[26:27], s[34:35]
	s_cbranch_scc0 .LBB0_873
	s_and_b64 vcc, exec, s[22:23]
	s_cbranch_vccz .LBB0_876
	s_barrier

.LBB0_975:
	ds_read_b128 v[132:135], v179
	ds_read_b128 v[136:139], v179 offset:1024
	ds_read_b128 v[140:143], v179 offset:2048
	ds_read_b128 v[144:147], v179 offset:3072
	ds_read_b128 v[148:151], v180
	ds_read_b128 v[166:169], v180 offset:1024
	ds_read_b128 v[170:173], v180 offset:2048
	ds_read_b128 v[174:177], v180 offset:3072
	s_add_u32 s22, s20, 0x100
	s_addc_u32 s23, s21, 0
	s_add_u32 s24, s62, s20
	s_addc_u32 s25, s63, s21
	s_cmpk_eq_i32 s64, 0x54
	s_cselect_b32 s26, s16, s24
	s_cselect_b32 s24, 0, s22
	s_cselect_b32 s27, s17, s25
	s_cselect_b32 s25, 0, s23
	s_add_u32 s24, s2, s24
	s_addc_u32 s25, s3, s25
	s_mov_b32 m0, s57
	v_lshl_add_u64 v[218:219], v[128:129], 0, s[20:21]
	ds_read_b128 v[186:189], v181
	ds_read_b128 v[190:193], v181 offset:1024
	ds_read_b128 v[194:197], v181 offset:2048
	ds_read_b128 v[198:201], v181 offset:3072
	ds_read_b128 v[202:205], v181 offset:4096
	ds_read_b128 v[206:209], v181 offset:5120
	ds_read_b128 v[210:213], v181 offset:6144
	ds_read_b128 v[214:217], v181 offset:7168
	global_load_lds_dwordx4 v[218:219], off
	v_lshl_add_u64 v[218:219], v[130:131], 0, s[20:21]
	s_mov_b32 m0, s58
	s_nop 0
	global_load_lds_dwordx4 v[218:219], off
	s_waitcnt vmcnt(8)
	s_waitcnt lgkmcnt(0)
	s_barrier
	s_setprio 1
	s_waitcnt lgkmcnt(0)
	v_mfma_f32_16x16x32_bf16 v[124:127], v[132:135], v[186:189], v[124:127]
	v_mfma_f32_16x16x32_bf16 v[124:127], v[136:139], v[190:193], v[124:127]
	v_mfma_f32_16x16x32_bf16 v[120:123], v[140:143], v[186:189], v[120:123]
	v_mfma_f32_16x16x32_bf16 v[120:123], v[144:147], v[190:193], v[120:123]
	v_mfma_f32_16x16x32_bf16 v[108:111], v[132:135], v[194:197], v[108:111]
	v_mfma_f32_16x16x32_bf16 v[108:111], v[136:139], v[198:201], v[108:111]
	v_mfma_f32_16x16x32_bf16 v[104:107], v[140:143], v[194:197], v[104:107]
	v_mfma_f32_16x16x32_bf16 v[104:107], v[144:147], v[198:201], v[104:107]
	v_mfma_f32_16x16x32_bf16 v[92:95], v[132:135], v[202:205], v[92:95]
	v_mfma_f32_16x16x32_bf16 v[92:95], v[136:139], v[206:209], v[92:95]
	v_mfma_f32_16x16x32_bf16 v[88:91], v[140:143], v[202:205], v[88:91]
	v_mfma_f32_16x16x32_bf16 v[88:91], v[144:147], v[206:209], v[88:91]
	v_mfma_f32_16x16x32_bf16 v[76:79], v[132:135], v[210:213], v[76:79]
	v_mfma_f32_16x16x32_bf16 v[76:79], v[136:139], v[214:217], v[76:79]
	v_mfma_f32_16x16x32_bf16 v[72:75], v[140:143], v[210:213], v[72:75]
	v_mfma_f32_16x16x32_bf16 v[72:75], v[144:147], v[214:217], v[72:75]
	s_setprio 0
	s_setprio 1
	v_mfma_f32_16x16x32_bf16 v[116:119], v[148:151], v[186:189], v[116:119]
	v_mfma_f32_16x16x32_bf16 v[116:119], v[166:169], v[190:193], v[116:119]
	v_mfma_f32_16x16x32_bf16 v[112:115], v[170:173], v[186:189], v[112:115]
	v_mfma_f32_16x16x32_bf16 v[112:115], v[174:177], v[190:193], v[112:115]
	v_mfma_f32_16x16x32_bf16 v[100:103], v[148:151], v[194:197], v[100:103]
	v_mfma_f32_16x16x32_bf16 v[100:103], v[166:169], v[198:201], v[100:103]
	v_mfma_f32_16x16x32_bf16 v[96:99], v[170:173], v[194:197], v[96:99]
	v_mfma_f32_16x16x32_bf16 v[96:99], v[174:177], v[198:201], v[96:99]
	v_mfma_f32_16x16x32_bf16 v[84:87], v[148:151], v[202:205], v[84:87]
	v_mfma_f32_16x16x32_bf16 v[84:87], v[166:169], v[206:209], v[84:87]
	v_mfma_f32_16x16x32_bf16 v[80:83], v[170:173], v[202:205], v[80:83]
	v_mfma_f32_16x16x32_bf16 v[80:83], v[174:177], v[206:209], v[80:83]
	v_mfma_f32_16x16x32_bf16 v[68:71], v[148:151], v[210:213], v[68:71]
	v_mfma_f32_16x16x32_bf16 v[68:71], v[166:169], v[214:217], v[68:71]
	v_mfma_f32_16x16x32_bf16 v[64:67], v[170:173], v[210:213], v[64:67]
	v_mfma_f32_16x16x32_bf16 v[64:67], v[174:177], v[214:217], v[64:67]
	s_setprio 0
	s_barrier
	s_mov_b32 m0, s59
	s_add_u32 s98, s24, s6
	s_addc_u32 s99, s25, s7
	ds_read_b128 v[186:189], v181 offset:16384
	ds_read_b128 v[190:193], v181 offset:17408
	ds_read_b128 v[194:197], v181 offset:18432
	ds_read_b128 v[198:201], v181 offset:19456
	ds_read_b128 v[202:205], v181 offset:20480
	ds_read_b128 v[206:209], v181 offset:21504
	ds_read_b128 v[210:213], v181 offset:22528
	ds_read_b128 v[214:217], v181 offset:23552
	global_load_lds_dwordx4 v154, s[24:25]
	s_add_i32 m0, s59, 0x2000
	s_add_u32 s20, s24, 0x160000
	s_addc_u32 s21, s25, 0
	s_add_i32 s65, s56, s31
	global_load_lds_dwordx4 v158, s[24:25]
	s_mov_b32 m0, s65
	s_nop 0
	global_load_lds_dwordx4 v154, s[20:21]
	s_add_i32 m0, s65, 0x2000
	s_nop 0
	global_load_lds_dwordx4 v158, s[20:21]
	s_add_u32 s100, s26, s6
	s_addc_u32 s101, s27, s7
	s_mov_b32 m0, s33
	s_nop 0
	global_load_lds_dwordx4 v152, s[26:27]
	s_mov_b32 m0, s34
	s_nop 0
	global_load_lds_dwordx4 v156, s[26:27]
	s_waitcnt vmcnt(8)
	s_waitcnt lgkmcnt(0)
	s_barrier
	s_setprio 1
	v_mfma_f32_16x16x32_bf16 v[60:63], v[132:135], v[186:189], v[60:63]
	v_mfma_f32_16x16x32_bf16 v[60:63], v[136:139], v[190:193], v[60:63]
	v_mfma_f32_16x16x32_bf16 v[56:59], v[140:143], v[186:189], v[56:59]
	v_mfma_f32_16x16x32_bf16 v[56:59], v[144:147], v[190:193], v[56:59]
	v_mfma_f32_16x16x32_bf16 v[44:47], v[132:135], v[194:197], v[44:47]
	v_mfma_f32_16x16x32_bf16 v[44:47], v[136:139], v[198:201], v[44:47]
	v_mfma_f32_16x16x32_bf16 v[40:43], v[140:143], v[194:197], v[40:43]
	v_mfma_f32_16x16x32_bf16 v[40:43], v[144:147], v[198:201], v[40:43]
	v_mfma_f32_16x16x32_bf16 v[28:31], v[132:135], v[202:205], v[28:31]
	v_mfma_f32_16x16x32_bf16 v[28:31], v[136:139], v[206:209], v[28:31]
	v_mfma_f32_16x16x32_bf16 v[24:27], v[140:143], v[202:205], v[24:27]
	v_mfma_f32_16x16x32_bf16 v[24:27], v[144:147], v[206:209], v[24:27]
	v_mfma_f32_16x16x32_bf16 v[12:15], v[132:135], v[210:213], v[12:15]
	v_mfma_f32_16x16x32_bf16 v[12:15], v[136:139], v[214:217], v[12:15]
	v_mfma_f32_16x16x32_bf16 v[8:11], v[140:143], v[210:213], v[8:11]
	v_mfma_f32_16x16x32_bf16 v[8:11], v[144:147], v[214:217], v[8:11]
	s_setprio 0
	s_setprio 1
	v_mfma_f32_16x16x32_bf16 v[52:55], v[148:151], v[186:189], v[52:55]
	v_mfma_f32_16x16x32_bf16 v[52:55], v[166:169], v[190:193], v[52:55]
	v_mfma_f32_16x16x32_bf16 v[48:51], v[170:173], v[186:189], v[48:51]
	v_mfma_f32_16x16x32_bf16 v[48:51], v[174:177], v[190:193], v[48:51]
	v_mfma_f32_16x16x32_bf16 v[36:39], v[148:151], v[194:197], v[36:39]
	v_mfma_f32_16x16x32_bf16 v[36:39], v[166:169], v[198:201], v[36:39]
	v_mfma_f32_16x16x32_bf16 v[32:35], v[170:173], v[194:197], v[32:35]
	v_mfma_f32_16x16x32_bf16 v[32:35], v[174:177], v[198:201], v[32:35]
	v_mfma_f32_16x16x32_bf16 v[20:23], v[148:151], v[202:205], v[20:23]
	v_mfma_f32_16x16x32_bf16 v[20:23], v[166:169], v[206:209], v[20:23]
	v_mfma_f32_16x16x32_bf16 v[16:19], v[170:173], v[202:205], v[16:19]
	v_mfma_f32_16x16x32_bf16 v[16:19], v[174:177], v[206:209], v[16:19]
	v_mfma_f32_16x16x32_bf16 v[4:7], v[148:151], v[210:213], v[4:7]
	v_mfma_f32_16x16x32_bf16 v[4:7], v[166:169], v[214:217], v[4:7]
	v_mfma_f32_16x16x32_bf16 v[0:3], v[170:173], v[210:213], v[0:3]
	v_mfma_f32_16x16x32_bf16 v[0:3], v[174:177], v[214:217], v[0:3]
	s_setprio 0
	s_barrier
	s_add_i32 s65, 0, 0x18000
	s_add_i32 s66, 0, 0x1c000
	v_add_u32_e32 v144, s65, v178
	v_add_u32_e32 v160, s66, v178
	ds_read_b128 v[132:135], v144
	ds_read_b128 v[136:139], v144 offset:1024
	ds_read_b128 v[140:143], v144 offset:2048
	ds_read_b128 v[144:147], v144 offset:3072
	ds_read_b128 v[148:151], v160
	ds_read_b128 v[166:169], v160 offset:1024
	ds_read_b128 v[170:173], v160 offset:2048
	ds_read_b128 v[174:177], v160 offset:3072
	s_add_u32 s20, s26, 0x160000
	s_addc_u32 s21, s27, 0
	s_mov_b32 m0, s35
	ds_read_b128 v[186:189], v181 offset:32768
	ds_read_b128 v[190:193], v181 offset:33792
	ds_read_b128 v[194:197], v181 offset:34816
	ds_read_b128 v[198:201], v181 offset:35840
	ds_read_b128 v[202:205], v181 offset:36864
	ds_read_b128 v[206:209], v181 offset:37888
	ds_read_b128 v[210:213], v181 offset:38912
	ds_read_b128 v[214:217], v181 offset:39936
	global_load_lds_dwordx4 v152, s[20:21]
	s_mov_b32 m0, s36
	s_nop 0
	global_load_lds_dwordx4 v156, s[20:21]
	s_waitcnt vmcnt(8)
	s_waitcnt lgkmcnt(0)
	s_barrier
	s_setprio 1
	v_mfma_f32_16x16x32_bf16 v[124:127], v[132:135], v[186:189], v[124:127]
	v_mfma_f32_16x16x32_bf16 v[124:127], v[136:139], v[190:193], v[124:127]
	v_mfma_f32_16x16x32_bf16 v[120:123], v[140:143], v[186:189], v[120:123]
	v_mfma_f32_16x16x32_bf16 v[120:123], v[144:147], v[190:193], v[120:123]
	v_mfma_f32_16x16x32_bf16 v[108:111], v[132:135], v[194:197], v[108:111]
	v_mfma_f32_16x16x32_bf16 v[108:111], v[136:139], v[198:201], v[108:111]
	v_mfma_f32_16x16x32_bf16 v[104:107], v[140:143], v[194:197], v[104:107]
	v_mfma_f32_16x16x32_bf16 v[104:107], v[144:147], v[198:201], v[104:107]
	v_mfma_f32_16x16x32_bf16 v[92:95], v[132:135], v[202:205], v[92:95]
	v_mfma_f32_16x16x32_bf16 v[92:95], v[136:139], v[206:209], v[92:95]
	v_mfma_f32_16x16x32_bf16 v[88:91], v[140:143], v[202:205], v[88:91]
	v_mfma_f32_16x16x32_bf16 v[88:91], v[144:147], v[206:209], v[88:91]
	v_mfma_f32_16x16x32_bf16 v[76:79], v[132:135], v[210:213], v[76:79]
	v_mfma_f32_16x16x32_bf16 v[76:79], v[136:139], v[214:217], v[76:79]
	v_mfma_f32_16x16x32_bf16 v[72:75], v[140:143], v[210:213], v[72:75]
	v_mfma_f32_16x16x32_bf16 v[72:75], v[144:147], v[214:217], v[72:75]
	s_setprio 0
	s_setprio 1
	v_mfma_f32_16x16x32_bf16 v[116:119], v[148:151], v[186:189], v[116:119]
	v_mfma_f32_16x16x32_bf16 v[116:119], v[166:169], v[190:193], v[116:119]
	v_mfma_f32_16x16x32_bf16 v[112:115], v[170:173], v[186:189], v[112:115]
	v_mfma_f32_16x16x32_bf16 v[112:115], v[174:177], v[190:193], v[112:115]
	v_mfma_f32_16x16x32_bf16 v[100:103], v[148:151], v[194:197], v[100:103]
	v_mfma_f32_16x16x32_bf16 v[100:103], v[166:169], v[198:201], v[100:103]
	v_mfma_f32_16x16x32_bf16 v[96:99], v[170:173], v[194:197], v[96:99]
	v_mfma_f32_16x16x32_bf16 v[96:99], v[174:177], v[198:201], v[96:99]
	v_mfma_f32_16x16x32_bf16 v[84:87], v[148:151], v[202:205], v[84:87]
	v_mfma_f32_16x16x32_bf16 v[84:87], v[166:169], v[206:209], v[84:87]
	v_mfma_f32_16x16x32_bf16 v[80:83], v[170:173], v[202:205], v[80:83]
	v_mfma_f32_16x16x32_bf16 v[80:83], v[174:177], v[206:209], v[80:83]
	v_mfma_f32_16x16x32_bf16 v[68:71], v[148:151], v[210:213], v[68:71]
	v_mfma_f32_16x16x32_bf16 v[68:71], v[166:169], v[214:217], v[68:71]
	v_mfma_f32_16x16x32_bf16 v[64:67], v[170:173], v[210:213], v[64:67]
	v_mfma_f32_16x16x32_bf16 v[64:67], v[174:177], v[214:217], v[64:67]
	s_setprio 0
	s_barrier
	s_add_i32 s20, s65, s31
	s_mov_b32 m0, s20
	ds_read_b128 v[186:189], v181 offset:49152
	ds_read_b128 v[190:193], v181 offset:50176
	ds_read_b128 v[194:197], v181 offset:51200
	ds_read_b128 v[198:201], v181 offset:52224
	ds_read_b128 v[202:205], v181 offset:53248
	ds_read_b128 v[206:209], v181 offset:54272
	ds_read_b128 v[210:213], v181 offset:55296
	ds_read_b128 v[214:217], v181 offset:56320
	global_load_lds_dwordx4 v154, s[98:99]
	s_add_i32 m0, s20, 0x2000
	s_add_u32 s20, s24, 0x160080
	s_addc_u32 s21, s25, 0
	s_add_i32 s24, s66, s31
	global_load_lds_dwordx4 v158, s[98:99]
	s_mov_b32 m0, s24
	s_nop 0
	global_load_lds_dwordx4 v154, s[20:21]
	s_add_i32 m0, s24, 0x2000
	s_nop 0
	global_load_lds_dwordx4 v158, s[20:21]
	s_mov_b32 m0, s39
	s_nop 0
	global_load_lds_dwordx4 v152, s[100:101]
	s_mov_b32 m0, s40
	s_nop 0
	global_load_lds_dwordx4 v156, s[100:101]
	s_waitcnt vmcnt(8)
	s_waitcnt lgkmcnt(0)
	s_barrier
	s_setprio 1
	s_waitcnt lgkmcnt(0)
	v_mfma_f32_16x16x32_bf16 v[60:63], v[132:135], v[186:189], v[60:63]
	v_mfma_f32_16x16x32_bf16 v[60:63], v[136:139], v[190:193], v[60:63]
	v_mfma_f32_16x16x32_bf16 v[56:59], v[140:143], v[186:189], v[56:59]
	v_mfma_f32_16x16x32_bf16 v[56:59], v[144:147], v[190:193], v[56:59]
	v_mfma_f32_16x16x32_bf16 v[44:47], v[132:135], v[194:197], v[44:47]
	v_mfma_f32_16x16x32_bf16 v[44:47], v[136:139], v[198:201], v[44:47]
	v_mfma_f32_16x16x32_bf16 v[40:43], v[140:143], v[194:197], v[40:43]
	v_mfma_f32_16x16x32_bf16 v[40:43], v[144:147], v[198:201], v[40:43]
	v_mfma_f32_16x16x32_bf16 v[28:31], v[132:135], v[202:205], v[28:31]
	v_mfma_f32_16x16x32_bf16 v[28:31], v[136:139], v[206:209], v[28:31]
	v_mfma_f32_16x16x32_bf16 v[24:27], v[140:143], v[202:205], v[24:27]
	v_mfma_f32_16x16x32_bf16 v[24:27], v[144:147], v[206:209], v[24:27]
	v_mfma_f32_16x16x32_bf16 v[12:15], v[132:135], v[210:213], v[12:15]
	v_mfma_f32_16x16x32_bf16 v[12:15], v[136:139], v[214:217], v[12:15]
	v_mfma_f32_16x16x32_bf16 v[8:11], v[140:143], v[210:213], v[8:11]
	v_mfma_f32_16x16x32_bf16 v[8:11], v[144:147], v[214:217], v[8:11]
	s_setprio 0
	s_setprio 1
	v_mfma_f32_16x16x32_bf16 v[52:55], v[148:151], v[186:189], v[52:55]
	v_mfma_f32_16x16x32_bf16 v[52:55], v[166:169], v[190:193], v[52:55]
	v_mfma_f32_16x16x32_bf16 v[48:51], v[170:173], v[186:189], v[48:51]
	v_mfma_f32_16x16x32_bf16 v[48:51], v[174:177], v[190:193], v[48:51]
	v_mfma_f32_16x16x32_bf16 v[36:39], v[148:151], v[194:197], v[36:39]
	v_mfma_f32_16x16x32_bf16 v[36:39], v[166:169], v[198:201], v[36:39]
	v_mfma_f32_16x16x32_bf16 v[32:35], v[170:173], v[194:197], v[32:35]
	v_mfma_f32_16x16x32_bf16 v[32:35], v[174:177], v[198:201], v[32:35]
	v_mfma_f32_16x16x32_bf16 v[20:23], v[148:151], v[202:205], v[20:23]
	v_mfma_f32_16x16x32_bf16 v[20:23], v[166:169], v[206:209], v[20:23]
	v_mfma_f32_16x16x32_bf16 v[16:19], v[170:173], v[202:205], v[16:19]
	v_mfma_f32_16x16x32_bf16 v[16:19], v[174:177], v[206:209], v[16:19]
	v_mfma_f32_16x16x32_bf16 v[4:7], v[148:151], v[210:213], v[4:7]
	v_mfma_f32_16x16x32_bf16 v[4:7], v[166:169], v[214:217], v[4:7]
	v_mfma_f32_16x16x32_bf16 v[0:3], v[170:173], v[210:213], v[0:3]
	v_mfma_f32_16x16x32_bf16 v[0:3], v[174:177], v[214:217], v[0:3]
	s_setprio 0
	s_barrier
	s_add_i32 s64, s64, 2
	s_cmpk_gt_u32 s64, 0x55
	s_mov_b64 s[20:21], s[22:23]
	s_cbranch_scc0 .LBB0_975
	s_and_b64 vcc, exec, s[8:9]
	s_cbranch_vccz .LBB0_978
	s_barrier
